# non-temporal hints on streamed-once accesses: P0 x/W_in reads, P5 x reads, P4 GL and kind-1 GA reads, P9 x3 reads and out stores, P3 Q and PU reads
# speedup vs baseline: 1.0388x; 1.0195x over previous
; __global__ void __launch_bounds__(NWAVES * 64, 2) mk_fwd(Args args) {
;     ...
;     XcdBarrier bar = xcd_barrier_post((unsigned*)(ws + WS_BAR), MISC + 8);
;     if (args.ph_hi > 1000) grid.sync();
.LBB0_5:
	s_or_b64 exec, exec, s[2:3]
	s_load_dwordx16 s[76:91], s[0:1], 0x0
	s_cmpk_lt_i32 s71, 0x3e9
	s_cbranch_scc1 .LBB0_17
	v_lshrrev_b32_e32 v1, 20, v0
	v_lshrrev_b32_e32 v0, 10, v0
	v_or_b32_e32 v0, v0, v1
	s_movk_i32 s2, 0x3ff
	v_and_or_b32 v0, v0, s2, v185
	v_cmp_eq_u32_e32 vcc, 0, v0
	s_waitcnt lgkmcnt(0)
	s_barrier
	s_and_saveexec_b64 s[2:3], vcc
	s_cbranch_execz .LBB0_16
	buffer_wbl2 sc1
	s_waitcnt vmcnt(0)
	s_load_dwordx2 s[4:5], s[4:5], 0x58
	v_mov_b32_e32 v2, 0
	s_mov_b64 s[6:7], exec
	v_mbcnt_lo_u32_b32 v1, s6, 0
	v_mbcnt_hi_u32_b32 v1, s7, v1
	s_waitcnt lgkmcnt(0)
	global_load_dword v0, v2, s[4:5] offset:40 nt
	v_cmp_eq_u32_e32 vcc, 0, v1
	s_and_saveexec_b64 s[8:9], vcc
	s_cbranch_execz .LBB0_9
	s_bcnt1_i32_b64 s6, s[6:7]
	v_mov_b32_e32 v3, s6
	global_atomic_add v3, v2, v3, s[4:5] offset:32 sc0

; #define LAS __attribute__((address_space(3)))
; __device__ __forceinline__ unsigned pk_fp8x4(float a, float b, float c, float d) { int w = 0; w = __builtin_amdgcn_cvt_pk_fp8_f32(a, b, w, false); w = __builtin_amdgcn_cvt_pk_fp8_f32(c, d, w, true); return (unsigned)w; }
; template <bool F8 = false>
; __device__ __forceinline__ void p0_transpose_item(const float* W, int K, int N, bf16_t* WT, int k0, int n0, int drow0, const float* gs, LAS float* scr, int lane) {
;     ...
;     for (int i = 0; i < 32; ++i) wv[i] = W[(size_t)(k0 + 2 * i + (lane >> 5)) * N + n0 + (lane & 31)];
;     if (gs) {
; #pragma unroll
;         for (int i = 0; i < 32; ++i) wv[i] *= gs[k0 + 2 * i + (lane >> 5)]; }
; #pragma unroll
;     for (int i = 0; i < 32; ++i) scr[(2 * i + (lane >> 5)) * 33 + (lane & 31)] = wv[i];
;     asm volatile("s_waitcnt lgkmcnt(0)" ::: "memory");
;     const int c = lane & 7;
; #pragma unroll
;     for (int j = 0; j < 4; ++j) { const int n = (lane >> 3) + 8 * j; const LAS float* s = scr + (8 * c) * 33 + n;
;         if (F8) { u32x2 o8; o8.x = pk_fp8x4(32.f * s[0 * 33], 32.f * s[1 * 33], 32.f * s[2 * 33], 32.f * s[3 * 33]); o8.y = pk_fp8x4(32.f * s[4 * 33], 32.f * s[5 * 33], 32.f * s[6 * 33], 32.f * s[7 * 33]);
; template <int PART>
; __device__ __forceinline__ void phase0(const Ptrs& P, LAS float* scr, int gw, int NGW, int lane) {
;     ...
;         if (r < I_IN) { const int nblk = NIN / 32, kb = r / nblk, nb = r % nblk, n0 = 32 * nb, sec = n0 >> 10;
;             if (sec < 5) p0_transpose_item(P.w_in, DM, NIN, (bf16_t*)(ws + WS_WIN), 64 * kb, n0, n0, nullptr, scr, lane);
;             else p0_transpose_item<true>(P.w_in, DM, NIN, (bf16_t*)(ws + WS_WG8), 64 * kb, n0, n0 - 5120, nullptr, scr, lane);
.LBB0_23:
	s_mov_b32 s5, s27
	v_lshl_add_u64 v[54:55], s[4:5], 2, v[6:7]
	v_mad_i64_i32 v[56:57], s[6:7], v52, s30, v[54:55]
	v_mad_i64_i32 v[58:59], s[6:7], v51, s30, v[54:55]
	v_mad_i64_i32 v[60:61], s[6:7], v50, s30, v[54:55]
	v_mad_i64_i32 v[62:63], s[6:7], v49, s30, v[54:55]
	v_mad_i64_i32 v[64:65], s[6:7], v48, s30, v[54:55]
	v_mad_i64_i32 v[66:67], s[6:7], v47, s30, v[54:55]
	v_mad_i64_i32 v[68:69], s[6:7], v46, s30, v[54:55]
	v_mad_i64_i32 v[70:71], s[6:7], v45, s30, v[54:55]
	global_load_dword v53, v[56:57], off nt
	global_load_dword v74, v[58:59], off nt
	global_load_dword v75, v[60:61], off nt
	global_load_dword v76, v[62:63], off nt
	global_load_dword v77, v[64:65], off nt
	global_load_dword v78, v[66:67], off nt
	global_load_dword v79, v[68:69], off nt
	global_load_dword v80, v[70:71], off nt
	v_mad_i64_i32 v[56:57], s[6:7], v44, s30, v[54:55]
	v_mad_i64_i32 v[58:59], s[6:7], v43, s30, v[54:55]
	v_mad_i64_i32 v[60:61], s[6:7], v42, s30, v[54:55]
	v_mad_i64_i32 v[62:63], s[6:7], v41, s30, v[54:55]
	v_mad_i64_i32 v[64:65], s[6:7], v40, s30, v[54:55]
	v_mad_i64_i32 v[66:67], s[6:7], v39, s30, v[54:55]
	v_mad_i64_i32 v[68:69], s[6:7], v38, s30, v[54:55]
	v_mad_i64_i32 v[70:71], s[6:7], v37, s30, v[54:55]
	v_mad_i64_i32 v[72:73], s[6:7], v36, s30, v[54:55]
	global_load_dword v81, v[56:57], off nt
	global_load_dword v82, v[58:59], off nt
	global_load_dword v83, v[60:61], off nt
	global_load_dword v84, v[62:63], off nt
	global_load_dword v85, v[64:65], off nt
	global_load_dword v86, v[66:67], off nt
	global_load_dword v87, v[68:69], off nt
	s_nop 0
	global_load_dword v70, v[70:71], off nt
	v_mad_i64_i32 v[56:57], s[6:7], v35, s30, v[54:55]
	v_mad_i64_i32 v[58:59], s[6:7], v34, s30, v[54:55]
	v_mad_i64_i32 v[60:61], s[6:7], v33, s30, v[54:55]
	v_mad_i64_i32 v[62:63], s[6:7], v32, s30, v[54:55]
	v_mad_i64_i32 v[64:65], s[6:7], v31, s30, v[54:55]
	v_mad_i64_i32 v[66:67], s[6:7], v30, s30, v[54:55]
	v_mad_i64_i32 v[68:69], s[6:7], v29, s30, v[54:55]
	global_load_dword v71, v[72:73], off nt
	s_nop 0
	global_load_dword v72, v[56:57], off nt
	global_load_dword v73, v[58:59], off nt
	global_load_dword v88, v[60:61], off nt
	global_load_dword v89, v[62:63], off nt
	global_load_dword v90, v[64:65], off nt
	global_load_dword v91, v[66:67], off nt
	global_load_dword v92, v[68:69], off nt
	v_mad_i64_i32 v[56:57], s[6:7], v28, s30, v[54:55]
	v_mad_i64_i32 v[58:59], s[6:7], v27, s30, v[54:55]
	v_mad_i64_i32 v[60:61], s[6:7], v26, s30, v[54:55]
	v_mad_i64_i32 v[62:63], s[6:7], v25, s30, v[54:55]
	v_mad_i64_i32 v[64:65], s[6:7], v24, s30, v[54:55]
	v_mad_i64_i32 v[66:67], s[6:7], v23, s30, v[54:55]
	v_mad_i64_i32 v[68:69], s[6:7], v22, s30, v[54:55]
	v_mad_i64_i32 v[54:55], s[6:7], v9, s30, v[54:55]
	global_load_dword v56, v[56:57], off nt
	s_nop 0
	global_load_dword v57, v[58:59], off nt
	s_nop 0
	global_load_dword v58, v[60:61], off nt
	global_load_dword v59, v[62:63], off nt
	s_nop 0
	global_load_dword v60, v[64:65], off nt
	global_load_dword v61, v[66:67], off nt
	global_load_dword v62, v[68:69], off nt
	s_nop 0
	global_load_dword v54, v[54:55], off nt
	v_mov_b32_e32 v66, 0
	v_mov_b32_e32 v67, 0
	s_ashr_i32 s3, s2, 31
	s_waitcnt vmcnt(30)
	ds_write2_b32 v14, v53, v74 offset1:66
	s_waitcnt vmcnt(28)
	ds_write2_b32 v14, v75, v76 offset0:132 offset1:198
	s_waitcnt vmcnt(26)
	ds_write2_b32 v15, v77, v78 offset0:8 offset1:74
	s_waitcnt vmcnt(24)
	ds_write2_b32 v15, v79, v80 offset0:140 offset1:206
	s_waitcnt vmcnt(22)
	ds_write2_b32 v16, v81, v82 offset0:16 offset1:82
	s_waitcnt vmcnt(20)
	ds_write2_b32 v16, v83, v84 offset0:148 offset1:214
	s_waitcnt vmcnt(18)
	ds_write2_b32 v17, v85, v86 offset0:24 offset1:90
	s_waitcnt vmcnt(16)
	ds_write2_b32 v17, v87, v70 offset0:156 offset1:222
	s_waitcnt vmcnt(14)
	ds_write2_b32 v18, v71, v72 offset0:32 offset1:98
	s_waitcnt vmcnt(12)
	ds_write2_b32 v18, v73, v88 offset0:164 offset1:230
	s_waitcnt vmcnt(10)
	ds_write2_b32 v19, v89, v90 offset0:40 offset1:106
	s_waitcnt vmcnt(8)
	ds_write2_b32 v19, v91, v92 offset0:172 offset1:238
	s_waitcnt vmcnt(6)
	ds_write2_b32 v20, v56, v57 offset0:48 offset1:114
	s_waitcnt vmcnt(4)
	ds_write2_b32 v20, v58, v59 offset0:180 offset1:246
	s_waitcnt vmcnt(2)
	ds_write2_b32 v21, v60, v61 offset0:56 offset1:122
	s_waitcnt vmcnt(0)
	ds_write2_b32 v21, v62, v54 offset0:188 offset1:254
	s_waitcnt lgkmcnt(0)
	ds_read2_b32 v[54:55], v13 offset1:8
	ds_read2_b32 v[56:57], v13 offset0:33 offset1:41
	ds_read2_b32 v[58:59], v13 offset0:66 offset1:74
	ds_read2_b32 v[60:61], v13 offset0:132 offset1:140
	ds_read2_b32 v[62:63], v13 offset0:165 offset1:173
	ds_read2_b32 v[64:65], v13 offset0:99 offset1:107
	ds_read2_b32 v[68:69], v13 offset0:198 offset1:206
	ds_read2_b32 v[70:71], v13 offset0:231 offset1:239
	s_waitcnt lgkmcnt(7)
	v_mul_f32_e32 v53, 0x42000000, v54
	s_waitcnt lgkmcnt(6)
	v_mul_f32_e32 v54, 0x42000000, v56
	v_cvt_pk_fp8_f32 v66, v53, v54
	s_waitcnt lgkmcnt(4)
	v_mul_f32_e32 v53, 0x42000000, v60
	s_waitcnt lgkmcnt(3)
	v_mul_f32_e32 v54, 0x42000000, v62
	v_cvt_pk_fp8_f32 v67, v53, v54
	v_mul_f32_e32 v56, 0x42000000, v58
	s_waitcnt lgkmcnt(2)
	v_mul_f32_e32 v53, 0x42000000, v64
	v_cvt_pk_fp8_f32 v66, v56, v53 op_sel:[0,0,1]
	s_waitcnt lgkmcnt(1)
	v_mul_f32_e32 v53, 0x42000000, v68
	s_waitcnt lgkmcnt(0)
; #define LAS __attribute__((address_space(3)))
; __device__ __forceinline__ unsigned pk_fp8x4(float a, float b, float c, float d) { int w = 0; w = __builtin_amdgcn_cvt_pk_fp8_f32(a, b, w, false); w = __builtin_amdgcn_cvt_pk_fp8_f32(c, d, w, true); return (unsigned)w; }
; template <bool F8 = false>
; __device__ __forceinline__ void p0_transpose_item(const float* W, int K, int N, bf16_t* WT, int k0, int n0, int drow0, const float* gs, LAS float* scr, int lane) {
;     ...
;     for (int j = 0; j < 4; ++j) { const int n = (lane >> 3) + 8 * j; const LAS float* s = scr + (8 * c) * 33 + n;
;         if (F8) { u32x2 o8; o8.x = pk_fp8x4(32.f * s[0 * 33], 32.f * s[1 * 33], 32.f * s[2 * 33], 32.f * s[3 * 33]); o8.y = pk_fp8x4(32.f * s[4 * 33], 32.f * s[5 * 33], 32.f * s[6 * 33], 32.f * s[7 * 33]);
;             *(u32x2*)((unsigned char*)WT + (size_t)(drow0 + n) * K + k0 + 8 * c) = o8; }
	v_mul_f32_e32 v54, 0x42000000, v70
	v_cvt_pk_fp8_f32 v67, v53, v54 op_sel:[0,0,1]
	v_mul_f32_e32 v53, 0x42000000, v55
	v_mul_f32_e32 v55, 0x42000000, v57
	v_mov_b32_e32 v54, 0
	v_cvt_pk_fp8_f32 v54, v53, v55
	v_mul_f32_e32 v53, 0x42000000, v61
	v_mul_f32_e32 v58, 0x42000000, v63
	v_mov_b32_e32 v55, 0
	v_cvt_pk_fp8_f32 v55, v53, v58
	v_mul_f32_e32 v56, 0x42000000, v59
	v_mul_f32_e32 v57, 0x42000000, v65
	v_add_u32_e32 v72, 0xffffec00, v8
	v_cvt_pk_fp8_f32 v54, v56, v57 op_sel:[0,0,1]
	v_mul_f32_e32 v53, 0x42000000, v69
	v_mul_f32_e32 v56, 0x42000000, v71
	v_ashrrev_i32_e32 v73, 31, v72
	v_cvt_pk_fp8_f32 v55, v53, v56 op_sel:[0,0,1]
	v_add_u32_e32 v56, 0xffffec08, v8
	v_lshlrev_b64 v[72:73], 10, v[72:73]
	v_lshl_add_u64 v[74:75], v[2:3], 0, s[2:3]
	v_ashrrev_i32_e32 v57, 31, v56
	v_lshl_add_u64 v[72:73], v[74:75], 0, v[72:73]
	v_lshlrev_b64 v[56:57], 10, v[56:57]
	global_store_dwordx2 v[72:73], v[66:67], off
	v_lshl_add_u64 v[56:57], v[74:75], 0, v[56:57]
	ds_read2_b32 v[58:59], v13 offset0:16 offset1:24
	ds_read2_b32 v[60:61], v13 offset0:49 offset1:57
	global_store_dwordx2 v[56:57], v[54:55], off
	ds_read2_b32 v[54:55], v13 offset0:82 offset1:90
	ds_read2_b32 v[56:57], v13 offset0:115 offset1:123
	ds_read2_b32 v[64:65], v13 offset0:148 offset1:156
	ds_read2_b32 v[66:67], v13 offset0:181 offset1:189
	s_waitcnt lgkmcnt(5)
	v_mul_f32_e32 v53, 0x42000000, v58
	s_waitcnt lgkmcnt(4)
	v_mul_f32_e32 v58, 0x42000000, v60
	v_mov_b32_e32 v62, 0
	ds_read2_b32 v[68:69], v13 offset0:214 offset1:222
	ds_read2_b32 v[70:71], v13 offset0:247 offset1:255
	v_cvt_pk_fp8_f32 v62, v53, v58
	s_waitcnt lgkmcnt(5)
	v_mul_f32_e32 v53, 0x42000000, v54
	s_waitcnt lgkmcnt(4)
	v_mul_f32_e32 v54, 0x42000000, v56
	s_waitcnt lgkmcnt(3)
	v_mul_f32_e32 v56, 0x42000000, v64
	s_waitcnt lgkmcnt(2)
	v_mul_f32_e32 v58, 0x42000000, v66
	v_mov_b32_e32 v63, 0
	v_cvt_pk_fp8_f32 v63, v56, v58
	v_cvt_pk_fp8_f32 v62, v53, v54 op_sel:[0,0,1]
	s_waitcnt lgkmcnt(1)
	v_mul_f32_e32 v53, 0x42000000, v68
	s_waitcnt lgkmcnt(0)
	v_mul_f32_e32 v54, 0x42000000, v70
	v_cvt_pk_fp8_f32 v63, v53, v54 op_sel:[0,0,1]
	v_mul_f32_e32 v53, 0x42000000, v59
	v_mul_f32_e32 v56, 0x42000000, v61
	v_mov_b32_e32 v54, 0
	v_mul_f32_e32 v58, 0x42000000, v55
	v_cvt_pk_fp8_f32 v54, v53, v56
	v_mul_f32_e32 v53, 0x42000000, v65
	v_mul_f32_e32 v56, 0x42000000, v67
	v_mov_b32_e32 v55, 0
	v_cvt_pk_fp8_f32 v55, v53, v56
	v_mul_f32_e32 v57, 0x42000000, v57
	v_mul_f32_e32 v53, 0x42000000, v69
	v_mul_f32_e32 v56, 0x42000000, v71
	v_add_u32_e32 v72, 0xffffec10, v8
	v_cvt_pk_fp8_f32 v54, v58, v57 op_sel:[0,0,1]
	v_cvt_pk_fp8_f32 v55, v53, v56 op_sel:[0,0,1]
	v_add_u32_e32 v56, 0xffffec18, v8
	v_ashrrev_i32_e32 v73, 31, v72
	v_ashrrev_i32_e32 v57, 31, v56
	v_lshlrev_b64 v[72:73], 10, v[72:73]
	v_lshlrev_b64 v[56:57], 10, v[56:57]
	v_lshl_add_u64 v[72:73], v[74:75], 0, v[72:73]
	v_lshl_add_u64 v[56:57], v[74:75], 0, v[56:57]
	global_store_dwordx2 v[72:73], v[62:63], off
	global_store_dwordx2 v[56:57], v[54:55], off
	s_waitcnt lgkmcnt(0)
	s_cbranch_execnz .LBB0_20
; #define LAS __attribute__((address_space(3)))
; __device__ __forceinline__ unsigned cvt_pk(float lo, float hi) { f32x2_t v = {lo, hi}; bf16x2_t b = __builtin_convertvector(v, bf16x2_t); return __builtin_bit_cast(unsigned, b); }
; __device__ __forceinline__ unsigned pk_fp8x4(float a, float b, float c, float d) { int w = 0; w = __builtin_amdgcn_cvt_pk_fp8_f32(a, b, w, false); w = __builtin_amdgcn_cvt_pk_fp8_f32(c, d, w, true); return (unsigned)w; }
; template <bool F8 = false>
; __device__ __forceinline__ void p0_transpose_item(const float* W, int K, int N, bf16_t* WT, int k0, int n0, int drow0, const float* gs, LAS float* scr, int lane) {
;     ...
;     for (int i = 0; i < 32; ++i) wv[i] = W[(size_t)(k0 + 2 * i + (lane >> 5)) * N + n0 + (lane & 31)];
;     if (gs) {
; #pragma unroll
;         for (int i = 0; i < 32; ++i) wv[i] *= gs[k0 + 2 * i + (lane >> 5)]; }
; #pragma unroll
;     for (int i = 0; i < 32; ++i) scr[(2 * i + (lane >> 5)) * 33 + (lane & 31)] = wv[i];
;     asm volatile("s_waitcnt lgkmcnt(0)" ::: "memory");
;     const int c = lane & 7;
; #pragma unroll
;     for (int j = 0; j < 4; ++j) { const int n = (lane >> 3) + 8 * j; const LAS float* s = scr + (8 * c) * 33 + n;
;         if (F8) { u32x2 o8; o8.x = pk_fp8x4(32.f * s[0 * 33], 32.f * s[1 * 33], 32.f * s[2 * 33], 32.f * s[3 * 33]); o8.y = pk_fp8x4(32.f * s[4 * 33], 32.f * s[5 * 33], 32.f * s[6 * 33], 32.f * s[7 * 33]);
;             *(u32x2*)((unsigned char*)WT + (size_t)(drow0 + n) * K + k0 + 8 * c) = o8; }
;         else { u32x4 o; o.x = cvt_pk(s[0 * 33], s[1 * 33]); o.y = cvt_pk(s[2 * 33], s[3 * 33]); o.z = cvt_pk(s[4 * 33], s[5 * 33]); o.w = cvt_pk(s[6 * 33], s[7 * 33]);
;             *(u32x4*)(WT + (size_t)(drow0 + n) * K + k0 + 8 * c) = o; } }
; template <int PART>
; __device__ __forceinline__ void phase0(const Ptrs& P, LAS float* scr, int gw, int NGW, int lane) {
;     ...
;         if (r < I_IN) { const int nblk = NIN / 32, kb = r / nblk, nb = r % nblk, n0 = 32 * nb, sec = n0 >> 10;
;             if (sec < 5) p0_transpose_item(P.w_in, DM, NIN, (bf16_t*)(ws + WS_WIN), 64 * kb, n0, n0, nullptr, scr, lane);
.LBB0_24:
	s_ashr_i32 s5, s4, 31
	v_lshl_add_u64 v[54:55], s[4:5], 2, v[6:7]
	v_mad_i64_i32 v[52:53], s[4:5], v52, s30, v[54:55]
	v_mad_i64_i32 v[56:57], s[4:5], v51, s30, v[54:55]
	v_mad_i64_i32 v[50:51], s[4:5], v50, s30, v[54:55]
	v_mad_i64_i32 v[58:59], s[4:5], v49, s30, v[54:55]
	v_mad_i64_i32 v[48:49], s[4:5], v48, s30, v[54:55]
	v_mad_i64_i32 v[60:61], s[4:5], v47, s30, v[54:55]
	v_mad_i64_i32 v[46:47], s[4:5], v46, s30, v[54:55]
	v_mad_i64_i32 v[62:63], s[4:5], v45, s30, v[54:55]
	global_load_dword v64, v[52:53], off nt
	s_nop 0
	global_load_dword v56, v[56:57], off nt
	s_nop 0
	global_load_dword v57, v[50:51], off nt
	s_nop 0
	global_load_dword v58, v[58:59], off nt
	s_nop 0
	global_load_dword v59, v[48:49], off nt
	s_nop 0
	global_load_dword v60, v[60:61], off nt
	s_nop 0
	global_load_dword v61, v[46:47], off nt
	s_nop 0
	global_load_dword v62, v[62:63], off nt
	v_mad_i64_i32 v[44:45], s[4:5], v44, s30, v[54:55]
	v_mad_i64_i32 v[46:47], s[4:5], v43, s30, v[54:55]
	v_mad_i64_i32 v[42:43], s[4:5], v42, s30, v[54:55]
	v_mad_i64_i32 v[48:49], s[4:5], v41, s30, v[54:55]
	v_mad_i64_i32 v[40:41], s[4:5], v40, s30, v[54:55]
	v_mad_i64_i32 v[50:51], s[4:5], v39, s30, v[54:55]
	v_mad_i64_i32 v[38:39], s[4:5], v38, s30, v[54:55]
	v_mad_i64_i32 v[52:53], s[4:5], v37, s30, v[54:55]
	global_load_dword v63, v[44:45], off nt
	s_nop 0
	global_load_dword v46, v[46:47], off nt
	s_nop 0
	global_load_dword v47, v[42:43], off nt
	s_nop 0
	global_load_dword v48, v[48:49], off nt
	s_nop 0
	global_load_dword v49, v[40:41], off nt
	s_nop 0
	global_load_dword v50, v[50:51], off nt
	s_nop 0
	global_load_dword v51, v[38:39], off nt
	s_nop 0
	global_load_dword v52, v[52:53], off nt
	v_mad_i64_i32 v[36:37], s[4:5], v36, s30, v[54:55]
	v_mad_i64_i32 v[38:39], s[4:5], v35, s30, v[54:55]
	v_mad_i64_i32 v[34:35], s[4:5], v34, s30, v[54:55]
	v_mad_i64_i32 v[40:41], s[4:5], v33, s30, v[54:55]
	v_mad_i64_i32 v[32:33], s[4:5], v32, s30, v[54:55]
	v_mad_i64_i32 v[42:43], s[4:5], v31, s30, v[54:55]
	v_mad_i64_i32 v[30:31], s[4:5], v30, s30, v[54:55]
	v_mad_i64_i32 v[44:45], s[4:5], v29, s30, v[54:55]
	global_load_dword v53, v[36:37], off nt
	s_nop 0
	global_load_dword v38, v[38:39], off nt
	s_nop 0
	global_load_dword v39, v[34:35], off nt
	s_nop 0
	global_load_dword v40, v[40:41], off nt
	s_nop 0
	global_load_dword v41, v[32:33], off nt
	s_nop 0
	global_load_dword v42, v[42:43], off nt
	s_nop 0
	global_load_dword v43, v[30:31], off nt
	s_nop 0
	global_load_dword v44, v[44:45], off nt
	v_mad_i64_i32 v[28:29], s[4:5], v28, s30, v[54:55]
	v_mad_i64_i32 v[30:31], s[4:5], v27, s30, v[54:55]
	v_mad_i64_i32 v[26:27], s[4:5], v26, s30, v[54:55]
	v_mad_i64_i32 v[32:33], s[4:5], v25, s30, v[54:55]
	v_mad_i64_i32 v[24:25], s[4:5], v24, s30, v[54:55]
	v_mad_i64_i32 v[34:35], s[4:5], v23, s30, v[54:55]
	v_mad_i64_i32 v[22:23], s[4:5], v22, s30, v[54:55]
	v_mad_i64_i32 v[36:37], s[4:5], v9, s30, v[54:55]
	global_load_dword v9, v[28:29], off nt
	s_nop 0
	global_load_dword v28, v[30:31], off nt
	s_nop 0
	global_load_dword v26, v[26:27], off nt
	s_nop 0
	global_load_dword v27, v[32:33], off nt
	s_nop 0
	global_load_dword v24, v[24:25], off nt
	s_nop 0
	global_load_dword v25, v[34:35], off nt
	s_nop 0
	global_load_dword v22, v[22:23], off nt
	s_nop 0
	global_load_dword v23, v[36:37], off nt
	s_ashr_i32 s3, s2, 31
	s_waitcnt vmcnt(30)
	ds_write2_b32 v14, v64, v56 offset1:66
	s_waitcnt vmcnt(28)
	ds_write2_b32 v14, v57, v58 offset0:132 offset1:198
	s_waitcnt vmcnt(26)
	ds_write2_b32 v15, v59, v60 offset0:8 offset1:74
	s_waitcnt vmcnt(24)
	ds_write2_b32 v15, v61, v62 offset0:140 offset1:206
	s_waitcnt vmcnt(22)
	ds_write2_b32 v16, v63, v46 offset0:16 offset1:82
	s_waitcnt vmcnt(20)
	ds_write2_b32 v16, v47, v48 offset0:148 offset1:214
	s_waitcnt vmcnt(18)
	ds_write2_b32 v17, v49, v50 offset0:24 offset1:90
	s_waitcnt vmcnt(16)
	ds_write2_b32 v17, v51, v52 offset0:156 offset1:222
	s_waitcnt vmcnt(14)
	ds_write2_b32 v18, v53, v38 offset0:32 offset1:98
	s_waitcnt vmcnt(12)
	ds_write2_b32 v18, v39, v40 offset0:164 offset1:230
	s_waitcnt vmcnt(10)
	ds_write2_b32 v19, v41, v42 offset0:40 offset1:106
	s_waitcnt vmcnt(8)
	ds_write2_b32 v19, v43, v44 offset0:172 offset1:238
	s_waitcnt vmcnt(6)
	ds_write2_b32 v20, v9, v28 offset0:48 offset1:114
	s_waitcnt vmcnt(4)
	ds_write2_b32 v20, v26, v27 offset0:180 offset1:246
	s_waitcnt vmcnt(2)
	ds_write2_b32 v21, v24, v25 offset0:56 offset1:122
	s_waitcnt vmcnt(0)
	ds_write2_b32 v21, v22, v23 offset0:188 offset1:254
	s_waitcnt lgkmcnt(0)
	ds_read2_b32 v[26:27], v13 offset0:33 offset1:41
	ds_read2_b32 v[28:29], v13 offset1:8
	ds_read2_b32 v[30:31], v13 offset0:66 offset1:74
	ds_read2_b32 v[32:33], v13 offset0:99 offset1:107
	ds_read2_b32 v[34:35], v13 offset0:132 offset1:140
	ds_read2_b32 v[36:37], v13 offset0:165 offset1:173
	ds_read2_b32 v[38:39], v13 offset0:198 offset1:206
	ds_read2_b32 v[40:41], v13 offset0:231 offset1:239
	v_ashrrev_i32_e32 v9, 31, v8
	v_lshl_add_u64 v[42:43], s[2:3], 1, v[4:5]
	v_lshlrev_b64 v[44:45], 11, v[8:9]
	s_waitcnt lgkmcnt(6)
	v_cvt_pk_bf16_f32 v22, v28, v26
	s_waitcnt lgkmcnt(4)
	v_cvt_pk_bf16_f32 v23, v30, v32
	s_waitcnt lgkmcnt(2)
	v_cvt_pk_bf16_f32 v24, v34, v36
	s_waitcnt lgkmcnt(0)
	v_cvt_pk_bf16_f32 v25, v38, v40
	v_lshl_add_u64 v[44:45], v[42:43], 0, v[44:45]
	v_add_u32_e32 v26, 8, v8
	global_store_dwordx4 v[44:45], v[22:25], off
	s_nop 1
	v_cvt_pk_bf16_f32 v22, v29, v27
	v_ashrrev_i32_e32 v27, 31, v26
	v_cvt_pk_bf16_f32 v23, v31, v33
	v_cvt_pk_bf16_f32 v24, v35, v37
	v_cvt_pk_bf16_f32 v25, v39, v41
	v_lshlrev_b64 v[26:27], 11, v[26:27]
	ds_read2_b32 v[28:29], v13 offset0:49 offset1:57
	ds_read2_b32 v[30:31], v13 offset0:16 offset1:24
	ds_read2_b32 v[32:33], v13 offset0:82 offset1:90
	ds_read2_b32 v[34:35], v13 offset0:115 offset1:123
	ds_read2_b32 v[36:37], v13 offset0:148 offset1:156
	ds_read2_b32 v[38:39], v13 offset0:181 offset1:189
	ds_read2_b32 v[40:41], v13 offset0:214 offset1:222
	ds_read2_b32 v[44:45], v13 offset0:247 offset1:255
	v_lshl_add_u64 v[26:27], v[42:43], 0, v[26:27]
	global_store_dwordx4 v[26:27], v[22:25], off
	v_add_u32_e32 v26, 16, v8
	v_ashrrev_i32_e32 v27, 31, v26
	v_add_u32_e32 v8, 24, v8
	v_lshlrev_b64 v[26:27], 11, v[26:27]
	v_ashrrev_i32_e32 v9, 31, v8
	s_waitcnt lgkmcnt(6)
	v_cvt_pk_bf16_f32 v22, v30, v28
	s_waitcnt lgkmcnt(4)
	v_cvt_pk_bf16_f32 v23, v32, v34
	s_waitcnt lgkmcnt(2)
	v_cvt_pk_bf16_f32 v24, v36, v38
	s_waitcnt lgkmcnt(0)
	v_cvt_pk_bf16_f32 v25, v40, v44
	v_lshl_add_u64 v[26:27], v[42:43], 0, v[26:27]
	v_lshlrev_b64 v[8:9], 11, v[8:9]
	global_store_dwordx4 v[26:27], v[22:25], off
	v_lshl_add_u64 v[8:9], v[42:43], 0, v[8:9]
	s_nop 0
	v_cvt_pk_bf16_f32 v22, v31, v29
	v_cvt_pk_bf16_f32 v23, v33, v35
	v_cvt_pk_bf16_f32 v24, v37, v39
	v_cvt_pk_bf16_f32 v25, v41, v45
	global_store_dwordx4 v[8:9], v[22:25], off
	s_waitcnt lgkmcnt(0)
	s_branch .LBB0_20

; __device__ __forceinline__ unsigned cvt_pk(float lo, float hi) { f32x2_t v = {lo, hi}; bf16x2_t b = __builtin_convertvector(v, bf16x2_t); return __builtin_bit_cast(unsigned, b); }
; __device__ __forceinline__ unsigned pk_fp8x4(float a, float b, float c, float d) { int w = 0; w = __builtin_amdgcn_cvt_pk_fp8_f32(a, b, w, false); w = __builtin_amdgcn_cvt_pk_fp8_f32(c, d, w, true); return (unsigned)w; }
; template <int PART>
; __device__ __forceinline__ void phase0(const Ptrs& P, LAS float* scr, int gw, int NGW, int lane) {
;     ...
;     for (int m = gw; m < MT; m += NGW) {
;         const f32x4* xr = (const f32x4*)(P.x + (size_t)m * DM) + lane; const f32x4* gr = (const f32x4*)P.g_mix + lane;
;         f32x4 v[4]; float s = 0.f;
; #pragma unroll
;         for (int j = 0; j < 4; ++j) { v[j] = xr[64 * j]; s += (v[j][0] * v[j][0] + v[j][1] * v[j][1]) + (v[j][2] * v[j][2] + v[j][3] * v[j][3]); }
;         const float rstd = __builtin_amdgcn_rsqf(wave_sum(s) * (1.f / DM) + EPS);
;         u32x2* o8 = (u32x2*)(XN + (size_t)m * DM) + lane; unsigned* q8 = (unsigned*)(ws + WS_XN8 + (size_t)m * DM) + lane;
; #pragma unroll
;         for (int j = 0; j < 4; ++j) { const f32x4 g = gr[64 * j]; const float h0 = v[j][0] * rstd * g[0], h1 = v[j][1] * rstd * g[1], h2 = v[j][2] * rstd * g[2], h3 = v[j][3] * rstd * g[3];
;             u32x2 o; o.x = cvt_pk(h0, h1); o.y = cvt_pk(h2, h3); o8[64 * j] = o; q8[64 * j] = pk_fp8x4(h0, h1, h2, h3); }
;     }
.LBB0_27:
	global_load_dwordx4 v[18:21], v[6:7], off offset:-3072 nt
	global_load_dwordx4 v[22:25], v[6:7], off offset:-2048 nt
	global_load_dwordx4 v[26:29], v[6:7], off offset:-1024 nt
	global_load_dwordx4 v[30:33], v[6:7], off nt
	global_load_dwordx4 v[34:37], v[2:3], off
	v_mov_b32_e32 v17, 0
	s_add_i32 s27, s27, s58
	v_lshl_add_u64 v[6:7], v[6:7], 0, s[4:5]
	s_cmpk_gt_i32 s27, 0x3fff
	s_waitcnt vmcnt(4)
	v_pk_mul_f32 v[38:39], v[20:21], v[20:21]
	v_pk_mul_f32 v[40:41], v[18:19], v[18:19]
	s_waitcnt vmcnt(3)
	v_pk_mul_f32 v[42:43], v[24:25], v[24:25]
	v_pk_mul_f32 v[44:45], v[22:23], v[22:23]
	v_pk_mov_b32 v[50:51], v[40:41], v[38:39] op_sel:[1,0]
	v_mov_b32_e32 v41, v39
	v_pk_mov_b32 v[38:39], v[44:45], v[42:43] op_sel:[1,0]
	v_mov_b32_e32 v45, v43
	s_waitcnt vmcnt(1)
	v_mul_f32_e32 v49, v30, v30
	v_mul_f32_e32 v46, v27, v27
	v_mul_f32_e32 v48, v29, v29
	v_pk_add_f32 v[40:41], v[50:51], v[40:41]
	v_pk_add_f32 v[38:39], v[38:39], v[44:45]
	v_mul_f32_e32 v52, v31, v31
	v_mul_f32_e32 v53, v32, v32
	v_mul_f32_e32 v54, v33, v33
	v_pk_fma_f32 v[42:43], v[26:27], v[26:27], v[46:47] op_sel_hi:[1,1,0]
	v_pk_fma_f32 v[46:47], v[28:29], v[28:29], v[48:49] op_sel_hi:[1,1,0]
	v_pk_add_f32 v[40:41], v[40:41], v[40:41] op_sel:[0,1] op_sel_hi:[1,0]
	v_pk_add_f32 v[38:39], v[38:39], v[38:39] op_sel:[0,1] op_sel_hi:[1,0]
	v_mov_b32_e32 v43, v53
	v_mov_b32_e32 v47, v54
	v_mov_b32_e32 v41, v49
	v_mov_b32_e32 v39, v52
	v_pk_add_f32 v[42:43], v[42:43], v[46:47]
	v_pk_add_f32 v[38:39], v[40:41], v[38:39]
	s_nop 0
	v_pk_add_f32 v[38:39], v[38:39], v[42:43]
	s_nop 0
	v_add_f32_e32 v38, v38, v39
	ds_bpermute_b32 v39, v8, v38
	s_waitcnt lgkmcnt(0)
	v_add_f32_e32 v38, v38, v39
	ds_bpermute_b32 v39, v9, v38
	s_waitcnt lgkmcnt(0)
	v_add_f32_e32 v38, v38, v39
	ds_bpermute_b32 v39, v12, v38
	s_waitcnt lgkmcnt(0)
	v_add_f32_e32 v38, v38, v39
	ds_bpermute_b32 v39, v13, v38
	s_waitcnt lgkmcnt(0)
	v_add_f32_e32 v38, v38, v39
	ds_bpermute_b32 v39, v14, v38
	s_waitcnt lgkmcnt(0)
	v_add_f32_e32 v38, v38, v39
	ds_bpermute_b32 v39, v15, v38
	s_waitcnt lgkmcnt(0)
	v_add_f32_e32 v38, v38, v39
	v_fmamk_f32 v38, v38, 0x3a800000, v16
	v_rsq_f32_e32 v38, v38
	s_nop 0
	v_pk_mul_f32 v[18:19], v[18:19], v[38:39] op_sel_hi:[1,0]
	s_waitcnt vmcnt(0)
	v_pk_mul_f32 v[18:19], v[34:35], v[18:19]
	v_pk_mul_f32 v[20:21], v[20:21], v[38:39] op_sel_hi:[1,0]
	v_cvt_pk_fp8_f32 v17, v18, v19
	v_pk_mul_f32 v[20:21], v[36:37], v[20:21]
	v_cvt_pk_bf16_f32 v18, v18, v19
	v_cvt_pk_bf16_f32 v19, v20, v21
	v_cvt_pk_fp8_f32 v17, v20, v21 op_sel:[0,0,1]
	global_store_dwordx2 v[0:1], v[18:19], off offset:-1024
	v_pk_mul_f32 v[22:23], v[22:23], v[38:39] op_sel_hi:[1,0]
	v_pk_mul_f32 v[24:25], v[24:25], v[38:39] op_sel_hi:[1,0]
	global_store_dword v[4:5], v17, off offset:-512
	global_load_dwordx4 v[18:21], v[2:3], off offset:1024
	v_mov_b32_e32 v17, 0
	s_waitcnt vmcnt(0)
	v_pk_mul_f32 v[18:19], v[18:19], v[22:23]
	s_nop 0
	v_cvt_pk_fp8_f32 v17, v18, v19
	v_pk_mul_f32 v[20:21], v[20:21], v[24:25]
	v_cvt_pk_bf16_f32 v18, v18, v19
	v_cvt_pk_bf16_f32 v19, v20, v21
	v_cvt_pk_fp8_f32 v17, v20, v21 op_sel:[0,0,1]
	global_store_dwordx2 v[0:1], v[18:19], off offset:-512
	v_pk_mul_f32 v[22:23], v[26:27], v[38:39] op_sel_hi:[1,0]
	v_pk_mul_f32 v[24:25], v[28:29], v[38:39] op_sel_hi:[1,0]
	global_store_dword v[4:5], v17, off offset:-256
	global_load_dwordx4 v[18:21], v[2:3], off offset:2048
	v_mov_b32_e32 v17, 0
	s_waitcnt vmcnt(0)
	v_pk_mul_f32 v[18:19], v[22:23], v[18:19]
	s_nop 0
	v_cvt_pk_fp8_f32 v17, v18, v19
	v_pk_mul_f32 v[20:21], v[24:25], v[20:21]
	v_cvt_pk_bf16_f32 v18, v18, v19
	v_cvt_pk_bf16_f32 v19, v20, v21
	v_cvt_pk_fp8_f32 v17, v20, v21 op_sel:[0,0,1]
	global_store_dwordx2 v[0:1], v[18:19], off
	global_store_dword v[4:5], v17, off
	global_load_dwordx4 v[18:21], v[2:3], off offset:3072
	v_pk_mul_f32 v[22:23], v[30:31], v[38:39] op_sel_hi:[1,0]
	v_mov_b32_e32 v17, 0
	v_pk_mul_f32 v[24:25], v[32:33], v[38:39] op_sel_hi:[1,0]
	s_waitcnt vmcnt(0)
	v_pk_mul_f32 v[18:19], v[22:23], v[18:19]
	s_nop 0
	v_cvt_pk_fp8_f32 v17, v18, v19
	v_pk_mul_f32 v[20:21], v[24:25], v[20:21]
	v_cvt_pk_bf16_f32 v18, v18, v19
	v_cvt_pk_bf16_f32 v19, v20, v21
	v_cvt_pk_fp8_f32 v17, v20, v21 op_sel:[0,0,1]
	global_store_dwordx2 v[0:1], v[18:19], off offset:512
	v_lshl_add_u64 v[0:1], v[0:1], 0, s[6:7]
	global_store_dword v[4:5], v17, off offset:256
	v_lshl_add_u64 v[4:5], v[4:5], 0, s[2:3]
	s_cbranch_scc0 .LBB0_27

; __device__ __forceinline__ unsigned cvt_pk(float lo, float hi) { f32x2_t v = {lo, hi}; bf16x2_t b = __builtin_convertvector(v, bf16x2_t); return __builtin_bit_cast(unsigned, b); }
; template <int PART>
; __device__ __forceinline__ void phase0(const Ptrs& P, LAS float* scr, int gw, int NGW, int lane) {
;     ...
;     if (PART == 0) { bf16_t* WGF = (bf16_t*)(ws + WS_WGF);
;         for (int f = gw; f < 256; f += NGW) { const int kk = f & 3, cbh = (f >> 2) & 1, gate = (f >> 3) & 1, n = f >> 4;
;             const float* w = (gate ? P.w_ig : P.w_rg) + (size_t)n * 4096 + (size_t)(16 * kk + 8 * (lane >> 5)) * 64 + 32 * cbh + (lane & 31);
;             u32x4 o; o.x = cvt_pk(w[0], w[64]); o.y = cvt_pk(w[128], w[192]); o.z = cvt_pk(w[256], w[320]); o.w = cvt_pk(w[384], w[448]);
;             *(u32x4*)(WGF + ((size_t)f * 64 + lane) * 8) = o; } }
.LBB0_30:
	s_ashr_i32 s28, s24, 4
	s_bitcmp0_b32 s24, 3
	s_waitcnt lgkmcnt(0)
	s_cselect_b32 s4, s89, s9
	s_cselect_b32 s27, s88, s8
	s_ashr_i32 s29, s28, 31
	s_lshl_b64 s[28:29], s[28:29], 14
	v_and_or_b32 v0, s25, 48, v6
	s_add_u32 s28, s27, s28
	v_lshlrev_b32_e32 v0, 8, v0
	s_addc_u32 s29, s4, s29
	s_and_b32 s4, s6, 32
	v_lshl_add_u64 v[8:9], s[28:29], 0, v[0:1]
	s_lshl_b32 s4, s4, 2
	v_lshl_add_u64 v[8:9], v[8:9], 0, s[4:5]
	v_lshl_add_u64 v[8:9], v[8:9], 0, v[4:5]
	global_load_dword v0, v[8:9], off nt
	global_load_dword v7, v[8:9], off offset:256 nt
	global_load_dword v10, v[8:9], off offset:512 nt
	global_load_dword v11, v[8:9], off offset:768 nt
	global_load_dword v12, v[8:9], off offset:1024 nt
	global_load_dword v13, v[8:9], off offset:1280 nt
	global_load_dword v14, v[8:9], off offset:1536 nt
	global_load_dword v15, v[8:9], off offset:1792 nt
	s_add_i32 s24, s24, s58
	s_add_i32 s6, s6, s7
	s_add_i32 s25, s25, s26
	s_cmpk_lt_i32 s24, 0x100
	s_waitcnt vmcnt(6)
	v_cvt_pk_bf16_f32 v8, v0, v7
	s_waitcnt vmcnt(4)
	v_cvt_pk_bf16_f32 v9, v10, v11
	s_waitcnt vmcnt(2)
	v_cvt_pk_bf16_f32 v10, v12, v13
	s_waitcnt vmcnt(0)
	v_cvt_pk_bf16_f32 v11, v14, v15
	global_store_dwordx4 v[2:3], v[8:11], off
	v_lshl_add_u64 v[2:3], v[2:3], 0, s[2:3]
	s_cbranch_scc1 .LBB0_30

; #define LAS __attribute__((address_space(3)))
; template <bool DRY>
; __device__ __forceinline__ void attn_unit(const Ptrs& P, LAS unsigned char* wlds  , int wu, int lane) {
;     ...
;     bf16x8 qf[4];
;     { const bf16_t* qp = QO + (rowbase + tq) * DM + h * HD + 8 * hh;
; #pragma unroll
;         for (int kk = 0; kk < 4; ++kk) qf[kk] = *(const bf16x8*)(qp + 16 * kk); }
;     f32x16 o0, o1;
; #pragma unroll
;     for (int e = 0; e < 16; ++e) { o0[e] = 0.f; o1[e] = 0.f; }
;     float C2 = 0.f;
;     const int lrow = lane >> 3, lch = lane & 7;
;     const bf16_t* kg = Kb + (rowbase + lrow) * DM + h * HD + 8 * lch;
;     const bf16_t* vg = VT + (size_t)(h * HD + lrow) * MT + rowbase + 8 * lch;
;     LAS unsigned char* kl = wlds; LAS unsigned char* vl = wlds + 9216;
;     const int wofs = lrow * 144 + lch * 16, rofs = r32 * 144 + hh * 16;
;     u32x4 kr[8];
;     { const bf16_t* kp = kg + (size_t)((t0 >> 6) * 64) * DM;
; #pragma unroll
;         for (int i2 = 0; i2 < 8; ++i2) kr[i2] = *(const u32x4*)(kp + (size_t)(8 * i2) * DM); }
;     u32x4 vr[8];
; #pragma unroll
;     for (int i2 = 0; i2 < 8; ++i2) vr[i2] = *(const u32x4*)(vg + (size_t)(8 * i2) * MT + (t0 >> 6) * 64);
.LBB0_556:
	s_ashr_i32 s4, s81, 12
	s_lshl_b32 s8, s81, 5
	s_and_b32 s74, s8, 0x1fe0
	s_ashr_i32 s5, s4, 31
	v_or_b32_e32 v0, s74, v148
	s_lshl_b64 s[94:95], s[4:5], 13
	v_or_b32_e32 v0, s94, v0
	v_mov_b32_e32 v1, s95
	s_lshr_b32 s6, s81, 2
	v_lshlrev_b64 v[0:1], 11, v[0:1]
	s_and_b32 s92, s6, 0x3c0
	v_lshl_add_u64 v[0:1], s[86:87], 0, v[0:1]
	s_lshl_b32 s82, s92, 1
	v_lshl_add_u64 v[0:1], v[0:1], 0, s[82:83]
	v_lshl_add_u64 v[0:1], v[0:1], 0, v[146:147]
	global_load_dwordx4 v[64:67], v[0:1], off nt
	global_load_dwordx4 v[68:71], v[0:1], off offset:32 nt
	global_load_dwordx4 v[72:75], v[0:1], off offset:64 nt
	global_load_dwordx4 v[76:79], v[0:1], off offset:96 nt
	v_mov_b32_e32 v1, s95
	v_or_b32_e32 v0, s94, v144
	v_readlane_b32 s6, v247, 41
	v_lshlrev_b64 v[0:1], 11, v[0:1]
	v_readlane_b32 s7, v247, 42
	v_or_b32_e32 v2, s92, v144
	v_lshlrev_b32_e32 v2, 15, v2
	v_lshl_add_u64 v[0:1], s[6:7], 0, v[0:1]
	v_readlane_b32 s6, v247, 43
	v_mov_b32_e32 v3, v147
	v_readlane_b32 s7, v247, 44
	v_lshl_add_u64 v[0:1], v[0:1], 0, s[82:83]
	v_mov_b32_e32 v159, v147
	v_lshl_add_u64 v[2:3], s[6:7], 0, v[2:3]
	s_lshl_b64 s[6:7], s[4:5], 14
	v_lshl_add_u64 v[2:3], v[2:3], 0, s[6:7]
	s_and_b32 s6, s8, 0x1fc0
	v_lshl_add_u64 v[0:1], v[0:1], 0, v[158:159]
	s_lshl_b32 s82, s6, 11
	v_lshl_add_u64 v[0:1], v[0:1], 0, s[82:83]
	v_lshl_add_u64 v[160:161], v[2:3], 0, v[158:159]
	v_add_co_u32_e32 v2, vcc, s33, v0
	s_mov_b32 s7, 0x10000
	s_nop 0
	v_addc_co_u32_e32 v3, vcc, 0, v1, vcc
	global_load_dwordx4 v[80:83], v[0:1], off
	global_load_dwordx4 v[84:87], v[2:3], off
	v_add_co_u32_e32 v2, vcc, s75, v0
	s_lshl_b32 s82, s6, 1
	s_nop 0
	v_addc_co_u32_e32 v3, vcc, 0, v1, vcc
	v_add_co_u32_e32 v4, vcc, s96, v0
	s_mov_b32 s6, 0x40000
	s_nop 0
	v_addc_co_u32_e32 v5, vcc, 0, v1, vcc
	global_load_dwordx4 v[88:91], v[2:3], off
	global_load_dwordx4 v[92:95], v[4:5], off
	v_add_co_u32_e32 v2, vcc, s7, v0
	s_mov_b32 s7, 0x14000
	s_nop 0
	v_addc_co_u32_e32 v3, vcc, 0, v1, vcc
	v_add_co_u32_e32 v4, vcc, s7, v0
	s_mov_b32 s7, 0x18000
	s_nop 0
	v_addc_co_u32_e32 v5, vcc, 0, v1, vcc
	global_load_dwordx4 v[104:107], v[2:3], off
	global_load_dwordx4 v[108:111], v[4:5], off
	v_add_co_u32_e32 v2, vcc, s7, v0
	s_mov_b32 s7, 0x1c000
	s_nop 0
	v_addc_co_u32_e32 v3, vcc, 0, v1, vcc
	v_add_co_u32_e32 v0, vcc, s7, v0
	s_lshr_b32 s7, s81, 1
	s_nop 0
	v_addc_co_u32_e32 v1, vcc, 0, v1, vcc
	global_load_dwordx4 v[116:119], v[2:3], off
	global_load_dwordx4 v[124:127], v[0:1], off
	v_lshl_add_u64 v[0:1], v[160:161], 0, s[82:83]
	v_add_co_u32_e32 v2, vcc, s6, v0
	s_mov_b32 s6, 0x80000
	s_nop 0
	v_addc_co_u32_e32 v3, vcc, 0, v1, vcc
	global_load_dwordx4 v[96:99], v[0:1], off
	global_load_dwordx4 v[100:103], v[2:3], off
	v_add_co_u32_e32 v2, vcc, s6, v0
	s_mov_b32 s6, 0xc0000
	s_nop 0
	v_addc_co_u32_e32 v3, vcc, 0, v1, vcc
	v_add_co_u32_e32 v4, vcc, s6, v0
	s_mov_b32 s6, 0x100000
	s_nop 0
	v_addc_co_u32_e32 v5, vcc, 0, v1, vcc
	global_load_dwordx4 v[112:115], v[2:3], off
	global_load_dwordx4 v[120:123], v[4:5], off
	v_add_co_u32_e32 v2, vcc, s6, v0
	s_mov_b32 s6, 0x140000
	s_nop 0
	v_addc_co_u32_e32 v3, vcc, 0, v1, vcc
	v_add_co_u32_e32 v4, vcc, s6, v0
	s_lshl_b32 s6, s80, 11
	s_nop 0
	v_addc_co_u32_e32 v5, vcc, 0, v1, vcc
	global_load_dwordx4 v[128:131], v[2:3], off
	global_load_dwordx4 v[132:135], v[4:5], off
	v_add_co_u32_e32 v2, vcc, 0x180000, v0
	s_and_b32 s86, s6, 0xfe0000
	s_nop 0
	v_addc_co_u32_e32 v3, vcc, 0, v1, vcc
	v_add_co_u32_e32 v0, vcc, 0x1c0000, v0
	s_and_b32 s6, s80, 0x1fe0
	s_nop 0
	v_addc_co_u32_e32 v1, vcc, 0, v1, vcc
	global_load_dwordx4 v[136:139], v[2:3], off
	global_load_dwordx4 v[140:143], v[0:1], off
	s_and_b32 s7, s7, 0x780
	s_lshl_b64 s[4:5], s[4:5], 24
	v_add_u32_e32 v0, s6, v149
	s_and_b32 s6, s80, 0x1fc0
	s_or_b32 s4, s4, s7
	v_mov_b32_e32 v169, 0
	s_mov_b32 s87, s83
	v_subrev_u32_e32 v159, s6, v0
	v_lshl_add_u64 v[162:163], v[154:155], 0, s[4:5]
	s_mov_b64 s[4:5], 0
	s_mov_b32 s82, s6
	v_mov_b32_e32 v0, 0
	v_mov_b32_e32 v1, v169
	v_mov_b32_e32 v2, v169
	v_mov_b32_e32 v3, v169
	v_mov_b32_e32 v4, v169
	v_mov_b32_e32 v5, v169
	v_mov_b32_e32 v6, v169
	v_mov_b32_e32 v7, v169
	v_mov_b32_e32 v8, v169
	v_mov_b32_e32 v9, v169
	v_mov_b32_e32 v10, v169
	v_mov_b32_e32 v11, v169
	v_mov_b32_e32 v12, v169
	v_mov_b32_e32 v13, v169
	v_mov_b32_e32 v14, v169
	v_mov_b32_e32 v15, v169
	v_mov_b32_e32 v16, 0
	v_mov_b32_e32 v17, v169
	v_mov_b32_e32 v18, v169
	v_mov_b32_e32 v19, v169
	v_mov_b32_e32 v20, v169
	v_mov_b32_e32 v21, v169
	v_mov_b32_e32 v22, v169
	v_mov_b32_e32 v23, v169
	v_mov_b32_e32 v24, v169
	v_mov_b32_e32 v25, v169
	v_mov_b32_e32 v26, v169
	v_mov_b32_e32 v27, v169
	v_mov_b32_e32 v28, v169
	v_mov_b32_e32 v29, v169
	v_mov_b32_e32 v30, v169
	v_mov_b32_e32 v31, v169
	s_branch .LBB0_558

; __device__ __forceinline__ u32x4 pack8(f32x4 a, f32x4 b) { u32x4 w; w.x = cvt_pk(a[0], a[1]); w.y = cvt_pk(a[2], a[3]); w.z = cvt_pk(b[0], b[1]); w.w = cvt_pk(b[2], b[3]); return w; }
; __device__ __forceinline__ void lru_light(const Ptrs& P, int wu, int lane) {
;     ...
;     const size_t base = ((size_t)b * SEQ + chunk * 128 + (lane >> 3)) * DM + ch0;
; #pragma unroll 4
;     for (int i = 0; i < 16; ++i) { const size_t o = base + (size_t)(8 * i) * DM;
;         const u32x4 y = *(const u32x4*)(YL + o), p = *(const u32x4*)(PU + o);
;         f32x4 v0, v1;
;         v0[0] = bflo(y.x) + bflo(p.x) * s0[0]; v0[1] = bfhi(y.x) + bfhi(p.x) * s0[1]; v0[2] = bflo(y.y) + bflo(p.y) * s0[2]; v0[3] = bfhi(y.y) + bfhi(p.y) * s0[3];
;         v1[0] = bflo(y.z) + bflo(p.z) * s1[0]; v1[1] = bfhi(y.z) + bfhi(p.z) * s1[1]; v1[2] = bflo(y.w) + bflo(p.w) * s1[2]; v1[3] = bfhi(y.w) + bfhi(p.w) * s1[3];
;         *(u32x4*)(YL + o) = pack8(v0, v1); }
.LBB0_576:
	v_lshl_add_u64 v[2:3], v[0:1], 0, s[4:5]
	s_mov_b32 s6, 0x3804000
	v_add_co_u32_e64 v38, s[6:7], s6, v2
	s_mov_b32 s8, 0x7804000
	s_nop 0
	v_addc_co_u32_e64 v39, s[6:7], 0, v3, s[6:7]
	v_add_co_u32_e64 v8, s[6:7], s8, v2
	s_mov_b32 s9, 0x3808000
	s_nop 0
	v_addc_co_u32_e64 v9, s[6:7], 0, v3, s[6:7]
	v_add_co_u32_e64 v40, s[6:7], s9, v2
	s_mov_b32 s12, 0x7808000
	s_nop 0
	v_addc_co_u32_e64 v41, s[6:7], 0, v3, s[6:7]
	v_add_co_u32_e64 v16, s[6:7], s12, v2
	s_mov_b32 s13, 0x380c000
	s_nop 0
	v_addc_co_u32_e64 v17, s[6:7], 0, v3, s[6:7]
	v_add_co_u32_e64 v42, s[6:7], s13, v2
	s_mov_b32 s14, 0x780c000
	v_add_co_u32_e32 v36, vcc, 0x3800000, v2
	v_addc_co_u32_e64 v43, s[6:7], 0, v3, s[6:7]
	v_add_co_u32_e64 v24, s[6:7], s14, v2
	v_addc_co_u32_e32 v37, vcc, 0, v3, vcc
	s_nop 0
	v_addc_co_u32_e64 v25, s[6:7], 0, v3, s[6:7]
	v_add_co_u32_e32 v2, vcc, 0x7800000, v2
	global_load_dwordx4 v[4:7], v[38:39], off
	s_nop 0
	global_load_dwordx4 v[8:11], v[8:9], off nt
	s_nop 0
	global_load_dwordx4 v[12:15], v[40:41], off
	s_nop 0
	global_load_dwordx4 v[16:19], v[16:17], off nt
	s_nop 0
	global_load_dwordx4 v[20:23], v[42:43], off
	s_nop 0
	global_load_dwordx4 v[24:27], v[24:25], off nt
	v_addc_co_u32_e32 v3, vcc, 0, v3, vcc
	global_load_dwordx4 v[28:31], v[36:37], off
	global_load_dwordx4 v[32:35], v[2:3], off nt
	s_add_u32 s4, s4, 0x10000
	s_addc_u32 s5, s5, 0
	s_cmp_lg_u32 s4, 0x40000
	s_waitcnt vmcnt(7)
	v_lshlrev_b32_e32 v2, 16, v4
	v_and_b32_e32 v3, 0xffff0000, v4
	s_waitcnt vmcnt(6)
	v_lshlrev_b32_e32 v44, 16, v8
	v_and_b32_e32 v45, 0xffff0000, v8
	v_lshlrev_b32_e32 v4, 16, v5
	v_and_b32_e32 v5, 0xffff0000, v5
	v_lshlrev_b32_e32 v8, 16, v9
	v_and_b32_e32 v9, 0xffff0000, v9
	v_lshlrev_b32_e32 v46, 16, v6
	v_and_b32_e32 v47, 0xffff0000, v6
	v_lshlrev_b32_e32 v48, 16, v10
	v_and_b32_e32 v49, 0xffff0000, v10
	v_lshlrev_b32_e32 v6, 16, v7
	v_and_b32_e32 v7, 0xffff0000, v7
	v_lshlrev_b32_e32 v10, 16, v11
	v_and_b32_e32 v11, 0xffff0000, v11
	s_waitcnt vmcnt(5)
	v_lshlrev_b32_e32 v50, 16, v12
	v_and_b32_e32 v51, 0xffff0000, v12
	s_waitcnt vmcnt(4)
	v_lshlrev_b32_e32 v52, 16, v16
	v_and_b32_e32 v53, 0xffff0000, v16
	v_lshlrev_b32_e32 v12, 16, v13
	v_and_b32_e32 v13, 0xffff0000, v13
	v_lshlrev_b32_e32 v16, 16, v17
	v_and_b32_e32 v17, 0xffff0000, v17
	v_lshlrev_b32_e32 v54, 16, v14
	v_and_b32_e32 v55, 0xffff0000, v14
	v_lshlrev_b32_e32 v56, 16, v18
	v_and_b32_e32 v57, 0xffff0000, v18
	v_lshlrev_b32_e32 v14, 16, v15
	v_and_b32_e32 v15, 0xffff0000, v15
	v_lshlrev_b32_e32 v18, 16, v19
	v_and_b32_e32 v19, 0xffff0000, v19
	s_waitcnt vmcnt(3)
	v_lshlrev_b32_e32 v58, 16, v20
	v_and_b32_e32 v59, 0xffff0000, v20
	s_waitcnt vmcnt(2)
	v_lshlrev_b32_e32 v60, 16, v24
	v_and_b32_e32 v61, 0xffff0000, v24
	v_lshlrev_b32_e32 v20, 16, v21
	v_and_b32_e32 v21, 0xffff0000, v21
	v_lshlrev_b32_e32 v24, 16, v25
	v_and_b32_e32 v25, 0xffff0000, v25
	v_lshlrev_b32_e32 v62, 16, v22
	v_and_b32_e32 v63, 0xffff0000, v22
	v_lshlrev_b32_e32 v72, 16, v26
	v_and_b32_e32 v73, 0xffff0000, v26
	v_lshlrev_b32_e32 v22, 16, v23
	v_and_b32_e32 v23, 0xffff0000, v23
	v_lshlrev_b32_e32 v26, 16, v27
	v_and_b32_e32 v27, 0xffff0000, v27
	s_waitcnt vmcnt(1)
	v_lshlrev_b32_e32 v74, 16, v28
	v_and_b32_e32 v75, 0xffff0000, v28
	v_lshlrev_b32_e32 v28, 16, v29
	v_and_b32_e32 v29, 0xffff0000, v29
	v_lshlrev_b32_e32 v76, 16, v30
	v_and_b32_e32 v77, 0xffff0000, v30
	v_lshlrev_b32_e32 v30, 16, v31
	v_and_b32_e32 v31, 0xffff0000, v31
	v_pk_fma_f32 v[2:3], v[64:65], v[44:45], v[2:3]
	v_pk_fma_f32 v[4:5], v[66:67], v[8:9], v[4:5]
	v_pk_fma_f32 v[8:9], v[68:69], v[48:49], v[46:47]
	v_pk_fma_f32 v[6:7], v[70:71], v[10:11], v[6:7]
	v_pk_fma_f32 v[10:11], v[64:65], v[52:53], v[50:51]
	v_pk_fma_f32 v[12:13], v[66:67], v[16:17], v[12:13]
	v_pk_fma_f32 v[16:17], v[68:69], v[56:57], v[54:55]
	v_pk_fma_f32 v[14:15], v[70:71], v[18:19], v[14:15]
	v_pk_fma_f32 v[18:19], v[64:65], v[60:61], v[58:59]
	v_pk_fma_f32 v[20:21], v[66:67], v[24:25], v[20:21]
	v_pk_fma_f32 v[22:23], v[70:71], v[26:27], v[22:23]
	s_waitcnt vmcnt(0)
	v_lshlrev_b32_e32 v26, 16, v32
	v_and_b32_e32 v27, 0xffff0000, v32
	v_lshlrev_b32_e32 v32, 16, v33
	v_and_b32_e32 v33, 0xffff0000, v33
	v_lshlrev_b32_e32 v44, 16, v34
	v_and_b32_e32 v45, 0xffff0000, v34
	v_lshlrev_b32_e32 v34, 16, v35
	v_and_b32_e32 v35, 0xffff0000, v35
	v_pk_fma_f32 v[24:25], v[68:69], v[72:73], v[62:63]
	v_cvt_pk_bf16_f32 v2, v2, v3
	v_cvt_pk_bf16_f32 v3, v4, v5
	v_cvt_pk_bf16_f32 v4, v8, v9
	v_cvt_pk_bf16_f32 v5, v6, v7
	v_cvt_pk_bf16_f32 v6, v10, v11
	v_cvt_pk_bf16_f32 v8, v16, v17
	v_cvt_pk_bf16_f32 v9, v14, v15
	v_cvt_pk_bf16_f32 v10, v18, v19
	v_cvt_pk_bf16_f32 v11, v20, v21
	v_pk_fma_f32 v[14:15], v[64:65], v[26:27], v[74:75]
	v_pk_fma_f32 v[16:17], v[66:67], v[32:33], v[28:29]
	v_pk_fma_f32 v[18:19], v[68:69], v[44:45], v[76:77]
	v_pk_fma_f32 v[20:21], v[70:71], v[34:35], v[30:31]
	v_cvt_pk_bf16_f32 v7, v12, v13
	v_cvt_pk_bf16_f32 v12, v24, v25
	v_cvt_pk_bf16_f32 v13, v22, v23
	global_store_dwordx4 v[38:39], v[2:5], off
	global_store_dwordx4 v[40:41], v[6:9], off
	global_store_dwordx4 v[42:43], v[10:13], off
	v_cvt_pk_bf16_f32 v2, v14, v15
	v_cvt_pk_bf16_f32 v3, v16, v17
	v_cvt_pk_bf16_f32 v4, v18, v19
	v_cvt_pk_bf16_f32 v5, v20, v21
	global_store_dwordx4 v[36:37], v[2:5], off
	s_cbranch_scc1 .LBB0_576
	s_branch .LBB0_565

;     __device__ __forceinline__ void operator()(f32x4 (&acc)[2][2][4][2], const pg8::Unit& u, int wr, int wc, int fr, int fq) const {
;     ...
;             for (int m = 0; m < 4; ++m) { const size_t ro = (size_t)(row0 + ai * 128 + m * 16) * DM + colt;
; #pragma unroll
;                 for (int bj = 0; bj < 2; ++bj) { const size_t o = ro + bj * 128;
;                     const u32x4 ga = *(const u32x4*)(GA + o);
;                     float a8[8] = {bflo(ga.x), bfhi(ga.x), bflo(ga.y), bfhi(ga.y), bflo(ga.z), bfhi(ga.z), bflo(ga.w), bfhi(ga.w)};
; #pragma unroll
;                     for (int e = 0; e < 8; ++e) a8[e] = fmaxf(a8[e], 1e-30f);
;                     if (u.kind == 0) { const u32x4 gl = *(const u32x4*)(GL + o);
;                         const float l8[8] = {bflo(gl.x), bfhi(gl.x), bflo(gl.y), bfhi(gl.y), bflo(gl.z), bfhi(gl.z), bflo(gl.w), bfhi(gl.w)};
; #pragma unroll
;                         for (int e = 0; e < 4; ++e) { acc[ai][bj][m][0][e] *= l8[e] * __builtin_amdgcn_rcpf(a8[e]); acc[ai][bj][m][1][e] *= l8[4 + e] * __builtin_amdgcn_rcpf(a8[4 + e]); }
.LBB0_651:
	v_readlane_b32 s58, v247, 26
	v_readlane_b32 s59, v247, 27
	v_readlane_b32 s60, v247, 29
	v_readlane_b32 s61, v247, 30
	s_lshl_b32 s21, s56, 8
	s_or_b32 s21, s21, s47
	v_ashrrev_i32_e32 v156, 1, v158
	v_and_b32_e32 v156, -8, v156
	v_add_u32_e32 v156, s21, v156
	v_and_or_b32 v157, v158, 15, s46
	v_lshl_add_u32 v157, s4, 8, v157
	v_lshlrev_b32_e32 v234, 11, v157
	v_lshl_add_u32 v234, v156, 1, v234
	s_mov_b64 s[98:99], s[78:79]
	s_cmp_lg_u32 s5, 0
	s_cselect_b64 s[28:29], -1, 0
	s_cbranch_scc1 .Lbr_kind1
	s_mov_b64 s[100:101], s[66:67]
	global_load_dwordx4 v[140:143], v234, s[98:99]
	global_load_dwordx4 v[178:181], v234, s[100:101] nt
	global_load_dwordx4 v[144:147], v234, s[98:99] offset:256
	global_load_dwordx4 v[186:189], v234, s[100:101] offset:256 nt
	s_add_u32 s98, s98, 0x8000
	s_addc_u32 s99, s99, 0
	s_add_u32 s100, s100, 0x8000
	s_addc_u32 s101, s101, 0
	global_load_dwordx4 v[148:151], v234, s[98:99]
	global_load_dwordx4 v[190:193], v234, s[100:101] nt
	global_load_dwordx4 v[152:155], v234, s[98:99] offset:256
	global_load_dwordx4 v[194:197], v234, s[100:101] offset:256 nt
	s_add_u32 s98, s98, 0x8000
	s_addc_u32 s99, s99, 0
	s_add_u32 s100, s100, 0x8000
	s_addc_u32 s101, s101, 0
	global_load_dwordx4 v[162:165], v234, s[98:99]
	global_load_dwordx4 v[198:201], v234, s[100:101] nt
	global_load_dwordx4 v[166:169], v234, s[98:99] offset:256
	global_load_dwordx4 v[202:205], v234, s[100:101] offset:256 nt
	s_add_u32 s98, s98, 0x8000
	s_addc_u32 s99, s99, 0
	s_add_u32 s100, s100, 0x8000
	s_addc_u32 s101, s101, 0
	global_load_dwordx4 v[170:173], v234, s[98:99]
	global_load_dwordx4 v[206:209], v234, s[100:101] nt
	global_load_dwordx4 v[174:177], v234, s[98:99] offset:256
	global_load_dwordx4 v[210:213], v234, s[100:101] offset:256 nt
	s_add_u32 s98, s98, 0x28000
	s_addc_u32 s99, s99, 0
	s_add_u32 s100, s100, 0x28000
	s_addc_u32 s101, s101, 0
	s_waitcnt vmcnt(0)
	v_lshlrev_b32_e32 v214, 16, v140
	v_and_b32_e32 v215, 0xffff0000, v140
	v_lshlrev_b32_e32 v216, 16, v141
	v_and_b32_e32 v217, 0xffff0000, v141
	v_lshlrev_b32_e32 v218, 16, v142
	v_and_b32_e32 v219, 0xffff0000, v142
	v_lshlrev_b32_e32 v220, 16, v143
	v_and_b32_e32 v221, 0xffff0000, v143
	v_max_f32_e32 v214, v214, v214
	v_max_f32_e32 v215, v215, v215
	v_max_f32_e32 v216, v216, v216
	v_max_f32_e32 v217, v217, v217
	v_max_f32_e32 v218, v218, v218
	v_max_f32_e32 v219, v219, v219
	v_max_f32_e32 v220, v220, v220
	v_max_f32_e32 v221, v221, v221
	v_max_f32_e32 v214, 0xda24260, v214
	v_max_f32_e32 v215, 0xda24260, v215
	v_max_f32_e32 v216, 0xda24260, v216
	v_max_f32_e32 v217, 0xda24260, v217
	v_max_f32_e32 v218, 0xda24260, v218
	v_max_f32_e32 v219, 0xda24260, v219
	v_max_f32_e32 v220, 0xda24260, v220
	v_max_f32_e32 v221, 0xda24260, v221
	v_rcp_f32_e32 v214, v214
	v_rcp_f32_e32 v215, v215
	v_rcp_f32_e32 v216, v216
	v_rcp_f32_e32 v217, v217
	v_rcp_f32_e32 v218, v218
	v_rcp_f32_e32 v219, v219
	v_rcp_f32_e32 v220, v220
	v_rcp_f32_e32 v221, v221
	v_lshlrev_b32_e32 v222, 16, v178
	v_and_b32_e32 v223, 0xffff0000, v178
	v_lshlrev_b32_e32 v224, 16, v179
	v_and_b32_e32 v225, 0xffff0000, v179
	v_lshlrev_b32_e32 v226, 16, v180
	v_and_b32_e32 v227, 0xffff0000, v180
	v_lshlrev_b32_e32 v228, 16, v181
	v_and_b32_e32 v229, 0xffff0000, v181
	v_pk_mul_f32 v[214:215], v[214:215], v[222:223]
	v_pk_mul_f32 v[216:217], v[216:217], v[224:225]
	v_pk_mul_f32 v[218:219], v[218:219], v[226:227]
	v_pk_mul_f32 v[220:221], v[220:221], v[228:229]
	v_pk_mul_f32 v[124:125], v[124:125], v[214:215]
	v_pk_mul_f32 v[126:127], v[126:127], v[216:217]
	v_pk_mul_f32 v[120:121], v[120:121], v[218:219]
	v_pk_mul_f32 v[122:123], v[122:123], v[220:221]
	v_lshlrev_b32_e32 v214, 16, v144
	v_and_b32_e32 v215, 0xffff0000, v144
	v_lshlrev_b32_e32 v216, 16, v145
	v_and_b32_e32 v217, 0xffff0000, v145
	v_lshlrev_b32_e32 v218, 16, v146
	v_and_b32_e32 v219, 0xffff0000, v146
	v_lshlrev_b32_e32 v220, 16, v147
	v_and_b32_e32 v221, 0xffff0000, v147
	v_max_f32_e32 v214, v214, v214
	v_max_f32_e32 v215, v215, v215
	v_max_f32_e32 v216, v216, v216
	v_max_f32_e32 v217, v217, v217
	v_max_f32_e32 v218, v218, v218
	v_max_f32_e32 v219, v219, v219
	v_max_f32_e32 v220, v220, v220
	v_max_f32_e32 v221, v221, v221
	v_max_f32_e32 v214, 0xda24260, v214
	v_max_f32_e32 v215, 0xda24260, v215
	v_max_f32_e32 v216, 0xda24260, v216
	v_max_f32_e32 v217, 0xda24260, v217
	v_max_f32_e32 v218, 0xda24260, v218
	v_max_f32_e32 v219, 0xda24260, v219
	v_max_f32_e32 v220, 0xda24260, v220
	v_max_f32_e32 v221, 0xda24260, v221
	v_rcp_f32_e32 v214, v214
	v_rcp_f32_e32 v215, v215
	v_rcp_f32_e32 v216, v216
	v_rcp_f32_e32 v217, v217
	v_rcp_f32_e32 v218, v218
	v_rcp_f32_e32 v219, v219
	v_rcp_f32_e32 v220, v220
	v_rcp_f32_e32 v221, v221
	v_lshlrev_b32_e32 v222, 16, v186
	v_and_b32_e32 v223, 0xffff0000, v186
	v_lshlrev_b32_e32 v224, 16, v187
	v_and_b32_e32 v225, 0xffff0000, v187
	v_lshlrev_b32_e32 v226, 16, v188
	v_and_b32_e32 v227, 0xffff0000, v188
	v_lshlrev_b32_e32 v228, 16, v189
	v_and_b32_e32 v229, 0xffff0000, v189
	v_pk_mul_f32 v[214:215], v[214:215], v[222:223]
	v_pk_mul_f32 v[216:217], v[216:217], v[224:225]
	v_pk_mul_f32 v[218:219], v[218:219], v[226:227]
	v_pk_mul_f32 v[220:221], v[220:221], v[228:229]
	v_pk_mul_f32 v[92:93], v[92:93], v[214:215]
	v_pk_mul_f32 v[94:95], v[94:95], v[216:217]
	v_pk_mul_f32 v[88:89], v[88:89], v[218:219]
	v_pk_mul_f32 v[90:91], v[90:91], v[220:221]
	v_lshlrev_b32_e32 v214, 16, v148
	v_and_b32_e32 v215, 0xffff0000, v148
	v_lshlrev_b32_e32 v216, 16, v149
	v_and_b32_e32 v217, 0xffff0000, v149
	v_lshlrev_b32_e32 v218, 16, v150
	v_and_b32_e32 v219, 0xffff0000, v150
	v_lshlrev_b32_e32 v220, 16, v151
	v_and_b32_e32 v221, 0xffff0000, v151
;     __device__ __forceinline__ void operator()(f32x4 (&acc)[2][2][4][2], const pg8::Unit& u, int wr, int wc, int fr, int fq) const {
;     ...
;                     if (u.kind == 0) { const u32x4 gl = *(const u32x4*)(GL + o);
;                         const float l8[8] = {bflo(gl.x), bfhi(gl.x), bflo(gl.y), bfhi(gl.y), bflo(gl.z), bfhi(gl.z), bflo(gl.w), bfhi(gl.w)};
; #pragma unroll
;                         for (int e = 0; e < 4; ++e) { acc[ai][bj][m][0][e] *= l8[e] * __builtin_amdgcn_rcpf(a8[e]); acc[ai][bj][m][1][e] *= l8[4 + e] * __builtin_amdgcn_rcpf(a8[4 + e]); }
	v_max_f32_e32 v214, v214, v214
	v_max_f32_e32 v215, v215, v215
	v_max_f32_e32 v216, v216, v216
	v_max_f32_e32 v217, v217, v217
	v_max_f32_e32 v218, v218, v218
	v_max_f32_e32 v219, v219, v219
	v_max_f32_e32 v220, v220, v220
	v_max_f32_e32 v221, v221, v221
	v_max_f32_e32 v214, 0xda24260, v214
	v_max_f32_e32 v215, 0xda24260, v215
	v_max_f32_e32 v216, 0xda24260, v216
	v_max_f32_e32 v217, 0xda24260, v217
	v_max_f32_e32 v218, 0xda24260, v218
	v_max_f32_e32 v219, 0xda24260, v219
	v_max_f32_e32 v220, 0xda24260, v220
	v_max_f32_e32 v221, 0xda24260, v221
	v_rcp_f32_e32 v214, v214
	v_rcp_f32_e32 v215, v215
	v_rcp_f32_e32 v216, v216
	v_rcp_f32_e32 v217, v217
	v_rcp_f32_e32 v218, v218
	v_rcp_f32_e32 v219, v219
	v_rcp_f32_e32 v220, v220
	v_rcp_f32_e32 v221, v221
	v_lshlrev_b32_e32 v222, 16, v190
	v_and_b32_e32 v223, 0xffff0000, v190
	v_lshlrev_b32_e32 v224, 16, v191
	v_and_b32_e32 v225, 0xffff0000, v191
	v_lshlrev_b32_e32 v226, 16, v192
	v_and_b32_e32 v227, 0xffff0000, v192
	v_lshlrev_b32_e32 v228, 16, v193
	v_and_b32_e32 v229, 0xffff0000, v193
	v_pk_mul_f32 v[214:215], v[214:215], v[222:223]
	v_pk_mul_f32 v[216:217], v[216:217], v[224:225]
	v_pk_mul_f32 v[218:219], v[218:219], v[226:227]
	v_pk_mul_f32 v[220:221], v[220:221], v[228:229]
	v_pk_mul_f32 v[116:117], v[116:117], v[214:215]
	v_pk_mul_f32 v[118:119], v[118:119], v[216:217]
	v_pk_mul_f32 v[112:113], v[112:113], v[218:219]
	v_pk_mul_f32 v[114:115], v[114:115], v[220:221]
	v_lshlrev_b32_e32 v214, 16, v152
	v_and_b32_e32 v215, 0xffff0000, v152
	v_lshlrev_b32_e32 v216, 16, v153
	v_and_b32_e32 v217, 0xffff0000, v153
	v_lshlrev_b32_e32 v218, 16, v154
	v_and_b32_e32 v219, 0xffff0000, v154
	v_lshlrev_b32_e32 v220, 16, v155
	v_and_b32_e32 v221, 0xffff0000, v155
	v_max_f32_e32 v214, v214, v214
	v_max_f32_e32 v215, v215, v215
	v_max_f32_e32 v216, v216, v216
	v_max_f32_e32 v217, v217, v217
	v_max_f32_e32 v218, v218, v218
	v_max_f32_e32 v219, v219, v219
	v_max_f32_e32 v220, v220, v220
	v_max_f32_e32 v221, v221, v221
	v_max_f32_e32 v214, 0xda24260, v214
	v_max_f32_e32 v215, 0xda24260, v215
	v_max_f32_e32 v216, 0xda24260, v216
	v_max_f32_e32 v217, 0xda24260, v217
	v_max_f32_e32 v218, 0xda24260, v218
	v_max_f32_e32 v219, 0xda24260, v219
	v_max_f32_e32 v220, 0xda24260, v220
	v_max_f32_e32 v221, 0xda24260, v221
	v_rcp_f32_e32 v214, v214
	v_rcp_f32_e32 v215, v215
	v_rcp_f32_e32 v216, v216
	v_rcp_f32_e32 v217, v217
	v_rcp_f32_e32 v218, v218
	v_rcp_f32_e32 v219, v219
	v_rcp_f32_e32 v220, v220
	v_rcp_f32_e32 v221, v221
	v_lshlrev_b32_e32 v222, 16, v194
	v_and_b32_e32 v223, 0xffff0000, v194
	v_lshlrev_b32_e32 v224, 16, v195
	v_and_b32_e32 v225, 0xffff0000, v195
	v_lshlrev_b32_e32 v226, 16, v196
	v_and_b32_e32 v227, 0xffff0000, v196
	v_lshlrev_b32_e32 v228, 16, v197
	v_and_b32_e32 v229, 0xffff0000, v197
	v_pk_mul_f32 v[214:215], v[214:215], v[222:223]
	v_pk_mul_f32 v[216:217], v[216:217], v[224:225]
	v_pk_mul_f32 v[218:219], v[218:219], v[226:227]
	v_pk_mul_f32 v[220:221], v[220:221], v[228:229]
	v_pk_mul_f32 v[84:85], v[84:85], v[214:215]
	v_pk_mul_f32 v[86:87], v[86:87], v[216:217]
	v_pk_mul_f32 v[80:81], v[80:81], v[218:219]
	v_pk_mul_f32 v[82:83], v[82:83], v[220:221]
	v_lshlrev_b32_e32 v214, 16, v162
	v_and_b32_e32 v215, 0xffff0000, v162
	v_lshlrev_b32_e32 v216, 16, v163
	v_and_b32_e32 v217, 0xffff0000, v163
	v_lshlrev_b32_e32 v218, 16, v164
	v_and_b32_e32 v219, 0xffff0000, v164
	v_lshlrev_b32_e32 v220, 16, v165
	v_and_b32_e32 v221, 0xffff0000, v165
	v_max_f32_e32 v214, v214, v214
	v_max_f32_e32 v215, v215, v215
	v_max_f32_e32 v216, v216, v216
	v_max_f32_e32 v217, v217, v217
	v_max_f32_e32 v218, v218, v218
	v_max_f32_e32 v219, v219, v219
	v_max_f32_e32 v220, v220, v220
	v_max_f32_e32 v221, v221, v221
	v_max_f32_e32 v214, 0xda24260, v214
	v_max_f32_e32 v215, 0xda24260, v215
	v_max_f32_e32 v216, 0xda24260, v216
	v_max_f32_e32 v217, 0xda24260, v217
	v_max_f32_e32 v218, 0xda24260, v218
	v_max_f32_e32 v219, 0xda24260, v219
	v_max_f32_e32 v220, 0xda24260, v220
	v_max_f32_e32 v221, 0xda24260, v221
	v_rcp_f32_e32 v214, v214
	v_rcp_f32_e32 v215, v215
	v_rcp_f32_e32 v216, v216
	v_rcp_f32_e32 v217, v217
	v_rcp_f32_e32 v218, v218
	v_rcp_f32_e32 v219, v219
	v_rcp_f32_e32 v220, v220
	v_rcp_f32_e32 v221, v221
	v_lshlrev_b32_e32 v222, 16, v198
	v_and_b32_e32 v223, 0xffff0000, v198
	v_lshlrev_b32_e32 v224, 16, v199
	v_and_b32_e32 v225, 0xffff0000, v199
	v_lshlrev_b32_e32 v226, 16, v200
	v_and_b32_e32 v227, 0xffff0000, v200
	v_lshlrev_b32_e32 v228, 16, v201
	v_and_b32_e32 v229, 0xffff0000, v201
	v_pk_mul_f32 v[214:215], v[214:215], v[222:223]
	v_pk_mul_f32 v[216:217], v[216:217], v[224:225]
	v_pk_mul_f32 v[218:219], v[218:219], v[226:227]
	v_pk_mul_f32 v[220:221], v[220:221], v[228:229]
	v_pk_mul_f32 v[108:109], v[108:109], v[214:215]
	v_pk_mul_f32 v[110:111], v[110:111], v[216:217]
	v_pk_mul_f32 v[104:105], v[104:105], v[218:219]
	v_pk_mul_f32 v[106:107], v[106:107], v[220:221]
	v_lshlrev_b32_e32 v214, 16, v166
	v_and_b32_e32 v215, 0xffff0000, v166
	v_lshlrev_b32_e32 v216, 16, v167
	v_and_b32_e32 v217, 0xffff0000, v167
	v_lshlrev_b32_e32 v218, 16, v168
	v_and_b32_e32 v219, 0xffff0000, v168
	v_lshlrev_b32_e32 v220, 16, v169
	v_and_b32_e32 v221, 0xffff0000, v169
	v_max_f32_e32 v214, v214, v214
	v_max_f32_e32 v215, v215, v215
	v_max_f32_e32 v216, v216, v216
	v_max_f32_e32 v217, v217, v217
	v_max_f32_e32 v218, v218, v218
	v_max_f32_e32 v219, v219, v219
	v_max_f32_e32 v220, v220, v220
	v_max_f32_e32 v221, v221, v221
	v_max_f32_e32 v214, 0xda24260, v214
	v_max_f32_e32 v215, 0xda24260, v215
	v_max_f32_e32 v216, 0xda24260, v216
	v_max_f32_e32 v217, 0xda24260, v217
	v_max_f32_e32 v218, 0xda24260, v218
	v_max_f32_e32 v219, 0xda24260, v219
;     __device__ __forceinline__ void operator()(f32x4 (&acc)[2][2][4][2], const pg8::Unit& u, int wr, int wc, int fr, int fq) const {
;     ...
;             for (int m = 0; m < 4; ++m) { const size_t ro = (size_t)(row0 + ai * 128 + m * 16) * DM + colt;
; #pragma unroll
;                 for (int bj = 0; bj < 2; ++bj) { const size_t o = ro + bj * 128;
;                     const u32x4 ga = *(const u32x4*)(GA + o);
;                     float a8[8] = {bflo(ga.x), bfhi(ga.x), bflo(ga.y), bfhi(ga.y), bflo(ga.z), bfhi(ga.z), bflo(ga.w), bfhi(ga.w)};
; #pragma unroll
;                     for (int e = 0; e < 8; ++e) a8[e] = fmaxf(a8[e], 1e-30f);
;                     if (u.kind == 0) { const u32x4 gl = *(const u32x4*)(GL + o);
;                         const float l8[8] = {bflo(gl.x), bfhi(gl.x), bflo(gl.y), bfhi(gl.y), bflo(gl.z), bfhi(gl.z), bflo(gl.w), bfhi(gl.w)};
; #pragma unroll
;                         for (int e = 0; e < 4; ++e) { acc[ai][bj][m][0][e] *= l8[e] * __builtin_amdgcn_rcpf(a8[e]); acc[ai][bj][m][1][e] *= l8[4 + e] * __builtin_amdgcn_rcpf(a8[4 + e]); }
	v_max_f32_e32 v220, 0xda24260, v220
	v_max_f32_e32 v221, 0xda24260, v221
	v_rcp_f32_e32 v214, v214
	v_rcp_f32_e32 v215, v215
	v_rcp_f32_e32 v216, v216
	v_rcp_f32_e32 v217, v217
	v_rcp_f32_e32 v218, v218
	v_rcp_f32_e32 v219, v219
	v_rcp_f32_e32 v220, v220
	v_rcp_f32_e32 v221, v221
	v_lshlrev_b32_e32 v222, 16, v202
	v_and_b32_e32 v223, 0xffff0000, v202
	v_lshlrev_b32_e32 v224, 16, v203
	v_and_b32_e32 v225, 0xffff0000, v203
	v_lshlrev_b32_e32 v226, 16, v204
	v_and_b32_e32 v227, 0xffff0000, v204
	v_lshlrev_b32_e32 v228, 16, v205
	v_and_b32_e32 v229, 0xffff0000, v205
	v_pk_mul_f32 v[214:215], v[214:215], v[222:223]
	v_pk_mul_f32 v[216:217], v[216:217], v[224:225]
	v_pk_mul_f32 v[218:219], v[218:219], v[226:227]
	v_pk_mul_f32 v[220:221], v[220:221], v[228:229]
	v_pk_mul_f32 v[76:77], v[76:77], v[214:215]
	v_pk_mul_f32 v[78:79], v[78:79], v[216:217]
	v_pk_mul_f32 v[72:73], v[72:73], v[218:219]
	v_pk_mul_f32 v[74:75], v[74:75], v[220:221]
	v_lshlrev_b32_e32 v214, 16, v170
	v_and_b32_e32 v215, 0xffff0000, v170
	v_lshlrev_b32_e32 v216, 16, v171
	v_and_b32_e32 v217, 0xffff0000, v171
	v_lshlrev_b32_e32 v218, 16, v172
	v_and_b32_e32 v219, 0xffff0000, v172
	v_lshlrev_b32_e32 v220, 16, v173
	v_and_b32_e32 v221, 0xffff0000, v173
	v_max_f32_e32 v214, v214, v214
	v_max_f32_e32 v215, v215, v215
	v_max_f32_e32 v216, v216, v216
	v_max_f32_e32 v217, v217, v217
	v_max_f32_e32 v218, v218, v218
	v_max_f32_e32 v219, v219, v219
	v_max_f32_e32 v220, v220, v220
	v_max_f32_e32 v221, v221, v221
	v_max_f32_e32 v214, 0xda24260, v214
	v_max_f32_e32 v215, 0xda24260, v215
	v_max_f32_e32 v216, 0xda24260, v216
	v_max_f32_e32 v217, 0xda24260, v217
	v_max_f32_e32 v218, 0xda24260, v218
	v_max_f32_e32 v219, 0xda24260, v219
	v_max_f32_e32 v220, 0xda24260, v220
	v_max_f32_e32 v221, 0xda24260, v221
	v_rcp_f32_e32 v214, v214
	v_rcp_f32_e32 v215, v215
	v_rcp_f32_e32 v216, v216
	v_rcp_f32_e32 v217, v217
	v_rcp_f32_e32 v218, v218
	v_rcp_f32_e32 v219, v219
	v_rcp_f32_e32 v220, v220
	v_rcp_f32_e32 v221, v221
	v_lshlrev_b32_e32 v222, 16, v206
	v_and_b32_e32 v223, 0xffff0000, v206
	v_lshlrev_b32_e32 v224, 16, v207
	v_and_b32_e32 v225, 0xffff0000, v207
	v_lshlrev_b32_e32 v226, 16, v208
	v_and_b32_e32 v227, 0xffff0000, v208
	v_lshlrev_b32_e32 v228, 16, v209
	v_and_b32_e32 v229, 0xffff0000, v209
	v_pk_mul_f32 v[214:215], v[214:215], v[222:223]
	v_pk_mul_f32 v[216:217], v[216:217], v[224:225]
	v_pk_mul_f32 v[218:219], v[218:219], v[226:227]
	v_pk_mul_f32 v[220:221], v[220:221], v[228:229]
	v_pk_mul_f32 v[100:101], v[100:101], v[214:215]
	v_pk_mul_f32 v[102:103], v[102:103], v[216:217]
	v_pk_mul_f32 v[96:97], v[96:97], v[218:219]
	v_pk_mul_f32 v[98:99], v[98:99], v[220:221]
	v_lshlrev_b32_e32 v214, 16, v174
	v_and_b32_e32 v215, 0xffff0000, v174
	v_lshlrev_b32_e32 v216, 16, v175
	v_and_b32_e32 v217, 0xffff0000, v175
	v_lshlrev_b32_e32 v218, 16, v176
	v_and_b32_e32 v219, 0xffff0000, v176
	v_lshlrev_b32_e32 v220, 16, v177
	v_and_b32_e32 v221, 0xffff0000, v177
	v_max_f32_e32 v214, v214, v214
	v_max_f32_e32 v215, v215, v215
	v_max_f32_e32 v216, v216, v216
	v_max_f32_e32 v217, v217, v217
	v_max_f32_e32 v218, v218, v218
	v_max_f32_e32 v219, v219, v219
	v_max_f32_e32 v220, v220, v220
	v_max_f32_e32 v221, v221, v221
	v_max_f32_e32 v214, 0xda24260, v214
	v_max_f32_e32 v215, 0xda24260, v215
	v_max_f32_e32 v216, 0xda24260, v216
	v_max_f32_e32 v217, 0xda24260, v217
	v_max_f32_e32 v218, 0xda24260, v218
	v_max_f32_e32 v219, 0xda24260, v219
	v_max_f32_e32 v220, 0xda24260, v220
	v_max_f32_e32 v221, 0xda24260, v221
	v_rcp_f32_e32 v214, v214
	v_rcp_f32_e32 v215, v215
	v_rcp_f32_e32 v216, v216
	v_rcp_f32_e32 v217, v217
	v_rcp_f32_e32 v218, v218
	v_rcp_f32_e32 v219, v219
	v_rcp_f32_e32 v220, v220
	v_rcp_f32_e32 v221, v221
	v_lshlrev_b32_e32 v222, 16, v210
	v_and_b32_e32 v223, 0xffff0000, v210
	v_lshlrev_b32_e32 v224, 16, v211
	v_and_b32_e32 v225, 0xffff0000, v211
	v_lshlrev_b32_e32 v226, 16, v212
	v_and_b32_e32 v227, 0xffff0000, v212
	v_lshlrev_b32_e32 v228, 16, v213
	v_and_b32_e32 v229, 0xffff0000, v213
	v_pk_mul_f32 v[214:215], v[214:215], v[222:223]
	v_pk_mul_f32 v[216:217], v[216:217], v[224:225]
	v_pk_mul_f32 v[218:219], v[218:219], v[226:227]
	v_pk_mul_f32 v[220:221], v[220:221], v[228:229]
	v_pk_mul_f32 v[68:69], v[68:69], v[214:215]
	v_pk_mul_f32 v[70:71], v[70:71], v[216:217]
	v_pk_mul_f32 v[64:65], v[64:65], v[218:219]
	v_pk_mul_f32 v[66:67], v[66:67], v[220:221]
	global_load_dwordx4 v[140:143], v234, s[98:99]
	global_load_dwordx4 v[178:181], v234, s[100:101] nt
	global_load_dwordx4 v[144:147], v234, s[98:99] offset:256
	global_load_dwordx4 v[186:189], v234, s[100:101] offset:256 nt
	s_add_u32 s98, s98, 0x8000
	s_addc_u32 s99, s99, 0
	s_add_u32 s100, s100, 0x8000
	s_addc_u32 s101, s101, 0
	global_load_dwordx4 v[148:151], v234, s[98:99]
	global_load_dwordx4 v[190:193], v234, s[100:101] nt
	global_load_dwordx4 v[152:155], v234, s[98:99] offset:256
	global_load_dwordx4 v[194:197], v234, s[100:101] offset:256 nt
	s_add_u32 s98, s98, 0x8000
	s_addc_u32 s99, s99, 0
	s_add_u32 s100, s100, 0x8000
	s_addc_u32 s101, s101, 0
	global_load_dwordx4 v[162:165], v234, s[98:99]
	global_load_dwordx4 v[198:201], v234, s[100:101] nt
	global_load_dwordx4 v[166:169], v234, s[98:99] offset:256
	global_load_dwordx4 v[202:205], v234, s[100:101] offset:256 nt
	s_add_u32 s98, s98, 0x8000
	s_addc_u32 s99, s99, 0
	s_add_u32 s100, s100, 0x8000
	s_addc_u32 s101, s101, 0
	global_load_dwordx4 v[170:173], v234, s[98:99]
	global_load_dwordx4 v[206:209], v234, s[100:101] nt
	global_load_dwordx4 v[174:177], v234, s[98:99] offset:256
	global_load_dwordx4 v[210:213], v234, s[100:101] offset:256 nt
	s_add_u32 s98, s98, 0x28000
	s_addc_u32 s99, s99, 0
	s_add_u32 s100, s100, 0x28000
	s_addc_u32 s101, s101, 0
	s_waitcnt vmcnt(0)
;     __device__ __forceinline__ void operator()(f32x4 (&acc)[2][2][4][2], const pg8::Unit& u, int wr, int wc, int fr, int fq) const {
;     ...
;                     if (u.kind == 0) { const u32x4 gl = *(const u32x4*)(GL + o);
;                         const float l8[8] = {bflo(gl.x), bfhi(gl.x), bflo(gl.y), bfhi(gl.y), bflo(gl.z), bfhi(gl.z), bflo(gl.w), bfhi(gl.w)};
; #pragma unroll
;                         for (int e = 0; e < 4; ++e) { acc[ai][bj][m][0][e] *= l8[e] * __builtin_amdgcn_rcpf(a8[e]); acc[ai][bj][m][1][e] *= l8[4 + e] * __builtin_amdgcn_rcpf(a8[4 + e]); }
	v_lshlrev_b32_e32 v214, 16, v140
	v_and_b32_e32 v215, 0xffff0000, v140
	v_lshlrev_b32_e32 v216, 16, v141
	v_and_b32_e32 v217, 0xffff0000, v141
	v_lshlrev_b32_e32 v218, 16, v142
	v_and_b32_e32 v219, 0xffff0000, v142
	v_lshlrev_b32_e32 v220, 16, v143
	v_and_b32_e32 v221, 0xffff0000, v143
	v_max_f32_e32 v214, v214, v214
	v_max_f32_e32 v215, v215, v215
	v_max_f32_e32 v216, v216, v216
	v_max_f32_e32 v217, v217, v217
	v_max_f32_e32 v218, v218, v218
	v_max_f32_e32 v219, v219, v219
	v_max_f32_e32 v220, v220, v220
	v_max_f32_e32 v221, v221, v221
	v_max_f32_e32 v214, 0xda24260, v214
	v_max_f32_e32 v215, 0xda24260, v215
	v_max_f32_e32 v216, 0xda24260, v216
	v_max_f32_e32 v217, 0xda24260, v217
	v_max_f32_e32 v218, 0xda24260, v218
	v_max_f32_e32 v219, 0xda24260, v219
	v_max_f32_e32 v220, 0xda24260, v220
	v_max_f32_e32 v221, 0xda24260, v221
	v_rcp_f32_e32 v214, v214
	v_rcp_f32_e32 v215, v215
	v_rcp_f32_e32 v216, v216
	v_rcp_f32_e32 v217, v217
	v_rcp_f32_e32 v218, v218
	v_rcp_f32_e32 v219, v219
	v_rcp_f32_e32 v220, v220
	v_rcp_f32_e32 v221, v221
	v_lshlrev_b32_e32 v222, 16, v178
	v_and_b32_e32 v223, 0xffff0000, v178
	v_lshlrev_b32_e32 v224, 16, v179
	v_and_b32_e32 v225, 0xffff0000, v179
	v_lshlrev_b32_e32 v226, 16, v180
	v_and_b32_e32 v227, 0xffff0000, v180
	v_lshlrev_b32_e32 v228, 16, v181
	v_and_b32_e32 v229, 0xffff0000, v181
	v_pk_mul_f32 v[214:215], v[214:215], v[222:223]
	v_pk_mul_f32 v[216:217], v[216:217], v[224:225]
	v_pk_mul_f32 v[218:219], v[218:219], v[226:227]
	v_pk_mul_f32 v[220:221], v[220:221], v[228:229]
	v_pk_mul_f32 v[60:61], v[60:61], v[214:215]
	v_pk_mul_f32 v[62:63], v[62:63], v[216:217]
	v_pk_mul_f32 v[56:57], v[56:57], v[218:219]
	v_pk_mul_f32 v[58:59], v[58:59], v[220:221]
	v_lshlrev_b32_e32 v214, 16, v144
	v_and_b32_e32 v215, 0xffff0000, v144
	v_lshlrev_b32_e32 v216, 16, v145
	v_and_b32_e32 v217, 0xffff0000, v145
	v_lshlrev_b32_e32 v218, 16, v146
	v_and_b32_e32 v219, 0xffff0000, v146
	v_lshlrev_b32_e32 v220, 16, v147
	v_and_b32_e32 v221, 0xffff0000, v147
	v_max_f32_e32 v214, v214, v214
	v_max_f32_e32 v215, v215, v215
	v_max_f32_e32 v216, v216, v216
	v_max_f32_e32 v217, v217, v217
	v_max_f32_e32 v218, v218, v218
	v_max_f32_e32 v219, v219, v219
	v_max_f32_e32 v220, v220, v220
	v_max_f32_e32 v221, v221, v221
	v_max_f32_e32 v214, 0xda24260, v214
	v_max_f32_e32 v215, 0xda24260, v215
	v_max_f32_e32 v216, 0xda24260, v216
	v_max_f32_e32 v217, 0xda24260, v217
	v_max_f32_e32 v218, 0xda24260, v218
	v_max_f32_e32 v219, 0xda24260, v219
	v_max_f32_e32 v220, 0xda24260, v220
	v_max_f32_e32 v221, 0xda24260, v221
	v_rcp_f32_e32 v214, v214
	v_rcp_f32_e32 v215, v215
	v_rcp_f32_e32 v216, v216
	v_rcp_f32_e32 v217, v217
	v_rcp_f32_e32 v218, v218
	v_rcp_f32_e32 v219, v219
	v_rcp_f32_e32 v220, v220
	v_rcp_f32_e32 v221, v221
	v_lshlrev_b32_e32 v222, 16, v186
	v_and_b32_e32 v223, 0xffff0000, v186
	v_lshlrev_b32_e32 v224, 16, v187
	v_and_b32_e32 v225, 0xffff0000, v187
	v_lshlrev_b32_e32 v226, 16, v188
	v_and_b32_e32 v227, 0xffff0000, v188
	v_lshlrev_b32_e32 v228, 16, v189
	v_and_b32_e32 v229, 0xffff0000, v189
	v_pk_mul_f32 v[214:215], v[214:215], v[222:223]
	v_pk_mul_f32 v[216:217], v[216:217], v[224:225]
	v_pk_mul_f32 v[218:219], v[218:219], v[226:227]
	v_pk_mul_f32 v[220:221], v[220:221], v[228:229]
	v_pk_mul_f32 v[28:29], v[28:29], v[214:215]
	v_pk_mul_f32 v[30:31], v[30:31], v[216:217]
	v_pk_mul_f32 v[24:25], v[24:25], v[218:219]
	v_pk_mul_f32 v[26:27], v[26:27], v[220:221]
	v_lshlrev_b32_e32 v214, 16, v148
	v_and_b32_e32 v215, 0xffff0000, v148
	v_lshlrev_b32_e32 v216, 16, v149
	v_and_b32_e32 v217, 0xffff0000, v149
	v_lshlrev_b32_e32 v218, 16, v150
	v_and_b32_e32 v219, 0xffff0000, v150
	v_lshlrev_b32_e32 v220, 16, v151
	v_and_b32_e32 v221, 0xffff0000, v151
	v_max_f32_e32 v214, v214, v214
	v_max_f32_e32 v215, v215, v215
	v_max_f32_e32 v216, v216, v216
	v_max_f32_e32 v217, v217, v217
	v_max_f32_e32 v218, v218, v218
	v_max_f32_e32 v219, v219, v219
	v_max_f32_e32 v220, v220, v220
	v_max_f32_e32 v221, v221, v221
	v_max_f32_e32 v214, 0xda24260, v214
	v_max_f32_e32 v215, 0xda24260, v215
	v_max_f32_e32 v216, 0xda24260, v216
	v_max_f32_e32 v217, 0xda24260, v217
	v_max_f32_e32 v218, 0xda24260, v218
	v_max_f32_e32 v219, 0xda24260, v219
	v_max_f32_e32 v220, 0xda24260, v220
	v_max_f32_e32 v221, 0xda24260, v221
	v_rcp_f32_e32 v214, v214
	v_rcp_f32_e32 v215, v215
	v_rcp_f32_e32 v216, v216
	v_rcp_f32_e32 v217, v217
	v_rcp_f32_e32 v218, v218
	v_rcp_f32_e32 v219, v219
	v_rcp_f32_e32 v220, v220
	v_rcp_f32_e32 v221, v221
	v_lshlrev_b32_e32 v222, 16, v190
	v_and_b32_e32 v223, 0xffff0000, v190
	v_lshlrev_b32_e32 v224, 16, v191
	v_and_b32_e32 v225, 0xffff0000, v191
	v_lshlrev_b32_e32 v226, 16, v192
	v_and_b32_e32 v227, 0xffff0000, v192
	v_lshlrev_b32_e32 v228, 16, v193
	v_and_b32_e32 v229, 0xffff0000, v193
	v_pk_mul_f32 v[214:215], v[214:215], v[222:223]
	v_pk_mul_f32 v[216:217], v[216:217], v[224:225]
	v_pk_mul_f32 v[218:219], v[218:219], v[226:227]
	v_pk_mul_f32 v[220:221], v[220:221], v[228:229]
	v_pk_mul_f32 v[52:53], v[52:53], v[214:215]
	v_pk_mul_f32 v[54:55], v[54:55], v[216:217]
	v_pk_mul_f32 v[48:49], v[48:49], v[218:219]
	v_pk_mul_f32 v[50:51], v[50:51], v[220:221]
	v_lshlrev_b32_e32 v214, 16, v152
	v_and_b32_e32 v215, 0xffff0000, v152
	v_lshlrev_b32_e32 v216, 16, v153
	v_and_b32_e32 v217, 0xffff0000, v153
	v_lshlrev_b32_e32 v218, 16, v154
	v_and_b32_e32 v219, 0xffff0000, v154
	v_lshlrev_b32_e32 v220, 16, v155
	v_and_b32_e32 v221, 0xffff0000, v155
	v_max_f32_e32 v214, v214, v214
	v_max_f32_e32 v215, v215, v215
	v_max_f32_e32 v216, v216, v216
	v_max_f32_e32 v217, v217, v217
	v_max_f32_e32 v218, v218, v218
	v_max_f32_e32 v219, v219, v219
	v_max_f32_e32 v220, v220, v220
;     __device__ __forceinline__ void operator()(f32x4 (&acc)[2][2][4][2], const pg8::Unit& u, int wr, int wc, int fr, int fq) const {
;     ...
;                     if (u.kind == 0) { const u32x4 gl = *(const u32x4*)(GL + o);
;                         const float l8[8] = {bflo(gl.x), bfhi(gl.x), bflo(gl.y), bfhi(gl.y), bflo(gl.z), bfhi(gl.z), bflo(gl.w), bfhi(gl.w)};
; #pragma unroll
;                         for (int e = 0; e < 4; ++e) { acc[ai][bj][m][0][e] *= l8[e] * __builtin_amdgcn_rcpf(a8[e]); acc[ai][bj][m][1][e] *= l8[4 + e] * __builtin_amdgcn_rcpf(a8[4 + e]); }
	v_max_f32_e32 v221, v221, v221
	v_max_f32_e32 v214, 0xda24260, v214
	v_max_f32_e32 v215, 0xda24260, v215
	v_max_f32_e32 v216, 0xda24260, v216
	v_max_f32_e32 v217, 0xda24260, v217
	v_max_f32_e32 v218, 0xda24260, v218
	v_max_f32_e32 v219, 0xda24260, v219
	v_max_f32_e32 v220, 0xda24260, v220
	v_max_f32_e32 v221, 0xda24260, v221
	v_rcp_f32_e32 v214, v214
	v_rcp_f32_e32 v215, v215
	v_rcp_f32_e32 v216, v216
	v_rcp_f32_e32 v217, v217
	v_rcp_f32_e32 v218, v218
	v_rcp_f32_e32 v219, v219
	v_rcp_f32_e32 v220, v220
	v_rcp_f32_e32 v221, v221
	v_lshlrev_b32_e32 v222, 16, v194
	v_and_b32_e32 v223, 0xffff0000, v194
	v_lshlrev_b32_e32 v224, 16, v195
	v_and_b32_e32 v225, 0xffff0000, v195
	v_lshlrev_b32_e32 v226, 16, v196
	v_and_b32_e32 v227, 0xffff0000, v196
	v_lshlrev_b32_e32 v228, 16, v197
	v_and_b32_e32 v229, 0xffff0000, v197
	v_pk_mul_f32 v[214:215], v[214:215], v[222:223]
	v_pk_mul_f32 v[216:217], v[216:217], v[224:225]
	v_pk_mul_f32 v[218:219], v[218:219], v[226:227]
	v_pk_mul_f32 v[220:221], v[220:221], v[228:229]
	v_pk_mul_f32 v[20:21], v[20:21], v[214:215]
	v_pk_mul_f32 v[22:23], v[22:23], v[216:217]
	v_pk_mul_f32 v[16:17], v[16:17], v[218:219]
	v_pk_mul_f32 v[18:19], v[18:19], v[220:221]
	v_lshlrev_b32_e32 v214, 16, v162
	v_and_b32_e32 v215, 0xffff0000, v162
	v_lshlrev_b32_e32 v216, 16, v163
	v_and_b32_e32 v217, 0xffff0000, v163
	v_lshlrev_b32_e32 v218, 16, v164
	v_and_b32_e32 v219, 0xffff0000, v164
	v_lshlrev_b32_e32 v220, 16, v165
	v_and_b32_e32 v221, 0xffff0000, v165
	v_max_f32_e32 v214, v214, v214
	v_max_f32_e32 v215, v215, v215
	v_max_f32_e32 v216, v216, v216
	v_max_f32_e32 v217, v217, v217
	v_max_f32_e32 v218, v218, v218
	v_max_f32_e32 v219, v219, v219
	v_max_f32_e32 v220, v220, v220
	v_max_f32_e32 v221, v221, v221
	v_max_f32_e32 v214, 0xda24260, v214
	v_max_f32_e32 v215, 0xda24260, v215
	v_max_f32_e32 v216, 0xda24260, v216
	v_max_f32_e32 v217, 0xda24260, v217
	v_max_f32_e32 v218, 0xda24260, v218
	v_max_f32_e32 v219, 0xda24260, v219
	v_max_f32_e32 v220, 0xda24260, v220
	v_max_f32_e32 v221, 0xda24260, v221
	v_rcp_f32_e32 v214, v214
	v_rcp_f32_e32 v215, v215
	v_rcp_f32_e32 v216, v216
	v_rcp_f32_e32 v217, v217
	v_rcp_f32_e32 v218, v218
	v_rcp_f32_e32 v219, v219
	v_rcp_f32_e32 v220, v220
	v_rcp_f32_e32 v221, v221
	v_lshlrev_b32_e32 v222, 16, v198
	v_and_b32_e32 v223, 0xffff0000, v198
	v_lshlrev_b32_e32 v224, 16, v199
	v_and_b32_e32 v225, 0xffff0000, v199
	v_lshlrev_b32_e32 v226, 16, v200
	v_and_b32_e32 v227, 0xffff0000, v200
	v_lshlrev_b32_e32 v228, 16, v201
	v_and_b32_e32 v229, 0xffff0000, v201
	v_pk_mul_f32 v[214:215], v[214:215], v[222:223]
	v_pk_mul_f32 v[216:217], v[216:217], v[224:225]
	v_pk_mul_f32 v[218:219], v[218:219], v[226:227]
	v_pk_mul_f32 v[220:221], v[220:221], v[228:229]
	v_pk_mul_f32 v[44:45], v[44:45], v[214:215]
	v_pk_mul_f32 v[46:47], v[46:47], v[216:217]
	v_pk_mul_f32 v[40:41], v[40:41], v[218:219]
	v_pk_mul_f32 v[42:43], v[42:43], v[220:221]
	v_lshlrev_b32_e32 v214, 16, v166
	v_and_b32_e32 v215, 0xffff0000, v166
	v_lshlrev_b32_e32 v216, 16, v167
	v_and_b32_e32 v217, 0xffff0000, v167
	v_lshlrev_b32_e32 v218, 16, v168
	v_and_b32_e32 v219, 0xffff0000, v168
	v_lshlrev_b32_e32 v220, 16, v169
	v_and_b32_e32 v221, 0xffff0000, v169
	v_max_f32_e32 v214, v214, v214
	v_max_f32_e32 v215, v215, v215
	v_max_f32_e32 v216, v216, v216
	v_max_f32_e32 v217, v217, v217
	v_max_f32_e32 v218, v218, v218
	v_max_f32_e32 v219, v219, v219
	v_max_f32_e32 v220, v220, v220
	v_max_f32_e32 v221, v221, v221
	v_max_f32_e32 v214, 0xda24260, v214
	v_max_f32_e32 v215, 0xda24260, v215
	v_max_f32_e32 v216, 0xda24260, v216
	v_max_f32_e32 v217, 0xda24260, v217
	v_max_f32_e32 v218, 0xda24260, v218
	v_max_f32_e32 v219, 0xda24260, v219
	v_max_f32_e32 v220, 0xda24260, v220
	v_max_f32_e32 v221, 0xda24260, v221
	v_rcp_f32_e32 v214, v214
	v_rcp_f32_e32 v215, v215
	v_rcp_f32_e32 v216, v216
	v_rcp_f32_e32 v217, v217
	v_rcp_f32_e32 v218, v218
	v_rcp_f32_e32 v219, v219
	v_rcp_f32_e32 v220, v220
	v_rcp_f32_e32 v221, v221
	v_lshlrev_b32_e32 v222, 16, v202
	v_and_b32_e32 v223, 0xffff0000, v202
	v_lshlrev_b32_e32 v224, 16, v203
	v_and_b32_e32 v225, 0xffff0000, v203
	v_lshlrev_b32_e32 v226, 16, v204
	v_and_b32_e32 v227, 0xffff0000, v204
	v_lshlrev_b32_e32 v228, 16, v205
	v_and_b32_e32 v229, 0xffff0000, v205
	v_pk_mul_f32 v[214:215], v[214:215], v[222:223]
	v_pk_mul_f32 v[216:217], v[216:217], v[224:225]
	v_pk_mul_f32 v[218:219], v[218:219], v[226:227]
	v_pk_mul_f32 v[220:221], v[220:221], v[228:229]
	v_pk_mul_f32 v[12:13], v[12:13], v[214:215]
	v_pk_mul_f32 v[14:15], v[14:15], v[216:217]
	v_pk_mul_f32 v[8:9], v[8:9], v[218:219]
	v_pk_mul_f32 v[10:11], v[10:11], v[220:221]
	v_lshlrev_b32_e32 v214, 16, v170
	v_and_b32_e32 v215, 0xffff0000, v170
	v_lshlrev_b32_e32 v216, 16, v171
	v_and_b32_e32 v217, 0xffff0000, v171
	v_lshlrev_b32_e32 v218, 16, v172
	v_and_b32_e32 v219, 0xffff0000, v172
	v_lshlrev_b32_e32 v220, 16, v173
	v_and_b32_e32 v221, 0xffff0000, v173
	v_max_f32_e32 v214, v214, v214
	v_max_f32_e32 v215, v215, v215
	v_max_f32_e32 v216, v216, v216
	v_max_f32_e32 v217, v217, v217
	v_max_f32_e32 v218, v218, v218
	v_max_f32_e32 v219, v219, v219
	v_max_f32_e32 v220, v220, v220
	v_max_f32_e32 v221, v221, v221
	v_max_f32_e32 v214, 0xda24260, v214
	v_max_f32_e32 v215, 0xda24260, v215
	v_max_f32_e32 v216, 0xda24260, v216
	v_max_f32_e32 v217, 0xda24260, v217
	v_max_f32_e32 v218, 0xda24260, v218
	v_max_f32_e32 v219, 0xda24260, v219
	v_max_f32_e32 v220, 0xda24260, v220
	v_max_f32_e32 v221, 0xda24260, v221
	v_rcp_f32_e32 v214, v214
	v_rcp_f32_e32 v215, v215
	v_rcp_f32_e32 v216, v216
	v_rcp_f32_e32 v217, v217
	v_rcp_f32_e32 v218, v218
	v_rcp_f32_e32 v219, v219
	v_rcp_f32_e32 v220, v220
; __device__ __forceinline__ u32x4 pack8(f32x4 a, f32x4 b) { u32x4 w; w.x = cvt_pk(a[0], a[1]); w.y = cvt_pk(a[2], a[3]); w.z = cvt_pk(b[0], b[1]); w.w = cvt_pk(b[2], b[3]); return w; }
;     __device__ __forceinline__ void operator()(f32x4 (&acc)[2][2][4][2], const pg8::Unit& u, int wr, int wc, int fr, int fq) const {
;     ...
;                     const u32x4 ga = *(const u32x4*)(GA + o);
;                     float a8[8] = {bflo(ga.x), bfhi(ga.x), bflo(ga.y), bfhi(ga.y), bflo(ga.z), bfhi(ga.z), bflo(ga.w), bfhi(ga.w)};
; #pragma unroll
;                     for (int e = 0; e < 8; ++e) a8[e] = fmaxf(a8[e], 1e-30f);
;                     if (u.kind == 0) { const u32x4 gl = *(const u32x4*)(GL + o);
;                         const float l8[8] = {bflo(gl.x), bfhi(gl.x), bflo(gl.y), bfhi(gl.y), bflo(gl.z), bfhi(gl.z), bflo(gl.w), bfhi(gl.w)};
; #pragma unroll
;                         for (int e = 0; e < 4; ++e) { acc[ai][bj][m][0][e] *= l8[e] * __builtin_amdgcn_rcpf(a8[e]); acc[ai][bj][m][1][e] *= l8[4 + e] * __builtin_amdgcn_rcpf(a8[4 + e]); }
;                     } else { f32x4 v0 = acc[ai][bj][m][0], v1 = acc[ai][bj][m][1];
; #pragma unroll
;                         for (int e = 0; e < 4; ++e) { v0[e] *= a8[e]; v1[e] *= a8[4 + e]; }
;                         *(u32x4*)(MG + o) = pack8(v0, v1); } } }
	v_rcp_f32_e32 v221, v221
	v_lshlrev_b32_e32 v222, 16, v206
	v_and_b32_e32 v223, 0xffff0000, v206
	v_lshlrev_b32_e32 v224, 16, v207
	v_and_b32_e32 v225, 0xffff0000, v207
	v_lshlrev_b32_e32 v226, 16, v208
	v_and_b32_e32 v227, 0xffff0000, v208
	v_lshlrev_b32_e32 v228, 16, v209
	v_and_b32_e32 v229, 0xffff0000, v209
	v_pk_mul_f32 v[214:215], v[214:215], v[222:223]
	v_pk_mul_f32 v[216:217], v[216:217], v[224:225]
	v_pk_mul_f32 v[218:219], v[218:219], v[226:227]
	v_pk_mul_f32 v[220:221], v[220:221], v[228:229]
	v_pk_mul_f32 v[36:37], v[36:37], v[214:215]
	v_pk_mul_f32 v[38:39], v[38:39], v[216:217]
	v_pk_mul_f32 v[32:33], v[32:33], v[218:219]
	v_pk_mul_f32 v[34:35], v[34:35], v[220:221]
	v_lshlrev_b32_e32 v214, 16, v174
	v_and_b32_e32 v215, 0xffff0000, v174
	v_lshlrev_b32_e32 v216, 16, v175
	v_and_b32_e32 v217, 0xffff0000, v175
	v_lshlrev_b32_e32 v218, 16, v176
	v_and_b32_e32 v219, 0xffff0000, v176
	v_lshlrev_b32_e32 v220, 16, v177
	v_and_b32_e32 v221, 0xffff0000, v177
	v_max_f32_e32 v214, v214, v214
	v_max_f32_e32 v215, v215, v215
	v_max_f32_e32 v216, v216, v216
	v_max_f32_e32 v217, v217, v217
	v_max_f32_e32 v218, v218, v218
	v_max_f32_e32 v219, v219, v219
	v_max_f32_e32 v220, v220, v220
	v_max_f32_e32 v221, v221, v221
	v_max_f32_e32 v214, 0xda24260, v214
	v_max_f32_e32 v215, 0xda24260, v215
	v_max_f32_e32 v216, 0xda24260, v216
	v_max_f32_e32 v217, 0xda24260, v217
	v_max_f32_e32 v218, 0xda24260, v218
	v_max_f32_e32 v219, 0xda24260, v219
	v_max_f32_e32 v220, 0xda24260, v220
	v_max_f32_e32 v221, 0xda24260, v221
	v_rcp_f32_e32 v214, v214
	v_rcp_f32_e32 v215, v215
	v_rcp_f32_e32 v216, v216
	v_rcp_f32_e32 v217, v217
	v_rcp_f32_e32 v218, v218
	v_rcp_f32_e32 v219, v219
	v_rcp_f32_e32 v220, v220
	v_rcp_f32_e32 v221, v221
	v_lshlrev_b32_e32 v222, 16, v210
	v_and_b32_e32 v223, 0xffff0000, v210
	v_lshlrev_b32_e32 v224, 16, v211
	v_and_b32_e32 v225, 0xffff0000, v211
	v_lshlrev_b32_e32 v226, 16, v212
	v_and_b32_e32 v227, 0xffff0000, v212
	v_lshlrev_b32_e32 v228, 16, v213
	v_and_b32_e32 v229, 0xffff0000, v213
	v_pk_mul_f32 v[214:215], v[214:215], v[222:223]
	v_pk_mul_f32 v[216:217], v[216:217], v[224:225]
	v_pk_mul_f32 v[218:219], v[218:219], v[226:227]
	v_pk_mul_f32 v[220:221], v[220:221], v[228:229]
	v_pk_mul_f32 v[4:5], v[4:5], v[214:215]
	v_pk_mul_f32 v[6:7], v[6:7], v[216:217]
	v_pk_mul_f32 v[0:1], v[0:1], v[218:219]
	v_pk_mul_f32 v[2:3], v[2:3], v[220:221]
	s_mov_b64 s[4:5], -1
	s_branch .Lbr_done
.Lbr_kind1:
	s_mov_b64 s[100:101], s[88:89]
	global_load_dwordx4 v[140:143], v234, s[98:99] nt
	global_load_dwordx4 v[144:147], v234, s[98:99] offset:256 nt
	s_add_u32 s98, s98, 0x8000
	s_addc_u32 s99, s99, 0
	global_load_dwordx4 v[148:151], v234, s[98:99] nt
	global_load_dwordx4 v[152:155], v234, s[98:99] offset:256 nt
	s_add_u32 s98, s98, 0x8000
	s_addc_u32 s99, s99, 0
	global_load_dwordx4 v[162:165], v234, s[98:99] nt
	global_load_dwordx4 v[166:169], v234, s[98:99] offset:256 nt
	s_add_u32 s98, s98, 0x8000
	s_addc_u32 s99, s99, 0
	global_load_dwordx4 v[170:173], v234, s[98:99] nt
	global_load_dwordx4 v[174:177], v234, s[98:99] offset:256 nt
	s_add_u32 s98, s98, 0x28000
	s_addc_u32 s99, s99, 0
	global_load_dwordx4 v[178:181], v234, s[98:99] nt
	global_load_dwordx4 v[186:189], v234, s[98:99] offset:256 nt
	s_add_u32 s98, s98, 0x8000
	s_addc_u32 s99, s99, 0
	global_load_dwordx4 v[190:193], v234, s[98:99] nt
	global_load_dwordx4 v[194:197], v234, s[98:99] offset:256 nt
	s_add_u32 s98, s98, 0x8000
	s_addc_u32 s99, s99, 0
	global_load_dwordx4 v[198:201], v234, s[98:99] nt
	global_load_dwordx4 v[202:205], v234, s[98:99] offset:256 nt
	s_add_u32 s98, s98, 0x8000
	s_addc_u32 s99, s99, 0
	global_load_dwordx4 v[206:209], v234, s[98:99] nt
	global_load_dwordx4 v[210:213], v234, s[98:99] offset:256 nt
	s_add_u32 s98, s98, 0x28000
	s_addc_u32 s99, s99, 0
	s_waitcnt vmcnt(0)
	v_lshlrev_b32_e32 v214, 16, v140
	v_and_b32_e32 v215, 0xffff0000, v140
	v_lshlrev_b32_e32 v216, 16, v141
	v_and_b32_e32 v217, 0xffff0000, v141
	v_lshlrev_b32_e32 v218, 16, v142
	v_and_b32_e32 v219, 0xffff0000, v142
	v_lshlrev_b32_e32 v220, 16, v143
	v_and_b32_e32 v221, 0xffff0000, v143
	v_max_f32_e32 v214, v214, v214
	v_max_f32_e32 v215, v215, v215
	v_max_f32_e32 v216, v216, v216
	v_max_f32_e32 v217, v217, v217
	v_max_f32_e32 v218, v218, v218
	v_max_f32_e32 v219, v219, v219
	v_max_f32_e32 v220, v220, v220
	v_max_f32_e32 v221, v221, v221
	v_max_f32_e32 v214, 0xda24260, v214
	v_max_f32_e32 v215, 0xda24260, v215
	v_max_f32_e32 v216, 0xda24260, v216
	v_max_f32_e32 v217, 0xda24260, v217
	v_max_f32_e32 v218, 0xda24260, v218
	v_max_f32_e32 v219, 0xda24260, v219
	v_max_f32_e32 v220, 0xda24260, v220
	v_max_f32_e32 v221, 0xda24260, v221
	v_pk_mul_f32 v[222:223], v[124:125], v[214:215]
	v_pk_mul_f32 v[224:225], v[126:127], v[216:217]
	v_pk_mul_f32 v[226:227], v[120:121], v[218:219]
	v_pk_mul_f32 v[228:229], v[122:123], v[220:221]
	v_cvt_pk_bf16_f32 v230, v222, v223
	v_cvt_pk_bf16_f32 v231, v224, v225
	v_cvt_pk_bf16_f32 v232, v226, v227
	v_cvt_pk_bf16_f32 v233, v228, v229
	global_store_dwordx4 v234, v[230:233], s[100:101]
	v_lshlrev_b32_e32 v214, 16, v144
	v_and_b32_e32 v215, 0xffff0000, v144
	v_lshlrev_b32_e32 v216, 16, v145
	v_and_b32_e32 v217, 0xffff0000, v145
	v_lshlrev_b32_e32 v218, 16, v146
	v_and_b32_e32 v219, 0xffff0000, v146
	v_lshlrev_b32_e32 v220, 16, v147
	v_and_b32_e32 v221, 0xffff0000, v147
	v_max_f32_e32 v214, v214, v214
	v_max_f32_e32 v215, v215, v215
	v_max_f32_e32 v216, v216, v216
	v_max_f32_e32 v217, v217, v217
	v_max_f32_e32 v218, v218, v218
	v_max_f32_e32 v219, v219, v219
	v_max_f32_e32 v220, v220, v220
	v_max_f32_e32 v221, v221, v221
	v_max_f32_e32 v214, 0xda24260, v214
; __device__ __forceinline__ u32x4 pack8(f32x4 a, f32x4 b) { u32x4 w; w.x = cvt_pk(a[0], a[1]); w.y = cvt_pk(a[2], a[3]); w.z = cvt_pk(b[0], b[1]); w.w = cvt_pk(b[2], b[3]); return w; }
;     __device__ __forceinline__ void operator()(f32x4 (&acc)[2][2][4][2], const pg8::Unit& u, int wr, int wc, int fr, int fq) const {
;     ...
;                     float a8[8] = {bflo(ga.x), bfhi(ga.x), bflo(ga.y), bfhi(ga.y), bflo(ga.z), bfhi(ga.z), bflo(ga.w), bfhi(ga.w)};
; #pragma unroll
;                     for (int e = 0; e < 8; ++e) a8[e] = fmaxf(a8[e], 1e-30f);
;                     if (u.kind == 0) { const u32x4 gl = *(const u32x4*)(GL + o);
;                         const float l8[8] = {bflo(gl.x), bfhi(gl.x), bflo(gl.y), bfhi(gl.y), bflo(gl.z), bfhi(gl.z), bflo(gl.w), bfhi(gl.w)};
; #pragma unroll
;                         for (int e = 0; e < 4; ++e) { acc[ai][bj][m][0][e] *= l8[e] * __builtin_amdgcn_rcpf(a8[e]); acc[ai][bj][m][1][e] *= l8[4 + e] * __builtin_amdgcn_rcpf(a8[4 + e]); }
;                     } else { f32x4 v0 = acc[ai][bj][m][0], v1 = acc[ai][bj][m][1];
; #pragma unroll
;                         for (int e = 0; e < 4; ++e) { v0[e] *= a8[e]; v1[e] *= a8[4 + e]; }
;                         *(u32x4*)(MG + o) = pack8(v0, v1); } } }
	v_max_f32_e32 v215, 0xda24260, v215
	v_max_f32_e32 v216, 0xda24260, v216
	v_max_f32_e32 v217, 0xda24260, v217
	v_max_f32_e32 v218, 0xda24260, v218
	v_max_f32_e32 v219, 0xda24260, v219
	v_max_f32_e32 v220, 0xda24260, v220
	v_max_f32_e32 v221, 0xda24260, v221
	v_pk_mul_f32 v[222:223], v[92:93], v[214:215]
	v_pk_mul_f32 v[224:225], v[94:95], v[216:217]
	v_pk_mul_f32 v[226:227], v[88:89], v[218:219]
	v_pk_mul_f32 v[228:229], v[90:91], v[220:221]
	v_cvt_pk_bf16_f32 v230, v222, v223
	v_cvt_pk_bf16_f32 v231, v224, v225
	v_cvt_pk_bf16_f32 v232, v226, v227
	v_cvt_pk_bf16_f32 v233, v228, v229
	global_store_dwordx4 v234, v[230:233], s[100:101] offset:256
	s_add_u32 s100, s100, 0x8000
	s_addc_u32 s101, s101, 0
	v_lshlrev_b32_e32 v214, 16, v148
	v_and_b32_e32 v215, 0xffff0000, v148
	v_lshlrev_b32_e32 v216, 16, v149
	v_and_b32_e32 v217, 0xffff0000, v149
	v_lshlrev_b32_e32 v218, 16, v150
	v_and_b32_e32 v219, 0xffff0000, v150
	v_lshlrev_b32_e32 v220, 16, v151
	v_and_b32_e32 v221, 0xffff0000, v151
	v_max_f32_e32 v214, v214, v214
	v_max_f32_e32 v215, v215, v215
	v_max_f32_e32 v216, v216, v216
	v_max_f32_e32 v217, v217, v217
	v_max_f32_e32 v218, v218, v218
	v_max_f32_e32 v219, v219, v219
	v_max_f32_e32 v220, v220, v220
	v_max_f32_e32 v221, v221, v221
	v_max_f32_e32 v214, 0xda24260, v214
	v_max_f32_e32 v215, 0xda24260, v215
	v_max_f32_e32 v216, 0xda24260, v216
	v_max_f32_e32 v217, 0xda24260, v217
	v_max_f32_e32 v218, 0xda24260, v218
	v_max_f32_e32 v219, 0xda24260, v219
	v_max_f32_e32 v220, 0xda24260, v220
	v_max_f32_e32 v221, 0xda24260, v221
	v_pk_mul_f32 v[222:223], v[116:117], v[214:215]
	v_pk_mul_f32 v[224:225], v[118:119], v[216:217]
	v_pk_mul_f32 v[226:227], v[112:113], v[218:219]
	v_pk_mul_f32 v[228:229], v[114:115], v[220:221]
	v_cvt_pk_bf16_f32 v230, v222, v223
	v_cvt_pk_bf16_f32 v231, v224, v225
	v_cvt_pk_bf16_f32 v232, v226, v227
	v_cvt_pk_bf16_f32 v233, v228, v229
	global_store_dwordx4 v234, v[230:233], s[100:101]
	v_lshlrev_b32_e32 v214, 16, v152
	v_and_b32_e32 v215, 0xffff0000, v152
	v_lshlrev_b32_e32 v216, 16, v153
	v_and_b32_e32 v217, 0xffff0000, v153
	v_lshlrev_b32_e32 v218, 16, v154
	v_and_b32_e32 v219, 0xffff0000, v154
	v_lshlrev_b32_e32 v220, 16, v155
	v_and_b32_e32 v221, 0xffff0000, v155
	v_max_f32_e32 v214, v214, v214
	v_max_f32_e32 v215, v215, v215
	v_max_f32_e32 v216, v216, v216
	v_max_f32_e32 v217, v217, v217
	v_max_f32_e32 v218, v218, v218
	v_max_f32_e32 v219, v219, v219
	v_max_f32_e32 v220, v220, v220
	v_max_f32_e32 v221, v221, v221
	v_max_f32_e32 v214, 0xda24260, v214
	v_max_f32_e32 v215, 0xda24260, v215
	v_max_f32_e32 v216, 0xda24260, v216
	v_max_f32_e32 v217, 0xda24260, v217
	v_max_f32_e32 v218, 0xda24260, v218
	v_max_f32_e32 v219, 0xda24260, v219
	v_max_f32_e32 v220, 0xda24260, v220
	v_max_f32_e32 v221, 0xda24260, v221
	v_pk_mul_f32 v[222:223], v[84:85], v[214:215]
	v_pk_mul_f32 v[224:225], v[86:87], v[216:217]
	v_pk_mul_f32 v[226:227], v[80:81], v[218:219]
	v_pk_mul_f32 v[228:229], v[82:83], v[220:221]
	v_cvt_pk_bf16_f32 v230, v222, v223
	v_cvt_pk_bf16_f32 v231, v224, v225
	v_cvt_pk_bf16_f32 v232, v226, v227
	v_cvt_pk_bf16_f32 v233, v228, v229
	global_store_dwordx4 v234, v[230:233], s[100:101] offset:256
	s_add_u32 s100, s100, 0x8000
	s_addc_u32 s101, s101, 0
	v_lshlrev_b32_e32 v214, 16, v162
	v_and_b32_e32 v215, 0xffff0000, v162
	v_lshlrev_b32_e32 v216, 16, v163
	v_and_b32_e32 v217, 0xffff0000, v163
	v_lshlrev_b32_e32 v218, 16, v164
	v_and_b32_e32 v219, 0xffff0000, v164
	v_lshlrev_b32_e32 v220, 16, v165
	v_and_b32_e32 v221, 0xffff0000, v165
	v_max_f32_e32 v214, v214, v214
	v_max_f32_e32 v215, v215, v215
	v_max_f32_e32 v216, v216, v216
	v_max_f32_e32 v217, v217, v217
	v_max_f32_e32 v218, v218, v218
	v_max_f32_e32 v219, v219, v219
	v_max_f32_e32 v220, v220, v220
	v_max_f32_e32 v221, v221, v221
	v_max_f32_e32 v214, 0xda24260, v214
	v_max_f32_e32 v215, 0xda24260, v215
	v_max_f32_e32 v216, 0xda24260, v216
	v_max_f32_e32 v217, 0xda24260, v217
	v_max_f32_e32 v218, 0xda24260, v218
	v_max_f32_e32 v219, 0xda24260, v219
	v_max_f32_e32 v220, 0xda24260, v220
	v_max_f32_e32 v221, 0xda24260, v221
	v_pk_mul_f32 v[222:223], v[108:109], v[214:215]
	v_pk_mul_f32 v[224:225], v[110:111], v[216:217]
	v_pk_mul_f32 v[226:227], v[104:105], v[218:219]
	v_pk_mul_f32 v[228:229], v[106:107], v[220:221]
	v_cvt_pk_bf16_f32 v230, v222, v223
	v_cvt_pk_bf16_f32 v231, v224, v225
	v_cvt_pk_bf16_f32 v232, v226, v227
	v_cvt_pk_bf16_f32 v233, v228, v229
	global_store_dwordx4 v234, v[230:233], s[100:101]
	v_lshlrev_b32_e32 v214, 16, v166
	v_and_b32_e32 v215, 0xffff0000, v166
	v_lshlrev_b32_e32 v216, 16, v167
	v_and_b32_e32 v217, 0xffff0000, v167
	v_lshlrev_b32_e32 v218, 16, v168
	v_and_b32_e32 v219, 0xffff0000, v168
	v_lshlrev_b32_e32 v220, 16, v169
	v_and_b32_e32 v221, 0xffff0000, v169
	v_max_f32_e32 v214, v214, v214
	v_max_f32_e32 v215, v215, v215
	v_max_f32_e32 v216, v216, v216
	v_max_f32_e32 v217, v217, v217
	v_max_f32_e32 v218, v218, v218
	v_max_f32_e32 v219, v219, v219
	v_max_f32_e32 v220, v220, v220
	v_max_f32_e32 v221, v221, v221
	v_max_f32_e32 v214, 0xda24260, v214
	v_max_f32_e32 v215, 0xda24260, v215
	v_max_f32_e32 v216, 0xda24260, v216
	v_max_f32_e32 v217, 0xda24260, v217
	v_max_f32_e32 v218, 0xda24260, v218
	v_max_f32_e32 v219, 0xda24260, v219
	v_max_f32_e32 v220, 0xda24260, v220
	v_max_f32_e32 v221, 0xda24260, v221
	v_pk_mul_f32 v[222:223], v[76:77], v[214:215]
	v_pk_mul_f32 v[224:225], v[78:79], v[216:217]
	v_pk_mul_f32 v[226:227], v[72:73], v[218:219]
	v_pk_mul_f32 v[228:229], v[74:75], v[220:221]
	v_cvt_pk_bf16_f32 v230, v222, v223
	v_cvt_pk_bf16_f32 v231, v224, v225
	v_cvt_pk_bf16_f32 v232, v226, v227
	v_cvt_pk_bf16_f32 v233, v228, v229
; __device__ __forceinline__ u32x4 pack8(f32x4 a, f32x4 b) { u32x4 w; w.x = cvt_pk(a[0], a[1]); w.y = cvt_pk(a[2], a[3]); w.z = cvt_pk(b[0], b[1]); w.w = cvt_pk(b[2], b[3]); return w; }
;     __device__ __forceinline__ void operator()(f32x4 (&acc)[2][2][4][2], const pg8::Unit& u, int wr, int wc, int fr, int fq) const {
;     ...
;                     float a8[8] = {bflo(ga.x), bfhi(ga.x), bflo(ga.y), bfhi(ga.y), bflo(ga.z), bfhi(ga.z), bflo(ga.w), bfhi(ga.w)};
; #pragma unroll
;                     for (int e = 0; e < 8; ++e) a8[e] = fmaxf(a8[e], 1e-30f);
;                     if (u.kind == 0) { const u32x4 gl = *(const u32x4*)(GL + o);
;                         const float l8[8] = {bflo(gl.x), bfhi(gl.x), bflo(gl.y), bfhi(gl.y), bflo(gl.z), bfhi(gl.z), bflo(gl.w), bfhi(gl.w)};
; #pragma unroll
;                         for (int e = 0; e < 4; ++e) { acc[ai][bj][m][0][e] *= l8[e] * __builtin_amdgcn_rcpf(a8[e]); acc[ai][bj][m][1][e] *= l8[4 + e] * __builtin_amdgcn_rcpf(a8[4 + e]); }
;                     } else { f32x4 v0 = acc[ai][bj][m][0], v1 = acc[ai][bj][m][1];
; #pragma unroll
;                         for (int e = 0; e < 4; ++e) { v0[e] *= a8[e]; v1[e] *= a8[4 + e]; }
;                         *(u32x4*)(MG + o) = pack8(v0, v1); } } }
	global_store_dwordx4 v234, v[230:233], s[100:101] offset:256
	s_add_u32 s100, s100, 0x8000
	s_addc_u32 s101, s101, 0
	v_lshlrev_b32_e32 v214, 16, v170
	v_and_b32_e32 v215, 0xffff0000, v170
	v_lshlrev_b32_e32 v216, 16, v171
	v_and_b32_e32 v217, 0xffff0000, v171
	v_lshlrev_b32_e32 v218, 16, v172
	v_and_b32_e32 v219, 0xffff0000, v172
	v_lshlrev_b32_e32 v220, 16, v173
	v_and_b32_e32 v221, 0xffff0000, v173
	v_max_f32_e32 v214, v214, v214
	v_max_f32_e32 v215, v215, v215
	v_max_f32_e32 v216, v216, v216
	v_max_f32_e32 v217, v217, v217
	v_max_f32_e32 v218, v218, v218
	v_max_f32_e32 v219, v219, v219
	v_max_f32_e32 v220, v220, v220
	v_max_f32_e32 v221, v221, v221
	v_max_f32_e32 v214, 0xda24260, v214
	v_max_f32_e32 v215, 0xda24260, v215
	v_max_f32_e32 v216, 0xda24260, v216
	v_max_f32_e32 v217, 0xda24260, v217
	v_max_f32_e32 v218, 0xda24260, v218
	v_max_f32_e32 v219, 0xda24260, v219
	v_max_f32_e32 v220, 0xda24260, v220
	v_max_f32_e32 v221, 0xda24260, v221
	v_pk_mul_f32 v[222:223], v[100:101], v[214:215]
	v_pk_mul_f32 v[224:225], v[102:103], v[216:217]
	v_pk_mul_f32 v[226:227], v[96:97], v[218:219]
	v_pk_mul_f32 v[228:229], v[98:99], v[220:221]
	v_cvt_pk_bf16_f32 v230, v222, v223
	v_cvt_pk_bf16_f32 v231, v224, v225
	v_cvt_pk_bf16_f32 v232, v226, v227
	v_cvt_pk_bf16_f32 v233, v228, v229
	global_store_dwordx4 v234, v[230:233], s[100:101]
	v_lshlrev_b32_e32 v214, 16, v174
	v_and_b32_e32 v215, 0xffff0000, v174
	v_lshlrev_b32_e32 v216, 16, v175
	v_and_b32_e32 v217, 0xffff0000, v175
	v_lshlrev_b32_e32 v218, 16, v176
	v_and_b32_e32 v219, 0xffff0000, v176
	v_lshlrev_b32_e32 v220, 16, v177
	v_and_b32_e32 v221, 0xffff0000, v177
	v_max_f32_e32 v214, v214, v214
	v_max_f32_e32 v215, v215, v215
	v_max_f32_e32 v216, v216, v216
	v_max_f32_e32 v217, v217, v217
	v_max_f32_e32 v218, v218, v218
	v_max_f32_e32 v219, v219, v219
	v_max_f32_e32 v220, v220, v220
	v_max_f32_e32 v221, v221, v221
	v_max_f32_e32 v214, 0xda24260, v214
	v_max_f32_e32 v215, 0xda24260, v215
	v_max_f32_e32 v216, 0xda24260, v216
	v_max_f32_e32 v217, 0xda24260, v217
	v_max_f32_e32 v218, 0xda24260, v218
	v_max_f32_e32 v219, 0xda24260, v219
	v_max_f32_e32 v220, 0xda24260, v220
	v_max_f32_e32 v221, 0xda24260, v221
	v_pk_mul_f32 v[222:223], v[68:69], v[214:215]
	v_pk_mul_f32 v[224:225], v[70:71], v[216:217]
	v_pk_mul_f32 v[226:227], v[64:65], v[218:219]
	v_pk_mul_f32 v[228:229], v[66:67], v[220:221]
	v_cvt_pk_bf16_f32 v230, v222, v223
	v_cvt_pk_bf16_f32 v231, v224, v225
	v_cvt_pk_bf16_f32 v232, v226, v227
	v_cvt_pk_bf16_f32 v233, v228, v229
	global_store_dwordx4 v234, v[230:233], s[100:101] offset:256
	s_add_u32 s100, s100, 0x28000
	s_addc_u32 s101, s101, 0
	v_lshlrev_b32_e32 v214, 16, v178
	v_and_b32_e32 v215, 0xffff0000, v178
	v_lshlrev_b32_e32 v216, 16, v179
	v_and_b32_e32 v217, 0xffff0000, v179
	v_lshlrev_b32_e32 v218, 16, v180
	v_and_b32_e32 v219, 0xffff0000, v180
	v_lshlrev_b32_e32 v220, 16, v181
	v_and_b32_e32 v221, 0xffff0000, v181
	v_max_f32_e32 v214, v214, v214
	v_max_f32_e32 v215, v215, v215
	v_max_f32_e32 v216, v216, v216
	v_max_f32_e32 v217, v217, v217
	v_max_f32_e32 v218, v218, v218
	v_max_f32_e32 v219, v219, v219
	v_max_f32_e32 v220, v220, v220
	v_max_f32_e32 v221, v221, v221
	v_max_f32_e32 v214, 0xda24260, v214
	v_max_f32_e32 v215, 0xda24260, v215
	v_max_f32_e32 v216, 0xda24260, v216
	v_max_f32_e32 v217, 0xda24260, v217
	v_max_f32_e32 v218, 0xda24260, v218
	v_max_f32_e32 v219, 0xda24260, v219
	v_max_f32_e32 v220, 0xda24260, v220
	v_max_f32_e32 v221, 0xda24260, v221
	v_pk_mul_f32 v[222:223], v[60:61], v[214:215]
	v_pk_mul_f32 v[224:225], v[62:63], v[216:217]
	v_pk_mul_f32 v[226:227], v[56:57], v[218:219]
	v_pk_mul_f32 v[228:229], v[58:59], v[220:221]
	v_cvt_pk_bf16_f32 v230, v222, v223
	v_cvt_pk_bf16_f32 v231, v224, v225
	v_cvt_pk_bf16_f32 v232, v226, v227
	v_cvt_pk_bf16_f32 v233, v228, v229
	global_store_dwordx4 v234, v[230:233], s[100:101]
	v_lshlrev_b32_e32 v214, 16, v186
	v_and_b32_e32 v215, 0xffff0000, v186
	v_lshlrev_b32_e32 v216, 16, v187
	v_and_b32_e32 v217, 0xffff0000, v187
	v_lshlrev_b32_e32 v218, 16, v188
	v_and_b32_e32 v219, 0xffff0000, v188
	v_lshlrev_b32_e32 v220, 16, v189
	v_and_b32_e32 v221, 0xffff0000, v189
	v_max_f32_e32 v214, v214, v214
	v_max_f32_e32 v215, v215, v215
	v_max_f32_e32 v216, v216, v216
	v_max_f32_e32 v217, v217, v217
	v_max_f32_e32 v218, v218, v218
	v_max_f32_e32 v219, v219, v219
	v_max_f32_e32 v220, v220, v220
	v_max_f32_e32 v221, v221, v221
	v_max_f32_e32 v214, 0xda24260, v214
	v_max_f32_e32 v215, 0xda24260, v215
	v_max_f32_e32 v216, 0xda24260, v216
	v_max_f32_e32 v217, 0xda24260, v217
	v_max_f32_e32 v218, 0xda24260, v218
	v_max_f32_e32 v219, 0xda24260, v219
	v_max_f32_e32 v220, 0xda24260, v220
	v_max_f32_e32 v221, 0xda24260, v221
	v_pk_mul_f32 v[222:223], v[28:29], v[214:215]
	v_pk_mul_f32 v[224:225], v[30:31], v[216:217]
	v_pk_mul_f32 v[226:227], v[24:25], v[218:219]
	v_pk_mul_f32 v[228:229], v[26:27], v[220:221]
	v_cvt_pk_bf16_f32 v230, v222, v223
	v_cvt_pk_bf16_f32 v231, v224, v225
	v_cvt_pk_bf16_f32 v232, v226, v227
	v_cvt_pk_bf16_f32 v233, v228, v229
	global_store_dwordx4 v234, v[230:233], s[100:101] offset:256
	s_add_u32 s100, s100, 0x8000
	s_addc_u32 s101, s101, 0
	v_lshlrev_b32_e32 v214, 16, v190
	v_and_b32_e32 v215, 0xffff0000, v190
	v_lshlrev_b32_e32 v216, 16, v191
	v_and_b32_e32 v217, 0xffff0000, v191
	v_lshlrev_b32_e32 v218, 16, v192
	v_and_b32_e32 v219, 0xffff0000, v192
	v_lshlrev_b32_e32 v220, 16, v193
	v_and_b32_e32 v221, 0xffff0000, v193
	v_max_f32_e32 v214, v214, v214
	v_max_f32_e32 v215, v215, v215
	v_max_f32_e32 v216, v216, v216
	v_max_f32_e32 v217, v217, v217
	v_max_f32_e32 v218, v218, v218
	v_max_f32_e32 v219, v219, v219
; __device__ __forceinline__ u32x4 pack8(f32x4 a, f32x4 b) { u32x4 w; w.x = cvt_pk(a[0], a[1]); w.y = cvt_pk(a[2], a[3]); w.z = cvt_pk(b[0], b[1]); w.w = cvt_pk(b[2], b[3]); return w; }
;     __device__ __forceinline__ void operator()(f32x4 (&acc)[2][2][4][2], const pg8::Unit& u, int wr, int wc, int fr, int fq) const {
;     ...
;                     float a8[8] = {bflo(ga.x), bfhi(ga.x), bflo(ga.y), bfhi(ga.y), bflo(ga.z), bfhi(ga.z), bflo(ga.w), bfhi(ga.w)};
; #pragma unroll
;                     for (int e = 0; e < 8; ++e) a8[e] = fmaxf(a8[e], 1e-30f);
;                     if (u.kind == 0) { const u32x4 gl = *(const u32x4*)(GL + o);
;                         const float l8[8] = {bflo(gl.x), bfhi(gl.x), bflo(gl.y), bfhi(gl.y), bflo(gl.z), bfhi(gl.z), bflo(gl.w), bfhi(gl.w)};
; #pragma unroll
;                         for (int e = 0; e < 4; ++e) { acc[ai][bj][m][0][e] *= l8[e] * __builtin_amdgcn_rcpf(a8[e]); acc[ai][bj][m][1][e] *= l8[4 + e] * __builtin_amdgcn_rcpf(a8[4 + e]); }
;                     } else { f32x4 v0 = acc[ai][bj][m][0], v1 = acc[ai][bj][m][1];
; #pragma unroll
;                         for (int e = 0; e < 4; ++e) { v0[e] *= a8[e]; v1[e] *= a8[4 + e]; }
;                         *(u32x4*)(MG + o) = pack8(v0, v1); } } }
	v_max_f32_e32 v220, v220, v220
	v_max_f32_e32 v221, v221, v221
	v_max_f32_e32 v214, 0xda24260, v214
	v_max_f32_e32 v215, 0xda24260, v215
	v_max_f32_e32 v216, 0xda24260, v216
	v_max_f32_e32 v217, 0xda24260, v217
	v_max_f32_e32 v218, 0xda24260, v218
	v_max_f32_e32 v219, 0xda24260, v219
	v_max_f32_e32 v220, 0xda24260, v220
	v_max_f32_e32 v221, 0xda24260, v221
	v_pk_mul_f32 v[222:223], v[52:53], v[214:215]
	v_pk_mul_f32 v[224:225], v[54:55], v[216:217]
	v_pk_mul_f32 v[226:227], v[48:49], v[218:219]
	v_pk_mul_f32 v[228:229], v[50:51], v[220:221]
	v_cvt_pk_bf16_f32 v230, v222, v223
	v_cvt_pk_bf16_f32 v231, v224, v225
	v_cvt_pk_bf16_f32 v232, v226, v227
	v_cvt_pk_bf16_f32 v233, v228, v229
	global_store_dwordx4 v234, v[230:233], s[100:101]
	v_lshlrev_b32_e32 v214, 16, v194
	v_and_b32_e32 v215, 0xffff0000, v194
	v_lshlrev_b32_e32 v216, 16, v195
	v_and_b32_e32 v217, 0xffff0000, v195
	v_lshlrev_b32_e32 v218, 16, v196
	v_and_b32_e32 v219, 0xffff0000, v196
	v_lshlrev_b32_e32 v220, 16, v197
	v_and_b32_e32 v221, 0xffff0000, v197
	v_max_f32_e32 v214, v214, v214
	v_max_f32_e32 v215, v215, v215
	v_max_f32_e32 v216, v216, v216
	v_max_f32_e32 v217, v217, v217
	v_max_f32_e32 v218, v218, v218
	v_max_f32_e32 v219, v219, v219
	v_max_f32_e32 v220, v220, v220
	v_max_f32_e32 v221, v221, v221
	v_max_f32_e32 v214, 0xda24260, v214
	v_max_f32_e32 v215, 0xda24260, v215
	v_max_f32_e32 v216, 0xda24260, v216
	v_max_f32_e32 v217, 0xda24260, v217
	v_max_f32_e32 v218, 0xda24260, v218
	v_max_f32_e32 v219, 0xda24260, v219
	v_max_f32_e32 v220, 0xda24260, v220
	v_max_f32_e32 v221, 0xda24260, v221
	v_pk_mul_f32 v[222:223], v[20:21], v[214:215]
	v_pk_mul_f32 v[224:225], v[22:23], v[216:217]
	v_pk_mul_f32 v[226:227], v[16:17], v[218:219]
	v_pk_mul_f32 v[228:229], v[18:19], v[220:221]
	v_cvt_pk_bf16_f32 v230, v222, v223
	v_cvt_pk_bf16_f32 v231, v224, v225
	v_cvt_pk_bf16_f32 v232, v226, v227
	v_cvt_pk_bf16_f32 v233, v228, v229
	global_store_dwordx4 v234, v[230:233], s[100:101] offset:256
	s_add_u32 s100, s100, 0x8000
	s_addc_u32 s101, s101, 0
	v_lshlrev_b32_e32 v214, 16, v198
	v_and_b32_e32 v215, 0xffff0000, v198
	v_lshlrev_b32_e32 v216, 16, v199
	v_and_b32_e32 v217, 0xffff0000, v199
	v_lshlrev_b32_e32 v218, 16, v200
	v_and_b32_e32 v219, 0xffff0000, v200
	v_lshlrev_b32_e32 v220, 16, v201
	v_and_b32_e32 v221, 0xffff0000, v201
	v_max_f32_e32 v214, v214, v214
	v_max_f32_e32 v215, v215, v215
	v_max_f32_e32 v216, v216, v216
	v_max_f32_e32 v217, v217, v217
	v_max_f32_e32 v218, v218, v218
	v_max_f32_e32 v219, v219, v219
	v_max_f32_e32 v220, v220, v220
	v_max_f32_e32 v221, v221, v221
	v_max_f32_e32 v214, 0xda24260, v214
	v_max_f32_e32 v215, 0xda24260, v215
	v_max_f32_e32 v216, 0xda24260, v216
	v_max_f32_e32 v217, 0xda24260, v217
	v_max_f32_e32 v218, 0xda24260, v218
	v_max_f32_e32 v219, 0xda24260, v219
	v_max_f32_e32 v220, 0xda24260, v220
	v_max_f32_e32 v221, 0xda24260, v221
	v_pk_mul_f32 v[222:223], v[44:45], v[214:215]
	v_pk_mul_f32 v[224:225], v[46:47], v[216:217]
	v_pk_mul_f32 v[226:227], v[40:41], v[218:219]
	v_pk_mul_f32 v[228:229], v[42:43], v[220:221]
	v_cvt_pk_bf16_f32 v230, v222, v223
	v_cvt_pk_bf16_f32 v231, v224, v225
	v_cvt_pk_bf16_f32 v232, v226, v227
	v_cvt_pk_bf16_f32 v233, v228, v229
	global_store_dwordx4 v234, v[230:233], s[100:101]
	v_lshlrev_b32_e32 v214, 16, v202
	v_and_b32_e32 v215, 0xffff0000, v202
	v_lshlrev_b32_e32 v216, 16, v203
	v_and_b32_e32 v217, 0xffff0000, v203
	v_lshlrev_b32_e32 v218, 16, v204
	v_and_b32_e32 v219, 0xffff0000, v204
	v_lshlrev_b32_e32 v220, 16, v205
	v_and_b32_e32 v221, 0xffff0000, v205
; __device__ __forceinline__ u32x4 pack8(f32x4 a, f32x4 b) { u32x4 w; w.x = cvt_pk(a[0], a[1]); w.y = cvt_pk(a[2], a[3]); w.z = cvt_pk(b[0], b[1]); w.w = cvt_pk(b[2], b[3]); return w; }
;     __device__ __forceinline__ void operator()(f32x4 (&acc)[2][2][4][2], const pg8::Unit& u, int wr, int wc, int fr, int fq) const {
;     ...
;                     float a8[8] = {bflo(ga.x), bfhi(ga.x), bflo(ga.y), bfhi(ga.y), bflo(ga.z), bfhi(ga.z), bflo(ga.w), bfhi(ga.w)};
; #pragma unroll
;                     for (int e = 0; e < 8; ++e) a8[e] = fmaxf(a8[e], 1e-30f);
;                     if (u.kind == 0) { const u32x4 gl = *(const u32x4*)(GL + o);
;                         const float l8[8] = {bflo(gl.x), bfhi(gl.x), bflo(gl.y), bfhi(gl.y), bflo(gl.z), bfhi(gl.z), bflo(gl.w), bfhi(gl.w)};
; #pragma unroll
;                         for (int e = 0; e < 4; ++e) { acc[ai][bj][m][0][e] *= l8[e] * __builtin_amdgcn_rcpf(a8[e]); acc[ai][bj][m][1][e] *= l8[4 + e] * __builtin_amdgcn_rcpf(a8[4 + e]); }
;                     } else { f32x4 v0 = acc[ai][bj][m][0], v1 = acc[ai][bj][m][1];
; #pragma unroll
;                         for (int e = 0; e < 4; ++e) { v0[e] *= a8[e]; v1[e] *= a8[4 + e]; }
;                         *(u32x4*)(MG + o) = pack8(v0, v1); } } }
	v_max_f32_e32 v214, v214, v214
	v_max_f32_e32 v215, v215, v215
	v_max_f32_e32 v216, v216, v216
	v_max_f32_e32 v217, v217, v217
	v_max_f32_e32 v218, v218, v218
	v_max_f32_e32 v219, v219, v219
	v_max_f32_e32 v220, v220, v220
	v_max_f32_e32 v221, v221, v221
	v_max_f32_e32 v214, 0xda24260, v214
	v_max_f32_e32 v215, 0xda24260, v215
	v_max_f32_e32 v216, 0xda24260, v216
	v_max_f32_e32 v217, 0xda24260, v217
	v_max_f32_e32 v218, 0xda24260, v218
	v_max_f32_e32 v219, 0xda24260, v219
	v_max_f32_e32 v220, 0xda24260, v220
	v_max_f32_e32 v221, 0xda24260, v221
	v_pk_mul_f32 v[222:223], v[12:13], v[214:215]
	v_pk_mul_f32 v[224:225], v[14:15], v[216:217]
	v_pk_mul_f32 v[226:227], v[8:9], v[218:219]
	v_pk_mul_f32 v[228:229], v[10:11], v[220:221]
	v_cvt_pk_bf16_f32 v230, v222, v223
	v_cvt_pk_bf16_f32 v231, v224, v225
	v_cvt_pk_bf16_f32 v232, v226, v227
	v_cvt_pk_bf16_f32 v233, v228, v229
	global_store_dwordx4 v234, v[230:233], s[100:101] offset:256
	s_add_u32 s100, s100, 0x8000
	s_addc_u32 s101, s101, 0
	v_lshlrev_b32_e32 v214, 16, v206
	v_and_b32_e32 v215, 0xffff0000, v206
	v_lshlrev_b32_e32 v216, 16, v207
	v_and_b32_e32 v217, 0xffff0000, v207
	v_lshlrev_b32_e32 v218, 16, v208
	v_and_b32_e32 v219, 0xffff0000, v208
	v_lshlrev_b32_e32 v220, 16, v209
	v_and_b32_e32 v221, 0xffff0000, v209
	v_max_f32_e32 v214, v214, v214
	v_max_f32_e32 v215, v215, v215
	v_max_f32_e32 v216, v216, v216
	v_max_f32_e32 v217, v217, v217
	v_max_f32_e32 v218, v218, v218
	v_max_f32_e32 v219, v219, v219
	v_max_f32_e32 v220, v220, v220
	v_max_f32_e32 v221, v221, v221
	v_max_f32_e32 v214, 0xda24260, v214
	v_max_f32_e32 v215, 0xda24260, v215
	v_max_f32_e32 v216, 0xda24260, v216
	v_max_f32_e32 v217, 0xda24260, v217
	v_max_f32_e32 v218, 0xda24260, v218
	v_max_f32_e32 v219, 0xda24260, v219
	v_max_f32_e32 v220, 0xda24260, v220
	v_max_f32_e32 v221, 0xda24260, v221
	v_pk_mul_f32 v[222:223], v[36:37], v[214:215]
	v_pk_mul_f32 v[224:225], v[38:39], v[216:217]
	v_pk_mul_f32 v[226:227], v[32:33], v[218:219]
	v_pk_mul_f32 v[228:229], v[34:35], v[220:221]
	v_cvt_pk_bf16_f32 v230, v222, v223
	v_cvt_pk_bf16_f32 v231, v224, v225
	v_cvt_pk_bf16_f32 v232, v226, v227
	v_cvt_pk_bf16_f32 v233, v228, v229
	global_store_dwordx4 v234, v[230:233], s[100:101]
	v_lshlrev_b32_e32 v214, 16, v210
	v_and_b32_e32 v215, 0xffff0000, v210
	v_lshlrev_b32_e32 v216, 16, v211
	v_and_b32_e32 v217, 0xffff0000, v211
	v_lshlrev_b32_e32 v218, 16, v212
	v_and_b32_e32 v219, 0xffff0000, v212
	v_lshlrev_b32_e32 v220, 16, v213
	v_and_b32_e32 v221, 0xffff0000, v213
	v_max_f32_e32 v214, v214, v214
	v_max_f32_e32 v215, v215, v215
	v_max_f32_e32 v216, v216, v216
	v_max_f32_e32 v217, v217, v217
	v_max_f32_e32 v218, v218, v218
	v_max_f32_e32 v219, v219, v219
	v_max_f32_e32 v220, v220, v220
	v_max_f32_e32 v221, v221, v221
	v_max_f32_e32 v214, 0xda24260, v214
	v_max_f32_e32 v215, 0xda24260, v215
	v_max_f32_e32 v216, 0xda24260, v216
	v_max_f32_e32 v217, 0xda24260, v217
	v_max_f32_e32 v218, 0xda24260, v218
	v_max_f32_e32 v219, 0xda24260, v219
	v_max_f32_e32 v220, 0xda24260, v220
	v_max_f32_e32 v221, 0xda24260, v221
	v_pk_mul_f32 v[222:223], v[4:5], v[214:215]
	v_pk_mul_f32 v[224:225], v[6:7], v[216:217]
	v_pk_mul_f32 v[226:227], v[0:1], v[218:219]
	v_pk_mul_f32 v[228:229], v[2:3], v[220:221]
	v_cvt_pk_bf16_f32 v230, v222, v223
	v_cvt_pk_bf16_f32 v231, v224, v225
	v_cvt_pk_bf16_f32 v232, v226, v227
	v_cvt_pk_bf16_f32 v233, v228, v229
	global_store_dwordx4 v234, v[230:233], s[100:101] offset:256
	s_add_u32 s100, s100, 0x28000
	s_addc_u32 s101, s101, 0
	s_mov_b64 s[4:5], 0

; __device__ __forceinline__ u32x4 pack8(f32x4 a, f32x4 b) { u32x4 w; w.x = cvt_pk(a[0], a[1]); w.y = cvt_pk(a[2], a[3]); w.z = cvt_pk(b[0], b[1]); w.w = cvt_pk(b[2], b[3]); return w; }
;     __device__ __forceinline__ void operator()(EPI_ARGS) const {
;         const int row0 = u.pm * 256 + wr * 64 + fr, colt = u.pn * 256 + wc * 32 + 8 * fq;
; #pragma unroll
;         for (int ai = 0; ai < 2; ++ai)
; #pragma unroll
;             for (int m = 0; m < 4; ++m) { const int row = row0 + ai * 128 + m * 16; const size_t ro = (size_t)row * DM + colt; float s = 0.f;
; #pragma unroll
;                 for (int bj = 0; bj < 2; ++bj) { const size_t o = ro + bj * 128;
;                     f32x4 v0 = acc[ai][bj][m][0], v1 = acc[ai][bj][m][1];
;                     if (IN_BF16) { const u32x4 t = *(const u32x4*)((const bf16_t*)xin + o);
;                         v0[0] += bflo(t.x); v0[1] += bfhi(t.x); v0[2] += bflo(t.y); v0[3] += bfhi(t.y); v1[0] += bflo(t.z); v1[1] += bfhi(t.z); v1[2] += bflo(t.w); v1[3] += bfhi(t.w);
;                     } else { v0 = v0 + *(const f32x4*)((const float*)xin + o); v1 = v1 + *(const f32x4*)((const float*)xin + o + 4); }
;                     *(u32x4*)(xb + o) = pack8(v0, v1);
;                     s += ((v0[0] * v0[0] + v0[1] * v0[1]) + (v0[2] * v0[2] + v0[3] * v0[3])) + ((v1[0] * v1[0] + v1[1] * v1[1]) + (v1[2] * v1[2] + v1[3] * v1[3])); }
;                 s += __shfl_xor(s, 16); s += __shfl_xor(s, 32);
;                 if (fq == 0) ss[(size_t)row * 16 + u.pn * 4 + wc] = s; }
.LBB0_795:
	s_lshl_b32 s15, s35, 8
	s_or_b32 s15, s15, s43
	v_ashrrev_i32_e32 v140, 1, v144
	v_and_b32_e32 v140, -8, v140
	v_add_u32_e32 v140, s15, v140
	v_and_or_b32 v141, v144, 15, s42
	v_lshl_add_u32 v142, s6, 8, v141
	v_lshlrev_b32_e32 v222, 12, v142
	v_lshl_add_u32 v222, v140, 2, v222
	v_lshlrev_b32_e32 v223, 11, v142
	v_lshl_add_u32 v223, v140, 1, v223
	s_lshl_b32 s15, s35, 4
	s_lshl_b32 s24, s41, 2
	s_add_i32 s15, s15, s24
	v_lshl_add_u32 v224, v142, 6, s15
	v_xor_b32_e32 v225, 16, v144
	v_lshlrev_b32_e32 v225, 2, v225
	v_xor_b32_e32 v226, 32, v144
	v_lshlrev_b32_e32 v226, 2, v226
	v_cmp_gt_u32_e32 vcc, 16, v144
	s_mov_b64 s[98:99], s[76:77]
	s_mov_b64 s[100:101], s[72:73]
	s_mov_b64 s[24:25], s[2:3]
	global_load_dwordx4 v[150:153], v222, s[98:99] nt
	global_load_dwordx4 v[154:157], v222, s[98:99] offset:16 nt
	global_load_dwordx4 v[158:161], v222, s[98:99] offset:512 nt
	global_load_dwordx4 v[162:165], v222, s[98:99] offset:528 nt
	s_add_u32 s98, s98, 0x10000
	s_addc_u32 s99, s99, 0
	global_load_dwordx4 v[166:169], v222, s[98:99] nt
	global_load_dwordx4 v[170:173], v222, s[98:99] offset:16 nt
	global_load_dwordx4 v[174:177], v222, s[98:99] offset:512 nt
	global_load_dwordx4 v[178:181], v222, s[98:99] offset:528 nt
	s_add_u32 s98, s98, 0x10000
	s_addc_u32 s99, s99, 0
	global_load_dwordx4 v[186:189], v222, s[98:99] nt
	global_load_dwordx4 v[190:193], v222, s[98:99] offset:16 nt
	global_load_dwordx4 v[194:197], v222, s[98:99] offset:512 nt
	global_load_dwordx4 v[198:201], v222, s[98:99] offset:528 nt
	s_add_u32 s98, s98, 0x10000
	s_addc_u32 s99, s99, 0
	global_load_dwordx4 v[202:205], v222, s[98:99] nt
	global_load_dwordx4 v[206:209], v222, s[98:99] offset:16 nt
	global_load_dwordx4 v[210:213], v222, s[98:99] offset:512 nt
	global_load_dwordx4 v[238:241], v222, s[98:99] offset:528 nt
	s_add_u32 s98, s98, 0x50000
	s_addc_u32 s99, s99, 0
	s_waitcnt vmcnt(0)
	v_pk_add_f32 v[124:125], v[124:125], v[150:151]
	v_pk_add_f32 v[126:127], v[126:127], v[152:153]
	v_pk_add_f32 v[120:121], v[120:121], v[154:155]
	v_pk_add_f32 v[122:123], v[122:123], v[156:157]
	v_pk_add_f32 v[116:117], v[116:117], v[158:159]
	v_pk_add_f32 v[118:119], v[118:119], v[160:161]
	v_pk_add_f32 v[112:113], v[112:113], v[162:163]
	v_pk_add_f32 v[114:115], v[114:115], v[164:165]
	v_pk_add_f32 v[108:109], v[108:109], v[166:167]
	v_pk_add_f32 v[110:111], v[110:111], v[168:169]
	v_pk_add_f32 v[104:105], v[104:105], v[170:171]
	v_pk_add_f32 v[106:107], v[106:107], v[172:173]
	v_pk_add_f32 v[100:101], v[100:101], v[174:175]
	v_pk_add_f32 v[102:103], v[102:103], v[176:177]
	v_pk_add_f32 v[96:97], v[96:97], v[178:179]
	v_pk_add_f32 v[98:99], v[98:99], v[180:181]
	v_pk_add_f32 v[92:93], v[92:93], v[186:187]
	v_pk_add_f32 v[94:95], v[94:95], v[188:189]
	v_pk_add_f32 v[88:89], v[88:89], v[190:191]
	v_pk_add_f32 v[90:91], v[90:91], v[192:193]
	v_pk_add_f32 v[84:85], v[84:85], v[194:195]
	v_pk_add_f32 v[86:87], v[86:87], v[196:197]
	v_pk_add_f32 v[80:81], v[80:81], v[198:199]
	v_pk_add_f32 v[82:83], v[82:83], v[200:201]
	v_pk_add_f32 v[76:77], v[76:77], v[202:203]
	v_pk_add_f32 v[78:79], v[78:79], v[204:205]
	v_pk_add_f32 v[72:73], v[72:73], v[206:207]
	v_pk_add_f32 v[74:75], v[74:75], v[208:209]
	v_pk_add_f32 v[68:69], v[68:69], v[210:211]
	v_pk_add_f32 v[70:71], v[70:71], v[212:213]
	v_pk_add_f32 v[64:65], v[64:65], v[238:239]
	v_pk_add_f32 v[66:67], v[66:67], v[240:241]
	global_load_dwordx4 v[150:153], v222, s[98:99] nt
	global_load_dwordx4 v[154:157], v222, s[98:99] offset:16 nt
	global_load_dwordx4 v[158:161], v222, s[98:99] offset:512 nt
	global_load_dwordx4 v[162:165], v222, s[98:99] offset:528 nt
	s_add_u32 s98, s98, 0x10000
	s_addc_u32 s99, s99, 0
	global_load_dwordx4 v[166:169], v222, s[98:99] nt
	global_load_dwordx4 v[170:173], v222, s[98:99] offset:16 nt
	global_load_dwordx4 v[174:177], v222, s[98:99] offset:512 nt
	global_load_dwordx4 v[178:181], v222, s[98:99] offset:528 nt
	s_add_u32 s98, s98, 0x10000
	s_addc_u32 s99, s99, 0
	global_load_dwordx4 v[186:189], v222, s[98:99] nt
	global_load_dwordx4 v[190:193], v222, s[98:99] offset:16 nt
	global_load_dwordx4 v[194:197], v222, s[98:99] offset:512 nt
	global_load_dwordx4 v[198:201], v222, s[98:99] offset:528 nt
	s_add_u32 s98, s98, 0x10000
	s_addc_u32 s99, s99, 0
	global_load_dwordx4 v[202:205], v222, s[98:99] nt
	global_load_dwordx4 v[206:209], v222, s[98:99] offset:16 nt
	global_load_dwordx4 v[210:213], v222, s[98:99] offset:512 nt
	global_load_dwordx4 v[238:241], v222, s[98:99] offset:528 nt
	s_add_u32 s98, s98, 0x50000
	s_addc_u32 s99, s99, 0
	v_mul_f32_e32 v242, v125, v125
	v_mul_f32_e32 v243, v127, v127
	v_mul_f32_e32 v244, v121, v121
	v_mul_f32_e32 v245, v123, v123
	v_fmac_f32_e32 v242, v124, v124
	v_fmac_f32_e32 v243, v126, v126
	v_fmac_f32_e32 v244, v120, v120
	v_fmac_f32_e32 v245, v122, v122
	v_add_f32_e32 v242, v242, v243
	v_add_f32_e32 v243, v244, v245
	v_add_f32_e32 v227, v242, v243
	v_cvt_pk_bf16_f32 v230, v124, v125
	v_cvt_pk_bf16_f32 v231, v126, v127
	v_cvt_pk_bf16_f32 v232, v120, v121
	v_cvt_pk_bf16_f32 v233, v122, v123
	global_store_dwordx4 v223, v[230:233], s[100:101]
	v_mul_f32_e32 v242, v117, v117
	v_mul_f32_e32 v243, v119, v119
	v_mul_f32_e32 v244, v113, v113
	v_mul_f32_e32 v245, v115, v115
	v_fmac_f32_e32 v242, v116, v116
	v_fmac_f32_e32 v243, v118, v118
	v_fmac_f32_e32 v244, v112, v112
	v_fmac_f32_e32 v245, v114, v114
	v_add_f32_e32 v242, v242, v243
	v_add_f32_e32 v243, v244, v245
	v_add_f32_e32 v228, v242, v243
	v_cvt_pk_bf16_f32 v234, v116, v117
	v_cvt_pk_bf16_f32 v235, v118, v119
	v_cvt_pk_bf16_f32 v236, v112, v113
	v_cvt_pk_bf16_f32 v237, v114, v115
	global_store_dwordx4 v223, v[234:237], s[100:101] offset:256
	v_add_f32_e32 v227, v227, v228
	ds_bpermute_b32 v228, v225, v227
	s_waitcnt lgkmcnt(0)
; __device__ __forceinline__ u32x4 pack8(f32x4 a, f32x4 b) { u32x4 w; w.x = cvt_pk(a[0], a[1]); w.y = cvt_pk(a[2], a[3]); w.z = cvt_pk(b[0], b[1]); w.w = cvt_pk(b[2], b[3]); return w; }
;     __device__ __forceinline__ void operator()(EPI_ARGS) const {
;     ...
;                     f32x4 v0 = acc[ai][bj][m][0], v1 = acc[ai][bj][m][1];
;                     if (IN_BF16) { const u32x4 t = *(const u32x4*)((const bf16_t*)xin + o);
;                         v0[0] += bflo(t.x); v0[1] += bfhi(t.x); v0[2] += bflo(t.y); v0[3] += bfhi(t.y); v1[0] += bflo(t.z); v1[1] += bfhi(t.z); v1[2] += bflo(t.w); v1[3] += bfhi(t.w);
;                     } else { v0 = v0 + *(const f32x4*)((const float*)xin + o); v1 = v1 + *(const f32x4*)((const float*)xin + o + 4); }
;                     *(u32x4*)(xb + o) = pack8(v0, v1);
;                     s += ((v0[0] * v0[0] + v0[1] * v0[1]) + (v0[2] * v0[2] + v0[3] * v0[3])) + ((v1[0] * v1[0] + v1[1] * v1[1]) + (v1[2] * v1[2] + v1[3] * v1[3])); }
;                 s += __shfl_xor(s, 16); s += __shfl_xor(s, 32);
;                 if (fq == 0) ss[(size_t)row * 16 + u.pn * 4 + wc] = s; }
	v_add_f32_e32 v227, v227, v228
	ds_bpermute_b32 v228, v226, v227
	s_waitcnt lgkmcnt(0)
	v_add_f32_e32 v227, v227, v228
	s_and_saveexec_b64 s[22:23], vcc
	global_store_dword v224, v227, s[24:25]
	s_or_b64 exec, exec, s[22:23]
	s_add_u32 s100, s100, 0x8000
	s_addc_u32 s101, s101, 0
	s_add_u32 s24, s24, 0x400
	s_addc_u32 s25, s25, 0
	v_mul_f32_e32 v242, v109, v109
	v_mul_f32_e32 v243, v111, v111
	v_mul_f32_e32 v244, v105, v105
	v_mul_f32_e32 v245, v107, v107
	v_fmac_f32_e32 v242, v108, v108
	v_fmac_f32_e32 v243, v110, v110
	v_fmac_f32_e32 v244, v104, v104
	v_fmac_f32_e32 v245, v106, v106
	v_add_f32_e32 v242, v242, v243
	v_add_f32_e32 v243, v244, v245
	v_add_f32_e32 v227, v242, v243
	v_cvt_pk_bf16_f32 v230, v108, v109
	v_cvt_pk_bf16_f32 v231, v110, v111
	v_cvt_pk_bf16_f32 v232, v104, v105
	v_cvt_pk_bf16_f32 v233, v106, v107
	global_store_dwordx4 v223, v[230:233], s[100:101]
	v_mul_f32_e32 v242, v101, v101
	v_mul_f32_e32 v243, v103, v103
	v_mul_f32_e32 v244, v97, v97
	v_mul_f32_e32 v245, v99, v99
	v_fmac_f32_e32 v242, v100, v100
	v_fmac_f32_e32 v243, v102, v102
	v_fmac_f32_e32 v244, v96, v96
	v_fmac_f32_e32 v245, v98, v98
	v_add_f32_e32 v242, v242, v243
	v_add_f32_e32 v243, v244, v245
	v_add_f32_e32 v228, v242, v243
	v_cvt_pk_bf16_f32 v234, v100, v101
	v_cvt_pk_bf16_f32 v235, v102, v103
	v_cvt_pk_bf16_f32 v236, v96, v97
	v_cvt_pk_bf16_f32 v237, v98, v99
	global_store_dwordx4 v223, v[234:237], s[100:101] offset:256
	v_add_f32_e32 v227, v227, v228
	ds_bpermute_b32 v228, v225, v227
	s_waitcnt lgkmcnt(0)
	v_add_f32_e32 v227, v227, v228
	ds_bpermute_b32 v228, v226, v227
	s_waitcnt lgkmcnt(0)
	v_add_f32_e32 v227, v227, v228
	s_and_saveexec_b64 s[22:23], vcc
	global_store_dword v224, v227, s[24:25]
	s_or_b64 exec, exec, s[22:23]
	s_add_u32 s100, s100, 0x8000
	s_addc_u32 s101, s101, 0
	s_add_u32 s24, s24, 0x400
	s_addc_u32 s25, s25, 0
	v_mul_f32_e32 v242, v93, v93
	v_mul_f32_e32 v243, v95, v95
	v_mul_f32_e32 v244, v89, v89
	v_mul_f32_e32 v245, v91, v91
	v_fmac_f32_e32 v242, v92, v92
	v_fmac_f32_e32 v243, v94, v94
	v_fmac_f32_e32 v244, v88, v88
	v_fmac_f32_e32 v245, v90, v90
	v_add_f32_e32 v242, v242, v243
	v_add_f32_e32 v243, v244, v245
	v_add_f32_e32 v227, v242, v243
	v_cvt_pk_bf16_f32 v230, v92, v93
	v_cvt_pk_bf16_f32 v231, v94, v95
	v_cvt_pk_bf16_f32 v232, v88, v89
	v_cvt_pk_bf16_f32 v233, v90, v91
	global_store_dwordx4 v223, v[230:233], s[100:101]
	v_mul_f32_e32 v242, v85, v85
	v_mul_f32_e32 v243, v87, v87
	v_mul_f32_e32 v244, v81, v81
	v_mul_f32_e32 v245, v83, v83
	v_fmac_f32_e32 v242, v84, v84
	v_fmac_f32_e32 v243, v86, v86
	v_fmac_f32_e32 v244, v80, v80
	v_fmac_f32_e32 v245, v82, v82
	v_add_f32_e32 v242, v242, v243
	v_add_f32_e32 v243, v244, v245
	v_add_f32_e32 v228, v242, v243
	v_cvt_pk_bf16_f32 v234, v84, v85
	v_cvt_pk_bf16_f32 v235, v86, v87
	v_cvt_pk_bf16_f32 v236, v80, v81
	v_cvt_pk_bf16_f32 v237, v82, v83
	global_store_dwordx4 v223, v[234:237], s[100:101] offset:256
	v_add_f32_e32 v227, v227, v228
	ds_bpermute_b32 v228, v225, v227
	s_waitcnt lgkmcnt(0)
	v_add_f32_e32 v227, v227, v228
	ds_bpermute_b32 v228, v226, v227
	s_waitcnt lgkmcnt(0)
	v_add_f32_e32 v227, v227, v228
	s_and_saveexec_b64 s[22:23], vcc
	global_store_dword v224, v227, s[24:25]
	s_or_b64 exec, exec, s[22:23]
	s_add_u32 s100, s100, 0x8000
	s_addc_u32 s101, s101, 0
	s_add_u32 s24, s24, 0x400
	s_addc_u32 s25, s25, 0
	v_mul_f32_e32 v242, v77, v77
	v_mul_f32_e32 v243, v79, v79
	v_mul_f32_e32 v244, v73, v73
	v_mul_f32_e32 v245, v75, v75
	v_fmac_f32_e32 v242, v76, v76
	v_fmac_f32_e32 v243, v78, v78
	v_fmac_f32_e32 v244, v72, v72
	v_fmac_f32_e32 v245, v74, v74
	v_add_f32_e32 v242, v242, v243
	v_add_f32_e32 v243, v244, v245
	v_add_f32_e32 v227, v242, v243
	v_cvt_pk_bf16_f32 v230, v76, v77
	v_cvt_pk_bf16_f32 v231, v78, v79
	v_cvt_pk_bf16_f32 v232, v72, v73
	v_cvt_pk_bf16_f32 v233, v74, v75
	global_store_dwordx4 v223, v[230:233], s[100:101]
	v_mul_f32_e32 v242, v69, v69
	v_mul_f32_e32 v243, v71, v71
	v_mul_f32_e32 v244, v65, v65
	v_mul_f32_e32 v245, v67, v67
	v_fmac_f32_e32 v242, v68, v68
	v_fmac_f32_e32 v243, v70, v70
	v_fmac_f32_e32 v244, v64, v64
	v_fmac_f32_e32 v245, v66, v66
	v_add_f32_e32 v242, v242, v243
	v_add_f32_e32 v243, v244, v245
	v_add_f32_e32 v228, v242, v243
	v_cvt_pk_bf16_f32 v234, v68, v69
	v_cvt_pk_bf16_f32 v235, v70, v71
	v_cvt_pk_bf16_f32 v236, v64, v65
	v_cvt_pk_bf16_f32 v237, v66, v67
	global_store_dwordx4 v223, v[234:237], s[100:101] offset:256
	v_add_f32_e32 v227, v227, v228
	ds_bpermute_b32 v228, v225, v227
	s_waitcnt lgkmcnt(0)
	v_add_f32_e32 v227, v227, v228
	ds_bpermute_b32 v228, v226, v227
	s_waitcnt lgkmcnt(0)
	v_add_f32_e32 v227, v227, v228
	s_and_saveexec_b64 s[22:23], vcc
	global_store_dword v224, v227, s[24:25]
	s_or_b64 exec, exec, s[22:23]
	s_add_u32 s100, s100, 0x28000
	s_addc_u32 s101, s101, 0
	s_add_u32 s24, s24, 0x1400
	s_addc_u32 s25, s25, 0
	s_waitcnt vmcnt(12)
; __device__ __forceinline__ u32x4 pack8(f32x4 a, f32x4 b) { u32x4 w; w.x = cvt_pk(a[0], a[1]); w.y = cvt_pk(a[2], a[3]); w.z = cvt_pk(b[0], b[1]); w.w = cvt_pk(b[2], b[3]); return w; }
;     __device__ __forceinline__ void operator()(EPI_ARGS) const {
;     ...
;                     f32x4 v0 = acc[ai][bj][m][0], v1 = acc[ai][bj][m][1];
;                     if (IN_BF16) { const u32x4 t = *(const u32x4*)((const bf16_t*)xin + o);
;                         v0[0] += bflo(t.x); v0[1] += bfhi(t.x); v0[2] += bflo(t.y); v0[3] += bfhi(t.y); v1[0] += bflo(t.z); v1[1] += bfhi(t.z); v1[2] += bflo(t.w); v1[3] += bfhi(t.w);
;                     } else { v0 = v0 + *(const f32x4*)((const float*)xin + o); v1 = v1 + *(const f32x4*)((const float*)xin + o + 4); }
;                     *(u32x4*)(xb + o) = pack8(v0, v1);
;                     s += ((v0[0] * v0[0] + v0[1] * v0[1]) + (v0[2] * v0[2] + v0[3] * v0[3])) + ((v1[0] * v1[0] + v1[1] * v1[1]) + (v1[2] * v1[2] + v1[3] * v1[3])); }
;                 s += __shfl_xor(s, 16); s += __shfl_xor(s, 32);
;                 if (fq == 0) ss[(size_t)row * 16 + u.pn * 4 + wc] = s; }
	v_pk_add_f32 v[60:61], v[60:61], v[150:151]
	v_pk_add_f32 v[62:63], v[62:63], v[152:153]
	v_pk_add_f32 v[56:57], v[56:57], v[154:155]
	v_pk_add_f32 v[58:59], v[58:59], v[156:157]
	v_pk_add_f32 v[52:53], v[52:53], v[158:159]
	v_pk_add_f32 v[54:55], v[54:55], v[160:161]
	v_pk_add_f32 v[48:49], v[48:49], v[162:163]
	v_pk_add_f32 v[50:51], v[50:51], v[164:165]
	v_pk_add_f32 v[44:45], v[44:45], v[166:167]
	v_pk_add_f32 v[46:47], v[46:47], v[168:169]
	v_pk_add_f32 v[40:41], v[40:41], v[170:171]
	v_pk_add_f32 v[42:43], v[42:43], v[172:173]
	v_pk_add_f32 v[36:37], v[36:37], v[174:175]
	v_pk_add_f32 v[38:39], v[38:39], v[176:177]
	v_pk_add_f32 v[32:33], v[32:33], v[178:179]
	v_pk_add_f32 v[34:35], v[34:35], v[180:181]
	v_pk_add_f32 v[28:29], v[28:29], v[186:187]
	v_pk_add_f32 v[30:31], v[30:31], v[188:189]
	v_pk_add_f32 v[24:25], v[24:25], v[190:191]
	v_pk_add_f32 v[26:27], v[26:27], v[192:193]
	v_pk_add_f32 v[20:21], v[20:21], v[194:195]
	v_pk_add_f32 v[22:23], v[22:23], v[196:197]
	v_pk_add_f32 v[16:17], v[16:17], v[198:199]
	v_pk_add_f32 v[18:19], v[18:19], v[200:201]
	v_pk_add_f32 v[12:13], v[12:13], v[202:203]
	v_pk_add_f32 v[14:15], v[14:15], v[204:205]
	v_pk_add_f32 v[8:9], v[8:9], v[206:207]
	v_pk_add_f32 v[10:11], v[10:11], v[208:209]
	v_pk_add_f32 v[4:5], v[4:5], v[210:211]
	v_pk_add_f32 v[6:7], v[6:7], v[212:213]
	v_pk_add_f32 v[0:1], v[0:1], v[238:239]
	v_pk_add_f32 v[2:3], v[2:3], v[240:241]
	v_mul_f32_e32 v242, v61, v61
	v_mul_f32_e32 v243, v63, v63
	v_mul_f32_e32 v244, v57, v57
	v_mul_f32_e32 v245, v59, v59
	v_fmac_f32_e32 v242, v60, v60
	v_fmac_f32_e32 v243, v62, v62
	v_fmac_f32_e32 v244, v56, v56
	v_fmac_f32_e32 v245, v58, v58
	v_add_f32_e32 v242, v242, v243
	v_add_f32_e32 v243, v244, v245
	v_add_f32_e32 v227, v242, v243
	v_cvt_pk_bf16_f32 v230, v60, v61
	v_cvt_pk_bf16_f32 v231, v62, v63
	v_cvt_pk_bf16_f32 v232, v56, v57
	v_cvt_pk_bf16_f32 v233, v58, v59
	global_store_dwordx4 v223, v[230:233], s[100:101]
	v_mul_f32_e32 v242, v53, v53
	v_mul_f32_e32 v243, v55, v55
	v_mul_f32_e32 v244, v49, v49
	v_mul_f32_e32 v245, v51, v51
	v_fmac_f32_e32 v242, v52, v52
	v_fmac_f32_e32 v243, v54, v54
	v_fmac_f32_e32 v244, v48, v48
	v_fmac_f32_e32 v245, v50, v50
	v_add_f32_e32 v242, v242, v243
	v_add_f32_e32 v243, v244, v245
	v_add_f32_e32 v228, v242, v243
	v_cvt_pk_bf16_f32 v234, v52, v53
	v_cvt_pk_bf16_f32 v235, v54, v55
	v_cvt_pk_bf16_f32 v236, v48, v49
	v_cvt_pk_bf16_f32 v237, v50, v51
	global_store_dwordx4 v223, v[234:237], s[100:101] offset:256
	v_add_f32_e32 v227, v227, v228
	ds_bpermute_b32 v228, v225, v227
	s_waitcnt lgkmcnt(0)
	v_add_f32_e32 v227, v227, v228
	ds_bpermute_b32 v228, v226, v227
	s_waitcnt lgkmcnt(0)
	v_add_f32_e32 v227, v227, v228
	s_and_saveexec_b64 s[22:23], vcc
	global_store_dword v224, v227, s[24:25]
	s_or_b64 exec, exec, s[22:23]
	s_add_u32 s100, s100, 0x8000
	s_addc_u32 s101, s101, 0
	s_add_u32 s24, s24, 0x400
	s_addc_u32 s25, s25, 0
	v_mul_f32_e32 v242, v45, v45
	v_mul_f32_e32 v243, v47, v47
	v_mul_f32_e32 v244, v41, v41
	v_mul_f32_e32 v245, v43, v43
	v_fmac_f32_e32 v242, v44, v44
	v_fmac_f32_e32 v243, v46, v46
	v_fmac_f32_e32 v244, v40, v40
	v_fmac_f32_e32 v245, v42, v42
	v_add_f32_e32 v242, v242, v243
	v_add_f32_e32 v243, v244, v245
	v_add_f32_e32 v227, v242, v243
	v_cvt_pk_bf16_f32 v230, v44, v45
	v_cvt_pk_bf16_f32 v231, v46, v47
	v_cvt_pk_bf16_f32 v232, v40, v41
	v_cvt_pk_bf16_f32 v233, v42, v43
	global_store_dwordx4 v223, v[230:233], s[100:101]
	v_mul_f32_e32 v242, v37, v37
	v_mul_f32_e32 v243, v39, v39
	v_mul_f32_e32 v244, v33, v33
	v_mul_f32_e32 v245, v35, v35
	v_fmac_f32_e32 v242, v36, v36
	v_fmac_f32_e32 v243, v38, v38
	v_fmac_f32_e32 v244, v32, v32
	v_fmac_f32_e32 v245, v34, v34
	v_add_f32_e32 v242, v242, v243
	v_add_f32_e32 v243, v244, v245
	v_add_f32_e32 v228, v242, v243
	v_cvt_pk_bf16_f32 v234, v36, v37
	v_cvt_pk_bf16_f32 v235, v38, v39
	v_cvt_pk_bf16_f32 v236, v32, v33
	v_cvt_pk_bf16_f32 v237, v34, v35
	global_store_dwordx4 v223, v[234:237], s[100:101] offset:256
	v_add_f32_e32 v227, v227, v228
	ds_bpermute_b32 v228, v225, v227
	s_waitcnt lgkmcnt(0)
; __device__ __forceinline__ u32x4 pack8(f32x4 a, f32x4 b) { u32x4 w; w.x = cvt_pk(a[0], a[1]); w.y = cvt_pk(a[2], a[3]); w.z = cvt_pk(b[0], b[1]); w.w = cvt_pk(b[2], b[3]); return w; }
;     __device__ __forceinline__ void operator()(EPI_ARGS) const {
;     ...
;                     f32x4 v0 = acc[ai][bj][m][0], v1 = acc[ai][bj][m][1];
;                     if (IN_BF16) { const u32x4 t = *(const u32x4*)((const bf16_t*)xin + o);
;                         v0[0] += bflo(t.x); v0[1] += bfhi(t.x); v0[2] += bflo(t.y); v0[3] += bfhi(t.y); v1[0] += bflo(t.z); v1[1] += bfhi(t.z); v1[2] += bflo(t.w); v1[3] += bfhi(t.w);
;                     } else { v0 = v0 + *(const f32x4*)((const float*)xin + o); v1 = v1 + *(const f32x4*)((const float*)xin + o + 4); }
;                     *(u32x4*)(xb + o) = pack8(v0, v1);
;                     s += ((v0[0] * v0[0] + v0[1] * v0[1]) + (v0[2] * v0[2] + v0[3] * v0[3])) + ((v1[0] * v1[0] + v1[1] * v1[1]) + (v1[2] * v1[2] + v1[3] * v1[3])); }
;                 s += __shfl_xor(s, 16); s += __shfl_xor(s, 32);
;                 if (fq == 0) ss[(size_t)row * 16 + u.pn * 4 + wc] = s; }
	v_add_f32_e32 v227, v227, v228
	ds_bpermute_b32 v228, v226, v227
	s_waitcnt lgkmcnt(0)
	v_add_f32_e32 v227, v227, v228
	s_and_saveexec_b64 s[22:23], vcc
	global_store_dword v224, v227, s[24:25]
	s_or_b64 exec, exec, s[22:23]
	s_add_u32 s100, s100, 0x8000
	s_addc_u32 s101, s101, 0
	s_add_u32 s24, s24, 0x400
	s_addc_u32 s25, s25, 0
	v_mul_f32_e32 v242, v29, v29
	v_mul_f32_e32 v243, v31, v31
	v_mul_f32_e32 v244, v25, v25
	v_mul_f32_e32 v245, v27, v27
	v_fmac_f32_e32 v242, v28, v28
	v_fmac_f32_e32 v243, v30, v30
	v_fmac_f32_e32 v244, v24, v24
	v_fmac_f32_e32 v245, v26, v26
	v_add_f32_e32 v242, v242, v243
	v_add_f32_e32 v243, v244, v245
	v_add_f32_e32 v227, v242, v243
	v_cvt_pk_bf16_f32 v230, v28, v29
	v_cvt_pk_bf16_f32 v231, v30, v31
	v_cvt_pk_bf16_f32 v232, v24, v25
	v_cvt_pk_bf16_f32 v233, v26, v27
	global_store_dwordx4 v223, v[230:233], s[100:101]
	v_mul_f32_e32 v242, v21, v21
	v_mul_f32_e32 v243, v23, v23
	v_mul_f32_e32 v244, v17, v17
	v_mul_f32_e32 v245, v19, v19
	v_fmac_f32_e32 v242, v20, v20
	v_fmac_f32_e32 v243, v22, v22
	v_fmac_f32_e32 v244, v16, v16
	v_fmac_f32_e32 v245, v18, v18
	v_add_f32_e32 v242, v242, v243
	v_add_f32_e32 v243, v244, v245
	v_add_f32_e32 v228, v242, v243
	v_cvt_pk_bf16_f32 v234, v20, v21
	v_cvt_pk_bf16_f32 v235, v22, v23
	v_cvt_pk_bf16_f32 v236, v16, v17
	v_cvt_pk_bf16_f32 v237, v18, v19
	global_store_dwordx4 v223, v[234:237], s[100:101] offset:256
	v_add_f32_e32 v227, v227, v228
	ds_bpermute_b32 v228, v225, v227
	s_waitcnt lgkmcnt(0)
	v_add_f32_e32 v227, v227, v228
	ds_bpermute_b32 v228, v226, v227
	s_waitcnt lgkmcnt(0)
	v_add_f32_e32 v227, v227, v228
	s_and_saveexec_b64 s[22:23], vcc
	global_store_dword v224, v227, s[24:25]
	s_or_b64 exec, exec, s[22:23]
	s_add_u32 s100, s100, 0x8000
	s_addc_u32 s101, s101, 0
	s_add_u32 s24, s24, 0x400
	s_addc_u32 s25, s25, 0
	v_mul_f32_e32 v242, v13, v13
	v_mul_f32_e32 v243, v15, v15
	v_mul_f32_e32 v244, v9, v9
	v_mul_f32_e32 v245, v11, v11
	v_fmac_f32_e32 v242, v12, v12
	v_fmac_f32_e32 v243, v14, v14
	v_fmac_f32_e32 v244, v8, v8
	v_fmac_f32_e32 v245, v10, v10
	v_add_f32_e32 v242, v242, v243
	v_add_f32_e32 v243, v244, v245
	v_add_f32_e32 v227, v242, v243
	v_cvt_pk_bf16_f32 v230, v12, v13
	v_cvt_pk_bf16_f32 v231, v14, v15
	v_cvt_pk_bf16_f32 v232, v8, v9
	v_cvt_pk_bf16_f32 v233, v10, v11
	global_store_dwordx4 v223, v[230:233], s[100:101]
	v_mul_f32_e32 v242, v5, v5
	v_mul_f32_e32 v243, v7, v7
	v_mul_f32_e32 v244, v1, v1
	v_mul_f32_e32 v245, v3, v3
	v_fmac_f32_e32 v242, v4, v4
	v_fmac_f32_e32 v243, v6, v6
	v_fmac_f32_e32 v244, v0, v0
	v_fmac_f32_e32 v245, v2, v2
	v_add_f32_e32 v242, v242, v243
	v_add_f32_e32 v243, v244, v245
	v_add_f32_e32 v228, v242, v243
	v_cvt_pk_bf16_f32 v234, v4, v5
	v_cvt_pk_bf16_f32 v235, v6, v7
	v_cvt_pk_bf16_f32 v236, v0, v1
	v_cvt_pk_bf16_f32 v237, v2, v3
	global_store_dwordx4 v223, v[234:237], s[100:101] offset:256
	v_add_f32_e32 v227, v227, v228
	ds_bpermute_b32 v228, v225, v227
	s_waitcnt lgkmcnt(0)
	v_add_f32_e32 v227, v227, v228
	ds_bpermute_b32 v228, v226, v227
	s_waitcnt lgkmcnt(0)
	v_add_f32_e32 v227, v227, v228
	s_and_saveexec_b64 s[22:23], vcc
	global_store_dword v224, v227, s[24:25]
	s_or_b64 exec, exec, s[22:23]
	s_add_u32 s100, s100, 0x28000
	s_addc_u32 s101, s101, 0
	s_add_u32 s24, s24, 0x1400
	s_addc_u32 s25, s25, 0
	s_andn2_b64 vcc, exec, s[16:17]
	s_mov_b64 s[16:17], -1
	s_cbranch_vccnz .LBB0_784
	s_andn2_b64 vcc, exec, s[8:9]
	s_cbranch_vccnz .LBB0_783
	s_barrier
	s_branch .LBB0_783

; __global__ void __launch_bounds__(NWAVES * 64, 2) mk_fwd(Args args) {
;     ...
;         for (int m = gw; m < MT; m += NGW) { const float rs = row_rstd(ss, m);
;             const u32x4* xr = (const u32x4*)(X3 + (size_t)m * DM) + lane; f32x4* orow = (f32x4*)(P.out + (size_t)m * DM); const f32x4* gr = (const f32x4*)P.g_fin;
; #pragma unroll
;             for (int j = 0; j < 2; ++j) { const u32x4 w = xr[64 * j]; const int c4 = (64 * j + lane) * 2; const f32x4 ga = gr[c4], gb = gr[c4 + 1];
;                 f32x4 a, b2; a[0] = bflo(w.x) * rs * ga[0]; a[1] = bfhi(w.x) * rs * ga[1]; a[2] = bflo(w.y) * rs * ga[2]; a[3] = bfhi(w.y) * rs * ga[3];
;                 b2[0] = bflo(w.z) * rs * gb[0]; b2[1] = bfhi(w.z) * rs * gb[1]; b2[2] = bflo(w.w) * rs * gb[2]; b2[3] = bfhi(w.w) * rs * gb[3];
;                 orow[c4] = a; orow[c4 + 1] = b2; } }
.LBB0_1154:
	s_add_u32 s10, s68, s0
	v_lshl_add_u64 v[14:15], s[68:69], 0, v[6:7]
	s_addc_u32 s11, s69, s1
	v_add_co_u32_e32 v38, vcc, s9, v14
	global_load_dwordx4 v[10:13], v[2:3], off
	s_nop 0
	v_addc_co_u32_e32 v39, vcc, 0, v15, vcc
	global_load_dwordx4 v[14:17], v0, s[10:11]
	global_load_dwordx4 v[18:21], v[38:39], off nt
	s_add_u32 s10, s10, 0x400000
	s_addc_u32 s11, s11, 0
	global_load_dwordx4 v[22:25], v1, s[10:11] offset:32
	global_load_dwordx4 v[26:29], v1, s[10:11] offset:16
	global_load_dwordx4 v[30:33], v1, s[10:11] offset:48
	global_load_dwordx4 v[34:37], v[2:3], off offset:16
	s_add_i32 s8, s8, s58
	s_add_u32 s0, s0, s2
	s_addc_u32 s1, s1, s3
	v_lshl_add_u64 v[6:7], v[6:7], 0, s[6:7]
	s_cmpk_lt_i32 s8, 0x4000
	s_waitcnt vmcnt(0)
	v_mov_b32_e32 v40, v14
	v_mov_b32_e32 v14, v16
	v_mov_b32_e32 v41, v22
	v_mov_b32_e32 v22, v15
	v_mov_b32_e32 v15, v24
	v_mov_b32_e32 v24, v17
	v_mov_b32_e32 v16, v26
	v_mov_b32_e32 v17, v30
	v_mov_b32_e32 v30, v27
	v_mov_b32_e32 v26, v28
	v_mov_b32_e32 v27, v32
	v_mov_b32_e32 v32, v29
	v_pk_add_f32 v[22:23], v[40:41], v[22:23]
	v_pk_add_f32 v[14:15], v[14:15], v[24:25]
	v_pk_add_f32 v[16:17], v[16:17], v[30:31]
	v_pk_add_f32 v[24:25], v[26:27], v[32:33]
	v_pk_add_f32 v[14:15], v[22:23], v[14:15]
	v_pk_add_f32 v[16:17], v[16:17], v[24:25]
	v_lshlrev_b32_e32 v42, 16, v18
	v_pk_add_f32 v[14:15], v[14:15], v[16:17]
	v_and_b32_e32 v43, 0xffff0000, v18
	v_add_f32_e32 v9, v14, v15
	v_fmamk_f32 v9, v9, 0x3a800000, v8
	v_rsq_f32_e32 v22, v9
	v_lshlrev_b32_e32 v18, 16, v19
	v_and_b32_e32 v19, 0xffff0000, v19
	v_lshlrev_b32_e32 v44, 16, v20
	v_and_b32_e32 v45, 0xffff0000, v20
	v_lshlrev_b32_e32 v20, 16, v21
	v_and_b32_e32 v21, 0xffff0000, v21
	v_pk_mul_f32 v[14:15], v[22:23], v[42:43] op_sel_hi:[0,1]
	v_pk_mul_f32 v[16:17], v[22:23], v[18:19] op_sel_hi:[0,1]
	v_pk_mul_f32 v[18:19], v[22:23], v[44:45] op_sel_hi:[0,1]
	v_pk_mul_f32 v[20:21], v[22:23], v[20:21] op_sel_hi:[0,1]
	v_pk_mul_f32 v[10:11], v[10:11], v[14:15]
	v_pk_mul_f32 v[12:13], v[12:13], v[16:17]
	v_pk_mul_f32 v[14:15], v[34:35], v[18:19]
	v_pk_mul_f32 v[16:17], v[36:37], v[20:21]
	global_store_dwordx4 v[4:5], v[10:13], off offset:-2064 nt
	global_store_dwordx4 v[4:5], v[14:17], off offset:-2048 nt
	global_load_dwordx4 v[10:13], v[38:39], off offset:1024 nt
	s_nop 0
	global_load_dwordx4 v[14:17], v[2:3], off offset:2048
	global_load_dwordx4 v[18:21], v[2:3], off offset:2064
	s_waitcnt vmcnt(2)
	v_lshlrev_b32_e32 v24, 16, v10
	v_and_b32_e32 v25, 0xffff0000, v10
	v_lshlrev_b32_e32 v10, 16, v11
	v_and_b32_e32 v11, 0xffff0000, v11
	v_lshlrev_b32_e32 v26, 16, v12
	v_and_b32_e32 v27, 0xffff0000, v12
	v_lshlrev_b32_e32 v12, 16, v13
	v_and_b32_e32 v13, 0xffff0000, v13
	v_pk_mul_f32 v[24:25], v[22:23], v[24:25] op_sel_hi:[0,1]
	v_pk_mul_f32 v[28:29], v[22:23], v[10:11] op_sel_hi:[0,1]
	v_pk_mul_f32 v[26:27], v[22:23], v[26:27] op_sel_hi:[0,1]
	v_pk_mul_f32 v[22:23], v[22:23], v[12:13] op_sel_hi:[0,1]
	s_waitcnt vmcnt(1)
	v_pk_mul_f32 v[10:11], v[14:15], v[24:25]
	v_pk_mul_f32 v[12:13], v[16:17], v[28:29]
	s_waitcnt vmcnt(0)
	v_pk_mul_f32 v[14:15], v[18:19], v[26:27]
	v_pk_mul_f32 v[16:17], v[20:21], v[22:23]
	global_store_dwordx4 v[4:5], v[10:13], off offset:-16 nt
	global_store_dwordx4 v[4:5], v[14:17], off nt
	v_lshl_add_u64 v[4:5], v[4:5], 0, s[4:5]
	s_cbranch_scc1 .LBB0_1154
